# GEMM K-loops: DMA stages use saddr+voffset form (94 v_lshl_add_u64 removed from load waves, base+0x80 snapshots in s98-s101)
# speedup vs baseline: 1.0129x; 1.0026x over previous
; #define PG8_STAGE(bufoff, gbase, voff) do { _Pragma("unroll") for (int _i = 0; _i < 2; ++_i) \
;         __builtin_amdgcn_global_load_lds((const unsigned*)((const char*)(gbase) + (voff)[_i]), (LAS unsigned*)(lds + (bufoff) + ldsw + _i * 8192), 16, 0, 0); } while (0)
; #define PG8_LDA(dst, b, h) do { _Pragma("unroll") for (int m = 0; m < 4; ++m) _Pragma("unroll") for (int k = 0; k < 2; ++k) dst[m][k] = *(const LAS bf16x8*)(lds + PG8_SA(b, h) + aoff + m * 2048 + k * 1024); } while (0)
; #define PG8_LDB(dst, b, h) do { _Pragma("unroll") for (int n = 0; n < 2; ++n) _Pragma("unroll") for (int k = 0; k < 2; ++k) dst[n][k] = *(const LAS bf16x8*)(lds + PG8_SB(b, h) + boff + n * 2048 + k * 1024); } while (0)
; #define PG8_WAIT_V(n) asm volatile("s_waitcnt vmcnt(" #n ")" ::: "memory")
; #define PG8_WAIT_L(n) asm volatile("s_waitcnt lgkmcnt(" #n ")" ::: "memory")
; #define PG8_BAR __builtin_amdgcn_s_barrier()
; #define PG8_SCHED __builtin_amdgcn_sched_barrier(0)
; template <class Epi>
; __device__ __forceinline__ void gemm_phase(ldsp lds, const Gemm g, const StaticOrder& S, const Epi& E) {
;     ...
;         for (int t = 0; t < nt; t += 2) {
;             const bool last = (t == nt - 2);
;             const char* a1 = cA + (size_t)(t + 1) * kstep;
;             const char* a2 = last ? nA : cA + (size_t)(t + 2) * kstep; const char* b2 = last ? nB : cB + (size_t)(t + 2) * kstep;
;             const char* a3 = a2 + kstep; const char* b3 = b2 + kstep;
;             if constexpr (Epi::NPRE > 0) { if (last) E.pre(pre, cur, wr, fr); }
;             if constexpr (Epi::MID_T > 0) { if (t == Epi::MID_T) E.mid(acc, cur, wr, wc, fr, fq); }
;             PG8_LDB(B0, 0, 0); PG8_SCHED; PG8_LDA(At, 0, 0); PG8_STAGE(PG8_SA(1, 1), a1 + hstep, voffA);
;             PG8_WAIT_L(8); PG8_WAIT_V(10); PG8_BAR; PG8_WAIT_L(0); PG8_MMA(0, 0, At, B0); PG8_BAR; PG8_SCHED;
;             PG8_LDB(B1, 0, 1); PG8_STAGE(PG8_SB(0, 0), b2, voffB);
;             PG8_WAIT_V(10); PG8_BAR; PG8_WAIT_L(0); PG8_MMA(0, 1, At, B1); PG8_BAR;
;             PG8_LDA(At, 0, 1); PG8_STAGE(PG8_SA(0, 0), a2, voffA);
;             PG8_WAIT_V(10); PG8_BAR; PG8_WAIT_L(0); PG8_MMA(1, 0, At, B0); PG8_BAR; PG8_SCHED;
;             PG8_STAGE(PG8_SB(0, 1), b2 + hstep, voffB);
;             PG8_WAIT_V(10); PG8_BAR; PG8_MMA(1, 1, At, B1); PG8_BAR;
.LBB0_133:
	v_add_u32_e32 v147, s57, v181
	ds_read_b128 v[166:169], v147
	ds_read_b128 v[170:173], v147 offset:1024
	ds_read_b128 v[174:177], v147 offset:2048
	ds_read_b128 v[184:187], v147 offset:3072
	s_add_u32 s38, s4, 0xfff80080
	s_addc_u32 s39, s5, -1
	s_and_b64 s[36:37], s[36:37], exec
	s_cselect_b32 s39, s7, s39
	s_cselect_b32 s38, s29, s38
	s_cselect_b32 s37, s27, s42
	s_cselect_b32 s36, s40, s41
	s_add_i32 m0, s45, 0xc000
	ds_read_b128 v[188:191], v183
	ds_read_b128 v[192:195], v183 offset:1024
	ds_read_b128 v[196:199], v183 offset:2048
	ds_read_b128 v[200:203], v183 offset:3072
	ds_read_b128 v[204:207], v183 offset:4096
	ds_read_b128 v[208:211], v183 offset:5120
	ds_read_b128 v[212:215], v183 offset:6144
	ds_read_b128 v[216:219], v183 offset:7168
	global_load_lds_dwordx4 v138, s[4:5]
	s_add_i32 m0, s45, 0xe000
	s_nop 0
	global_load_lds_dwordx4 v140, s[4:5]
	s_waitcnt lgkmcnt(8)
	s_waitcnt vmcnt(10)
	s_barrier
	s_waitcnt lgkmcnt(0)
	s_setprio 1
	s_waitcnt lgkmcnt(0)
	v_mfma_f32_16x16x32_bf16 v[60:63], v[166:169], v[188:191], v[60:63]
	v_mfma_f32_16x16x32_bf16 v[56:59], v[174:177], v[188:191], v[56:59]
	v_mfma_f32_16x16x32_bf16 v[52:55], v[166:169], v[196:199], v[52:55]
	v_mfma_f32_16x16x32_bf16 v[48:51], v[174:177], v[196:199], v[48:51]
	v_mfma_f32_16x16x32_bf16 v[44:47], v[166:169], v[204:207], v[44:47]
	v_mfma_f32_16x16x32_bf16 v[40:43], v[174:177], v[204:207], v[40:43]
	v_mfma_f32_16x16x32_bf16 v[36:39], v[166:169], v[212:215], v[36:39]
	v_mfma_f32_16x16x32_bf16 v[32:35], v[174:177], v[212:215], v[32:35]
	v_mfma_f32_16x16x32_bf16 v[60:63], v[170:173], v[192:195], v[60:63]
	v_mfma_f32_16x16x32_bf16 v[56:59], v[184:187], v[192:195], v[56:59]
	v_mfma_f32_16x16x32_bf16 v[52:55], v[170:173], v[200:203], v[52:55]
	v_mfma_f32_16x16x32_bf16 v[48:51], v[184:187], v[200:203], v[48:51]
	v_mfma_f32_16x16x32_bf16 v[44:47], v[170:173], v[208:211], v[44:47]
	v_mfma_f32_16x16x32_bf16 v[40:43], v[184:187], v[208:211], v[40:43]
	v_mfma_f32_16x16x32_bf16 v[36:39], v[170:173], v[216:219], v[36:39]
	s_barrier
	v_mfma_f32_16x16x32_bf16 v[32:35], v[184:187], v[216:219], v[32:35]
	s_setprio 0
	s_add_i32 s59, s57, s44
	v_add_u32_e32 v147, s58, v181
	s_add_u32 s98, s36, 0x80
	s_addc_u32 s99, s37, 0
	s_mov_b32 m0, s59
	ds_read_b128 v[222:225], v147
	ds_read_b128 v[226:229], v147 offset:1024
	ds_read_b128 v[230:233], v147 offset:2048
	ds_read_b128 v[234:237], v147 offset:3072
	global_load_lds_dwordx4 v130, s[36:37]
	s_add_i32 m0, s59, 0x2000
	s_nop 0
	global_load_lds_dwordx4 v134, s[36:37]
	s_waitcnt vmcnt(10)
	s_barrier
	s_waitcnt lgkmcnt(0)
	s_setprio 1
	s_waitcnt lgkmcnt(0)
	v_mfma_f32_16x16x32_bf16 v[124:127], v[222:225], v[188:191], v[124:127]
	v_mfma_f32_16x16x32_bf16 v[120:123], v[230:233], v[188:191], v[120:123]
	v_mfma_f32_16x16x32_bf16 v[116:119], v[222:225], v[196:199], v[116:119]
	v_mfma_f32_16x16x32_bf16 v[112:115], v[230:233], v[196:199], v[112:115]
	v_mfma_f32_16x16x32_bf16 v[108:111], v[222:225], v[204:207], v[108:111]
	v_mfma_f32_16x16x32_bf16 v[104:107], v[230:233], v[204:207], v[104:107]
	v_mfma_f32_16x16x32_bf16 v[100:103], v[222:225], v[212:215], v[100:103]
	v_mfma_f32_16x16x32_bf16 v[96:99], v[230:233], v[212:215], v[96:99]
	v_mfma_f32_16x16x32_bf16 v[124:127], v[226:229], v[192:195], v[124:127]
	v_mfma_f32_16x16x32_bf16 v[120:123], v[234:237], v[192:195], v[120:123]
	v_mfma_f32_16x16x32_bf16 v[116:119], v[226:229], v[200:203], v[116:119]
	v_mfma_f32_16x16x32_bf16 v[112:115], v[234:237], v[200:203], v[112:115]
	v_mfma_f32_16x16x32_bf16 v[108:111], v[226:229], v[208:211], v[108:111]
	v_mfma_f32_16x16x32_bf16 v[104:107], v[234:237], v[208:211], v[104:107]
	v_mfma_f32_16x16x32_bf16 v[100:103], v[226:229], v[216:219], v[100:103]
	s_barrier
	v_mfma_f32_16x16x32_bf16 v[96:99], v[234:237], v[216:219], v[96:99]
	s_setprio 0
	s_mov_b32 m0, s45
	s_add_u32 s100, s38, 0x80
	s_addc_u32 s101, s39, 0
	ds_read_b128 v[188:191], v183 offset:16384
	ds_read_b128 v[192:195], v183 offset:17408
	ds_read_b128 v[196:199], v183 offset:18432
	ds_read_b128 v[200:203], v183 offset:19456
	ds_read_b128 v[204:207], v183 offset:20480
	ds_read_b128 v[208:211], v183 offset:21504
	ds_read_b128 v[212:215], v183 offset:22528
	ds_read_b128 v[216:219], v183 offset:23552
	global_load_lds_dwordx4 v128, s[38:39]
	s_mov_b32 m0, s46
	s_nop 0
	global_load_lds_dwordx4 v132, s[38:39]
	s_waitcnt vmcnt(10)
	s_barrier
	s_waitcnt lgkmcnt(0)
	s_setprio 1
	s_waitcnt lgkmcnt(0)
	v_mfma_f32_16x16x32_bf16 v[28:31], v[166:169], v[188:191], v[28:31]
	v_mfma_f32_16x16x32_bf16 v[24:27], v[174:177], v[188:191], v[24:27]
	v_mfma_f32_16x16x32_bf16 v[20:23], v[166:169], v[196:199], v[20:23]
	v_mfma_f32_16x16x32_bf16 v[16:19], v[174:177], v[196:199], v[16:19]
	v_mfma_f32_16x16x32_bf16 v[12:15], v[166:169], v[204:207], v[12:15]
	v_mfma_f32_16x16x32_bf16 v[8:11], v[174:177], v[204:207], v[8:11]
	v_mfma_f32_16x16x32_bf16 v[4:7], v[166:169], v[212:215], v[4:7]
	v_mfma_f32_16x16x32_bf16 v[0:3], v[174:177], v[212:215], v[0:3]
	v_mfma_f32_16x16x32_bf16 v[28:31], v[170:173], v[192:195], v[28:31]
	v_mfma_f32_16x16x32_bf16 v[24:27], v[184:187], v[192:195], v[24:27]
	v_mfma_f32_16x16x32_bf16 v[20:23], v[170:173], v[200:203], v[20:23]
	v_mfma_f32_16x16x32_bf16 v[16:19], v[184:187], v[200:203], v[16:19]
	v_mfma_f32_16x16x32_bf16 v[12:15], v[170:173], v[208:211], v[12:15]
	v_mfma_f32_16x16x32_bf16 v[8:11], v[184:187], v[208:211], v[8:11]
	v_mfma_f32_16x16x32_bf16 v[4:7], v[170:173], v[216:219], v[4:7]
	s_barrier
	v_mfma_f32_16x16x32_bf16 v[0:3], v[184:187], v[216:219], v[0:3]
	s_setprio 0
	s_add_u32 s60, s36, 0x80000
	s_addc_u32 s61, s37, 0
	s_add_i32 s59, s58, s44
	s_mov_b32 m0, s59
	s_nop 0
	global_load_lds_dwordx4 v130, s[60:61]
	s_add_i32 m0, s59, 0x2000
	s_nop 0
	global_load_lds_dwordx4 v134, s[60:61]
	s_waitcnt vmcnt(10)
	s_barrier
; #define PG8_STAGE(bufoff, gbase, voff) do { _Pragma("unroll") for (int _i = 0; _i < 2; ++_i) \
;         __builtin_amdgcn_global_load_lds((const unsigned*)((const char*)(gbase) + (voff)[_i]), (LAS unsigned*)(lds + (bufoff) + ldsw + _i * 8192), 16, 0, 0); } while (0)
; #define PG8_LDA(dst, b, h) do { _Pragma("unroll") for (int m = 0; m < 4; ++m) _Pragma("unroll") for (int k = 0; k < 2; ++k) dst[m][k] = *(const LAS bf16x8*)(lds + PG8_SA(b, h) + aoff + m * 2048 + k * 1024); } while (0)
; #define PG8_LDB(dst, b, h) do { _Pragma("unroll") for (int n = 0; n < 2; ++n) _Pragma("unroll") for (int k = 0; k < 2; ++k) dst[n][k] = *(const LAS bf16x8*)(lds + PG8_SB(b, h) + boff + n * 2048 + k * 1024); } while (0)
; #define PG8_MMA(ai, bj, At, Bt) do { __builtin_amdgcn_s_setprio(1); _Pragma("unroll") for (int m = 0; m < 4; ++m) _Pragma("unroll") for (int n = 0; n < 2; ++n) _Pragma("unroll") for (int k = 0; k < 2; ++k) \
;         acc[ai][bj][m][n] = __builtin_amdgcn_mfma_f32_16x16x32_bf16(Bt[n][k], At[m][k], acc[ai][bj][m][n], 0, 0, 0); __builtin_amdgcn_s_setprio(0); } while (0)
; #define PG8_WAIT_V(n) asm volatile("s_waitcnt vmcnt(" #n ")" ::: "memory")
; #define PG8_WAIT_L(n) asm volatile("s_waitcnt lgkmcnt(" #n ")" ::: "memory")
; #define PG8_BAR __builtin_amdgcn_s_barrier()
; #define PG8_SCHED __builtin_amdgcn_sched_barrier(0)
; template <class Epi>
; __device__ __forceinline__ void gemm_phase(ldsp lds, const Gemm g, const StaticOrder& S, const Epi& E) {
;     ...
;             PG8_WAIT_V(10); PG8_BAR; PG8_MMA(1, 1, At, B1); PG8_BAR;
;             PG8_LDB(B0, 1, 0); PG8_SCHED; PG8_LDA(At, 1, 0); PG8_STAGE(PG8_SA(0, 1), a2 + hstep, voffA);
;             PG8_WAIT_L(8); PG8_WAIT_V(10); PG8_BAR; PG8_WAIT_L(0); PG8_MMA(0, 0, At, B0); PG8_BAR; PG8_SCHED;
;             PG8_LDB(B1, 1, 1); PG8_STAGE(PG8_SB(1, 0), b3, voffB);
	s_setprio 1
	v_mfma_f32_16x16x32_bf16 v[92:95], v[222:225], v[188:191], v[92:95]
	v_mfma_f32_16x16x32_bf16 v[88:91], v[230:233], v[188:191], v[88:91]
	v_mfma_f32_16x16x32_bf16 v[84:87], v[222:225], v[196:199], v[84:87]
	v_mfma_f32_16x16x32_bf16 v[80:83], v[230:233], v[196:199], v[80:83]
	v_mfma_f32_16x16x32_bf16 v[76:79], v[222:225], v[204:207], v[76:79]
	v_mfma_f32_16x16x32_bf16 v[72:75], v[230:233], v[204:207], v[72:75]
	v_mfma_f32_16x16x32_bf16 v[68:71], v[222:225], v[212:215], v[68:71]
	v_mfma_f32_16x16x32_bf16 v[64:67], v[230:233], v[212:215], v[64:67]
	v_mfma_f32_16x16x32_bf16 v[92:95], v[226:229], v[192:195], v[92:95]
	v_mfma_f32_16x16x32_bf16 v[88:91], v[234:237], v[192:195], v[88:91]
	v_mfma_f32_16x16x32_bf16 v[84:87], v[226:229], v[200:203], v[84:87]
	v_mfma_f32_16x16x32_bf16 v[80:83], v[234:237], v[200:203], v[80:83]
	v_mfma_f32_16x16x32_bf16 v[76:79], v[226:229], v[208:211], v[76:79]
	v_mfma_f32_16x16x32_bf16 v[72:75], v[234:237], v[208:211], v[72:75]
	v_mfma_f32_16x16x32_bf16 v[68:71], v[226:229], v[216:219], v[68:71]
	s_barrier
	v_mfma_f32_16x16x32_bf16 v[64:67], v[234:237], v[216:219], v[64:67]
	s_setprio 0
	s_add_i32 s59, 0, 0x18000
	v_add_u32_e32 v147, s59, v181
	ds_read_b128 v[166:169], v147
	ds_read_b128 v[170:173], v147 offset:1024
	ds_read_b128 v[174:177], v147 offset:2048
	ds_read_b128 v[184:187], v147 offset:3072
	s_add_u32 s38, s38, 0x80000
	s_addc_u32 s39, s39, 0
	s_mov_b32 m0, s47
	ds_read_b128 v[188:191], v183 offset:32768
	ds_read_b128 v[192:195], v183 offset:33792
	ds_read_b128 v[196:199], v183 offset:34816
	ds_read_b128 v[200:203], v183 offset:35840
	ds_read_b128 v[204:207], v183 offset:36864
	ds_read_b128 v[208:211], v183 offset:37888
	ds_read_b128 v[212:215], v183 offset:38912
	ds_read_b128 v[216:219], v183 offset:39936
	global_load_lds_dwordx4 v128, s[38:39]
	s_mov_b32 m0, s50
	s_nop 0
	global_load_lds_dwordx4 v132, s[38:39]
	s_waitcnt lgkmcnt(8)
	s_waitcnt vmcnt(10)
	s_barrier
	s_waitcnt lgkmcnt(0)
	s_setprio 1
	s_waitcnt lgkmcnt(0)
	v_mfma_f32_16x16x32_bf16 v[60:63], v[166:169], v[188:191], v[60:63]
	v_mfma_f32_16x16x32_bf16 v[56:59], v[174:177], v[188:191], v[56:59]
	v_mfma_f32_16x16x32_bf16 v[52:55], v[166:169], v[196:199], v[52:55]
	v_mfma_f32_16x16x32_bf16 v[48:51], v[174:177], v[196:199], v[48:51]
	v_mfma_f32_16x16x32_bf16 v[44:47], v[166:169], v[204:207], v[44:47]
	v_mfma_f32_16x16x32_bf16 v[40:43], v[174:177], v[204:207], v[40:43]
	v_mfma_f32_16x16x32_bf16 v[36:39], v[166:169], v[212:215], v[36:39]
	v_mfma_f32_16x16x32_bf16 v[32:35], v[174:177], v[212:215], v[32:35]
	v_mfma_f32_16x16x32_bf16 v[60:63], v[170:173], v[192:195], v[60:63]
	v_mfma_f32_16x16x32_bf16 v[56:59], v[184:187], v[192:195], v[56:59]
	v_mfma_f32_16x16x32_bf16 v[52:55], v[170:173], v[200:203], v[52:55]
	v_mfma_f32_16x16x32_bf16 v[48:51], v[184:187], v[200:203], v[48:51]
	v_mfma_f32_16x16x32_bf16 v[44:47], v[170:173], v[208:211], v[44:47]
	v_mfma_f32_16x16x32_bf16 v[40:43], v[184:187], v[208:211], v[40:43]
	v_mfma_f32_16x16x32_bf16 v[36:39], v[170:173], v[216:219], v[36:39]
	s_barrier
	v_mfma_f32_16x16x32_bf16 v[32:35], v[184:187], v[216:219], v[32:35]
	s_setprio 0
	s_add_i32 s38, 0, 0x1c000
	s_add_i32 s39, s59, s44
	v_add_u32_e32 v147, s38, v181
	s_mov_b32 m0, s39
	ds_read_b128 v[222:225], v147
	ds_read_b128 v[226:229], v147 offset:1024
	ds_read_b128 v[230:233], v147 offset:2048
	ds_read_b128 v[234:237], v147 offset:3072
	global_load_lds_dwordx4 v130, s[98:99]
	s_add_i32 m0, s39, 0x2000
	s_nop 0
	global_load_lds_dwordx4 v134, s[98:99]
	s_waitcnt vmcnt(10)
	s_barrier
; #define PG8_STAGE(bufoff, gbase, voff) do { _Pragma("unroll") for (int _i = 0; _i < 2; ++_i) \
;         __builtin_amdgcn_global_load_lds((const unsigned*)((const char*)(gbase) + (voff)[_i]), (LAS unsigned*)(lds + (bufoff) + ldsw + _i * 8192), 16, 0, 0); } while (0)
; #define PG8_LDA(dst, b, h) do { _Pragma("unroll") for (int m = 0; m < 4; ++m) _Pragma("unroll") for (int k = 0; k < 2; ++k) dst[m][k] = *(const LAS bf16x8*)(lds + PG8_SA(b, h) + aoff + m * 2048 + k * 1024); } while (0)
; #define PG8_MMA(ai, bj, At, Bt) do { __builtin_amdgcn_s_setprio(1); _Pragma("unroll") for (int m = 0; m < 4; ++m) _Pragma("unroll") for (int n = 0; n < 2; ++n) _Pragma("unroll") for (int k = 0; k < 2; ++k) \
;         acc[ai][bj][m][n] = __builtin_amdgcn_mfma_f32_16x16x32_bf16(Bt[n][k], At[m][k], acc[ai][bj][m][n], 0, 0, 0); __builtin_amdgcn_s_setprio(0); } while (0)
; #define PG8_WAIT_V(n) asm volatile("s_waitcnt vmcnt(" #n ")" ::: "memory")
; #define PG8_WAIT_L(n) asm volatile("s_waitcnt lgkmcnt(" #n ")" ::: "memory")
; #define PG8_BAR __builtin_amdgcn_s_barrier()
; #define PG8_SCHED __builtin_amdgcn_sched_barrier(0)
; template <class Epi>
; __device__ __forceinline__ void gemm_phase(ldsp lds, const Gemm g, const StaticOrder& S, const Epi& E) {
;     ...
;             PG8_WAIT_V(10); PG8_BAR; PG8_WAIT_L(0); PG8_MMA(0, 1, At, B1); PG8_BAR;
;             PG8_LDA(At, 1, 1); PG8_STAGE(PG8_SA(1, 0), a3, voffA);
;             PG8_WAIT_V(10); PG8_BAR; PG8_WAIT_L(0); PG8_MMA(1, 0, At, B0); PG8_BAR; PG8_SCHED;
;             PG8_STAGE(PG8_SB(1, 1), b3 + hstep, voffB);
;             PG8_WAIT_V(10); PG8_BAR; PG8_MMA(1, 1, At, B1); PG8_BAR;
;         }
	s_waitcnt lgkmcnt(0)
	s_setprio 1
	s_waitcnt lgkmcnt(0)
	v_mfma_f32_16x16x32_bf16 v[124:127], v[222:225], v[188:191], v[124:127]
	v_mfma_f32_16x16x32_bf16 v[120:123], v[230:233], v[188:191], v[120:123]
	v_mfma_f32_16x16x32_bf16 v[116:119], v[222:225], v[196:199], v[116:119]
	v_mfma_f32_16x16x32_bf16 v[112:115], v[230:233], v[196:199], v[112:115]
	v_mfma_f32_16x16x32_bf16 v[108:111], v[222:225], v[204:207], v[108:111]
	v_mfma_f32_16x16x32_bf16 v[104:107], v[230:233], v[204:207], v[104:107]
	v_mfma_f32_16x16x32_bf16 v[100:103], v[222:225], v[212:215], v[100:103]
	v_mfma_f32_16x16x32_bf16 v[96:99], v[230:233], v[212:215], v[96:99]
	v_mfma_f32_16x16x32_bf16 v[124:127], v[226:229], v[192:195], v[124:127]
	v_mfma_f32_16x16x32_bf16 v[120:123], v[234:237], v[192:195], v[120:123]
	v_mfma_f32_16x16x32_bf16 v[116:119], v[226:229], v[200:203], v[116:119]
	v_mfma_f32_16x16x32_bf16 v[112:115], v[234:237], v[200:203], v[112:115]
	v_mfma_f32_16x16x32_bf16 v[108:111], v[226:229], v[208:211], v[108:111]
	v_mfma_f32_16x16x32_bf16 v[104:107], v[234:237], v[208:211], v[104:107]
	v_mfma_f32_16x16x32_bf16 v[100:103], v[226:229], v[216:219], v[100:103]
	s_barrier
	v_mfma_f32_16x16x32_bf16 v[96:99], v[234:237], v[216:219], v[96:99]
	s_setprio 0
	s_mov_b32 m0, s52
	ds_read_b128 v[188:191], v183 offset:49152
	ds_read_b128 v[192:195], v183 offset:50176
	ds_read_b128 v[196:199], v183 offset:51200
	ds_read_b128 v[200:203], v183 offset:52224
	ds_read_b128 v[204:207], v183 offset:53248
	ds_read_b128 v[208:211], v183 offset:54272
	ds_read_b128 v[212:215], v183 offset:55296
	ds_read_b128 v[216:219], v183 offset:56320
	global_load_lds_dwordx4 v128, s[100:101]
	s_mov_b32 m0, s53
	s_nop 0
	global_load_lds_dwordx4 v132, s[100:101]
	s_waitcnt vmcnt(10)
	s_barrier
	s_waitcnt lgkmcnt(0)
	s_setprio 1
	s_waitcnt lgkmcnt(0)
	v_mfma_f32_16x16x32_bf16 v[28:31], v[166:169], v[188:191], v[28:31]
	v_mfma_f32_16x16x32_bf16 v[24:27], v[174:177], v[188:191], v[24:27]
	v_mfma_f32_16x16x32_bf16 v[20:23], v[166:169], v[196:199], v[20:23]
	v_mfma_f32_16x16x32_bf16 v[16:19], v[174:177], v[196:199], v[16:19]
	v_mfma_f32_16x16x32_bf16 v[12:15], v[166:169], v[204:207], v[12:15]
	v_mfma_f32_16x16x32_bf16 v[8:11], v[174:177], v[204:207], v[8:11]
	v_mfma_f32_16x16x32_bf16 v[4:7], v[166:169], v[212:215], v[4:7]
	v_mfma_f32_16x16x32_bf16 v[0:3], v[174:177], v[212:215], v[0:3]
	v_mfma_f32_16x16x32_bf16 v[28:31], v[170:173], v[192:195], v[28:31]
	v_mfma_f32_16x16x32_bf16 v[24:27], v[184:187], v[192:195], v[24:27]
	v_mfma_f32_16x16x32_bf16 v[20:23], v[170:173], v[200:203], v[20:23]
	v_mfma_f32_16x16x32_bf16 v[16:19], v[184:187], v[200:203], v[16:19]
	v_mfma_f32_16x16x32_bf16 v[12:15], v[170:173], v[208:211], v[12:15]
	v_mfma_f32_16x16x32_bf16 v[8:11], v[184:187], v[208:211], v[8:11]
	v_mfma_f32_16x16x32_bf16 v[4:7], v[170:173], v[216:219], v[4:7]
	s_barrier
	v_mfma_f32_16x16x32_bf16 v[0:3], v[184:187], v[216:219], v[0:3]
	s_setprio 0
	s_add_u32 s36, s36, 0x80080
	s_addc_u32 s37, s37, 0
	s_add_i32 s38, s38, s44
	s_mov_b32 m0, s38
	s_nop 0
	global_load_lds_dwordx4 v130, s[36:37]
	s_add_i32 m0, s38, 0x2000
	s_nop 0
	global_load_lds_dwordx4 v134, s[36:37]
	s_waitcnt vmcnt(10)
	s_barrier
	s_setprio 1
	v_mfma_f32_16x16x32_bf16 v[92:95], v[222:225], v[188:191], v[92:95]
	v_mfma_f32_16x16x32_bf16 v[88:91], v[230:233], v[188:191], v[88:91]
	v_mfma_f32_16x16x32_bf16 v[84:87], v[222:225], v[196:199], v[84:87]
	v_mfma_f32_16x16x32_bf16 v[80:83], v[230:233], v[196:199], v[80:83]
	v_mfma_f32_16x16x32_bf16 v[76:79], v[222:225], v[204:207], v[76:79]
	v_mfma_f32_16x16x32_bf16 v[72:75], v[230:233], v[204:207], v[72:75]
	v_mfma_f32_16x16x32_bf16 v[68:71], v[222:225], v[212:215], v[68:71]
	v_mfma_f32_16x16x32_bf16 v[64:67], v[230:233], v[212:215], v[64:67]
	v_mfma_f32_16x16x32_bf16 v[92:95], v[226:229], v[192:195], v[92:95]
	v_mfma_f32_16x16x32_bf16 v[88:91], v[234:237], v[192:195], v[88:91]
	v_mfma_f32_16x16x32_bf16 v[84:87], v[226:229], v[200:203], v[84:87]
	v_mfma_f32_16x16x32_bf16 v[80:83], v[234:237], v[200:203], v[80:83]
	v_mfma_f32_16x16x32_bf16 v[76:79], v[226:229], v[208:211], v[76:79]
	v_mfma_f32_16x16x32_bf16 v[72:75], v[234:237], v[208:211], v[72:75]
	v_mfma_f32_16x16x32_bf16 v[68:71], v[226:229], v[216:219], v[68:71]
	s_barrier
	v_mfma_f32_16x16x32_bf16 v[64:67], v[234:237], v[216:219], v[64:67]
	s_setprio 0
	s_add_i32 s43, s43, 2
	s_add_u32 s4, s4, 0x100
	s_addc_u32 s5, s5, 0
	s_add_u32 s41, s41, 0x100
	s_addc_u32 s42, s42, 0
	s_cmp_gt_u32 s43, 29
	s_cbranch_scc1 .LBB0_136

; #define PG8_STAGE(bufoff, gbase, voff) do { _Pragma("unroll") for (int _i = 0; _i < 2; ++_i) \
;         __builtin_amdgcn_global_load_lds((const unsigned*)((const char*)(gbase) + (voff)[_i]), (LAS unsigned*)(lds + (bufoff) + ldsw + _i * 8192), 16, 0, 0); } while (0)
; #define PG8_LDA(dst, b, h) do { _Pragma("unroll") for (int m = 0; m < 4; ++m) _Pragma("unroll") for (int k = 0; k < 2; ++k) dst[m][k] = *(const LAS bf16x8*)(lds + PG8_SA(b, h) + aoff + m * 2048 + k * 1024); } while (0)
; #define PG8_LDB(dst, b, h) do { _Pragma("unroll") for (int n = 0; n < 2; ++n) _Pragma("unroll") for (int k = 0; k < 2; ++k) dst[n][k] = *(const LAS bf16x8*)(lds + PG8_SB(b, h) + boff + n * 2048 + k * 1024); } while (0)
; #define PG8_WAIT_V(n) asm volatile("s_waitcnt vmcnt(" #n ")" ::: "memory")
; #define PG8_WAIT_L(n) asm volatile("s_waitcnt lgkmcnt(" #n ")" ::: "memory")
; #define PG8_BAR __builtin_amdgcn_s_barrier()
; #define PG8_SCHED __builtin_amdgcn_sched_barrier(0)
; template <class Epi>
; __device__ __forceinline__ void gemm_phase(ldsp lds, const Gemm g, const StaticOrder& S, const Epi& E) {
;     ...
;         for (int t = 0; t < nt; t += 2) {
;             const bool last = (t == nt - 2);
;             const char* a1 = cA + (size_t)(t + 1) * kstep;
;             const char* a2 = last ? nA : cA + (size_t)(t + 2) * kstep; const char* b2 = last ? nB : cB + (size_t)(t + 2) * kstep;
;             const char* a3 = a2 + kstep; const char* b3 = b2 + kstep;
;             if constexpr (Epi::NPRE > 0) { if (last) E.pre(pre, cur, wr, fr); }
;             if constexpr (Epi::MID_T > 0) { if (t == Epi::MID_T) E.mid(acc, cur, wr, wc, fr, fq); }
;             PG8_LDB(B0, 0, 0); PG8_SCHED; PG8_LDA(At, 0, 0); PG8_STAGE(PG8_SA(1, 1), a1 + hstep, voffA);
;             PG8_WAIT_L(8); PG8_WAIT_V(10); PG8_BAR; PG8_WAIT_L(0); PG8_MMA(0, 0, At, B0); PG8_BAR; PG8_SCHED;
;             PG8_LDB(B1, 0, 1); PG8_STAGE(PG8_SB(0, 0), b2, voffB);
;             PG8_WAIT_V(10); PG8_BAR; PG8_WAIT_L(0); PG8_MMA(0, 1, At, B1); PG8_BAR;
;             PG8_LDA(At, 0, 1); PG8_STAGE(PG8_SA(0, 0), a2, voffA);
;             PG8_WAIT_V(10); PG8_BAR; PG8_WAIT_L(0); PG8_MMA(1, 0, At, B0); PG8_BAR; PG8_SCHED;
;             PG8_STAGE(PG8_SB(0, 1), b2 + hstep, voffB);
;             PG8_WAIT_V(10); PG8_BAR; PG8_MMA(1, 1, At, B1); PG8_BAR;
.LBB0_574:
	ds_read_b128 v[128:131], v219
	ds_read_b128 v[132:135], v219 offset:1024
	ds_read_b128 v[136:139], v219 offset:2048
	ds_read_b128 v[140:143], v219 offset:3072
	s_add_u32 s22, s20, 0xfffe0080
	s_addc_u32 s23, s21, -1
	s_cmp_eq_u32 s46, 4
	s_cselect_b32 s25, s13, s23
	s_cselect_b32 s24, s42, s22
	s_cselect_b32 s23, s11, s45
	s_cselect_b32 s22, s43, s44
	s_add_i32 m0, s19, 0xc000
	ds_read_b128 v[144:147], v221
	ds_read_b128 v[148:151], v221 offset:1024
	ds_read_b128 v[152:155], v221 offset:2048
	ds_read_b128 v[156:159], v221 offset:3072
	ds_read_b128 v[160:163], v221 offset:4096
	ds_read_b128 v[164:167], v221 offset:5120
	ds_read_b128 v[168:171], v221 offset:6144
	ds_read_b128 v[172:175], v221 offset:7168
	global_load_lds_dwordx4 v184, s[20:21]
	s_add_i32 m0, s19, 0xe000
	s_nop 0
	global_load_lds_dwordx4 v186, s[20:21]
	s_waitcnt lgkmcnt(8)
	s_waitcnt vmcnt(10)
	s_barrier
	s_waitcnt lgkmcnt(0)
	s_setprio 1
	s_waitcnt lgkmcnt(0)
	v_mfma_f32_16x16x32_bf16 v[124:127], v[128:131], v[144:147], v[124:127]
	v_mfma_f32_16x16x32_bf16 v[120:123], v[136:139], v[144:147], v[120:123]
	v_mfma_f32_16x16x32_bf16 v[116:119], v[128:131], v[152:155], v[116:119]
	v_mfma_f32_16x16x32_bf16 v[112:115], v[136:139], v[152:155], v[112:115]
	v_mfma_f32_16x16x32_bf16 v[108:111], v[128:131], v[160:163], v[108:111]
	v_mfma_f32_16x16x32_bf16 v[104:107], v[136:139], v[160:163], v[104:107]
	v_mfma_f32_16x16x32_bf16 v[100:103], v[128:131], v[168:171], v[100:103]
	v_mfma_f32_16x16x32_bf16 v[96:99], v[136:139], v[168:171], v[96:99]
	v_mfma_f32_16x16x32_bf16 v[124:127], v[132:135], v[148:151], v[124:127]
	v_mfma_f32_16x16x32_bf16 v[120:123], v[140:143], v[148:151], v[120:123]
	v_mfma_f32_16x16x32_bf16 v[116:119], v[132:135], v[156:159], v[116:119]
	v_mfma_f32_16x16x32_bf16 v[112:115], v[140:143], v[156:159], v[112:115]
	v_mfma_f32_16x16x32_bf16 v[108:111], v[132:135], v[164:167], v[108:111]
	v_mfma_f32_16x16x32_bf16 v[104:107], v[140:143], v[164:167], v[104:107]
	v_mfma_f32_16x16x32_bf16 v[100:103], v[132:135], v[172:175], v[100:103]
	s_barrier
	v_mfma_f32_16x16x32_bf16 v[96:99], v[140:143], v[172:175], v[96:99]
	s_setprio 0
	s_add_i32 s47, s38, s28
	s_add_u32 s98, s22, 0x80
	s_addc_u32 s99, s23, 0
	s_mov_b32 m0, s47
	ds_read_b128 v[192:195], v222
	ds_read_b128 v[196:199], v222 offset:1024
	ds_read_b128 v[200:203], v222 offset:2048
	ds_read_b128 v[204:207], v222 offset:3072
	global_load_lds_dwordx4 v178, s[22:23]
	s_add_i32 m0, s47, 0x2000
	s_nop 0
	global_load_lds_dwordx4 v182, s[22:23]
	s_waitcnt vmcnt(10)
	s_barrier
	s_waitcnt lgkmcnt(0)
	s_setprio 1
	s_waitcnt lgkmcnt(0)
	v_mfma_f32_16x16x32_bf16 v[60:63], v[192:195], v[144:147], v[60:63]
	v_mfma_f32_16x16x32_bf16 v[56:59], v[200:203], v[144:147], v[56:59]
	v_mfma_f32_16x16x32_bf16 v[52:55], v[192:195], v[152:155], v[52:55]
	v_mfma_f32_16x16x32_bf16 v[48:51], v[200:203], v[152:155], v[48:51]
	v_mfma_f32_16x16x32_bf16 v[44:47], v[192:195], v[160:163], v[44:47]
	v_mfma_f32_16x16x32_bf16 v[40:43], v[200:203], v[160:163], v[40:43]
	v_mfma_f32_16x16x32_bf16 v[36:39], v[192:195], v[168:171], v[36:39]
	v_mfma_f32_16x16x32_bf16 v[32:35], v[200:203], v[168:171], v[32:35]
	v_mfma_f32_16x16x32_bf16 v[60:63], v[196:199], v[148:151], v[60:63]
	v_mfma_f32_16x16x32_bf16 v[56:59], v[204:207], v[148:151], v[56:59]
	v_mfma_f32_16x16x32_bf16 v[52:55], v[196:199], v[156:159], v[52:55]
	v_mfma_f32_16x16x32_bf16 v[48:51], v[204:207], v[156:159], v[48:51]
	v_mfma_f32_16x16x32_bf16 v[44:47], v[196:199], v[164:167], v[44:47]
	v_mfma_f32_16x16x32_bf16 v[40:43], v[204:207], v[164:167], v[40:43]
	v_mfma_f32_16x16x32_bf16 v[36:39], v[196:199], v[172:175], v[36:39]
	s_barrier
	v_mfma_f32_16x16x32_bf16 v[32:35], v[204:207], v[172:175], v[32:35]
	s_setprio 0
	s_mov_b32 m0, s19
	s_add_u32 s100, s24, 0x80
	s_addc_u32 s101, s25, 0
	ds_read_b128 v[144:147], v221 offset:16384
	ds_read_b128 v[148:151], v221 offset:17408
	ds_read_b128 v[152:155], v221 offset:18432
	ds_read_b128 v[156:159], v221 offset:19456
	ds_read_b128 v[160:163], v221 offset:20480
	ds_read_b128 v[164:167], v221 offset:21504
	ds_read_b128 v[168:171], v221 offset:22528
	ds_read_b128 v[172:175], v221 offset:23552
	global_load_lds_dwordx4 v176, s[24:25]
	s_mov_b32 m0, s29
	s_nop 0
	global_load_lds_dwordx4 v180, s[24:25]
	s_waitcnt vmcnt(10)
	s_barrier
	s_waitcnt lgkmcnt(0)
	s_setprio 1
	s_waitcnt lgkmcnt(0)
	v_mfma_f32_16x16x32_bf16 v[92:95], v[128:131], v[144:147], v[92:95]
	v_mfma_f32_16x16x32_bf16 v[88:91], v[136:139], v[144:147], v[88:91]
	v_mfma_f32_16x16x32_bf16 v[84:87], v[128:131], v[152:155], v[84:87]
	v_mfma_f32_16x16x32_bf16 v[80:83], v[136:139], v[152:155], v[80:83]
	v_mfma_f32_16x16x32_bf16 v[76:79], v[128:131], v[160:163], v[76:79]
	v_mfma_f32_16x16x32_bf16 v[72:75], v[136:139], v[160:163], v[72:75]
	v_mfma_f32_16x16x32_bf16 v[68:71], v[128:131], v[168:171], v[68:71]
	v_mfma_f32_16x16x32_bf16 v[64:67], v[136:139], v[168:171], v[64:67]
	v_mfma_f32_16x16x32_bf16 v[92:95], v[132:135], v[148:151], v[92:95]
	v_mfma_f32_16x16x32_bf16 v[88:91], v[140:143], v[148:151], v[88:91]
	v_mfma_f32_16x16x32_bf16 v[84:87], v[132:135], v[156:159], v[84:87]
	v_mfma_f32_16x16x32_bf16 v[80:83], v[140:143], v[156:159], v[80:83]
	v_mfma_f32_16x16x32_bf16 v[76:79], v[132:135], v[164:167], v[76:79]
	v_mfma_f32_16x16x32_bf16 v[72:75], v[140:143], v[164:167], v[72:75]
	v_mfma_f32_16x16x32_bf16 v[68:71], v[132:135], v[172:175], v[68:71]
	s_barrier
	v_mfma_f32_16x16x32_bf16 v[64:67], v[140:143], v[172:175], v[64:67]
	s_setprio 0
	s_add_u32 s50, s22, 0x20000
	s_addc_u32 s51, s23, 0
	s_add_i32 s47, s39, s28
	s_mov_b32 m0, s47
	s_nop 0
	global_load_lds_dwordx4 v178, s[50:51]
	s_add_i32 m0, s47, 0x2000
	s_nop 0
	global_load_lds_dwordx4 v182, s[50:51]
	s_waitcnt vmcnt(10)
	s_barrier
; #define PG8_STAGE(bufoff, gbase, voff) do { _Pragma("unroll") for (int _i = 0; _i < 2; ++_i) \
;         __builtin_amdgcn_global_load_lds((const unsigned*)((const char*)(gbase) + (voff)[_i]), (LAS unsigned*)(lds + (bufoff) + ldsw + _i * 8192), 16, 0, 0); } while (0)
; #define PG8_LDA(dst, b, h) do { _Pragma("unroll") for (int m = 0; m < 4; ++m) _Pragma("unroll") for (int k = 0; k < 2; ++k) dst[m][k] = *(const LAS bf16x8*)(lds + PG8_SA(b, h) + aoff + m * 2048 + k * 1024); } while (0)
; #define PG8_LDB(dst, b, h) do { _Pragma("unroll") for (int n = 0; n < 2; ++n) _Pragma("unroll") for (int k = 0; k < 2; ++k) dst[n][k] = *(const LAS bf16x8*)(lds + PG8_SB(b, h) + boff + n * 2048 + k * 1024); } while (0)
; #define PG8_MMA(ai, bj, At, Bt) do { __builtin_amdgcn_s_setprio(1); _Pragma("unroll") for (int m = 0; m < 4; ++m) _Pragma("unroll") for (int n = 0; n < 2; ++n) _Pragma("unroll") for (int k = 0; k < 2; ++k) \
;         acc[ai][bj][m][n] = __builtin_amdgcn_mfma_f32_16x16x32_bf16(Bt[n][k], At[m][k], acc[ai][bj][m][n], 0, 0, 0); __builtin_amdgcn_s_setprio(0); } while (0)
; #define PG8_WAIT_V(n) asm volatile("s_waitcnt vmcnt(" #n ")" ::: "memory")
; #define PG8_WAIT_L(n) asm volatile("s_waitcnt lgkmcnt(" #n ")" ::: "memory")
; #define PG8_BAR __builtin_amdgcn_s_barrier()
; #define PG8_SCHED __builtin_amdgcn_sched_barrier(0)
; template <class Epi>
; __device__ __forceinline__ void gemm_phase(ldsp lds, const Gemm g, const StaticOrder& S, const Epi& E) {
;     ...
;             PG8_WAIT_V(10); PG8_BAR; PG8_MMA(1, 1, At, B1); PG8_BAR;
;             PG8_LDB(B0, 1, 0); PG8_SCHED; PG8_LDA(At, 1, 0); PG8_STAGE(PG8_SA(0, 1), a2 + hstep, voffA);
;             PG8_WAIT_L(8); PG8_WAIT_V(10); PG8_BAR; PG8_WAIT_L(0); PG8_MMA(0, 0, At, B0); PG8_BAR; PG8_SCHED;
;             PG8_LDB(B1, 1, 1); PG8_STAGE(PG8_SB(1, 0), b3, voffB);
;             PG8_WAIT_V(10); PG8_BAR; PG8_WAIT_L(0); PG8_MMA(0, 1, At, B1); PG8_BAR;
;             PG8_LDA(At, 1, 1); PG8_STAGE(PG8_SA(1, 0), a3, voffA);
;             PG8_WAIT_V(10); PG8_BAR; PG8_WAIT_L(0); PG8_MMA(1, 0, At, B0); PG8_BAR; PG8_SCHED;
	s_setprio 1
	v_mfma_f32_16x16x32_bf16 v[28:31], v[192:195], v[144:147], v[28:31]
	v_mfma_f32_16x16x32_bf16 v[24:27], v[200:203], v[144:147], v[24:27]
	v_mfma_f32_16x16x32_bf16 v[20:23], v[192:195], v[152:155], v[20:23]
	v_mfma_f32_16x16x32_bf16 v[16:19], v[200:203], v[152:155], v[16:19]
	v_mfma_f32_16x16x32_bf16 v[12:15], v[192:195], v[160:163], v[12:15]
	v_mfma_f32_16x16x32_bf16 v[8:11], v[200:203], v[160:163], v[8:11]
	v_mfma_f32_16x16x32_bf16 v[4:7], v[192:195], v[168:171], v[4:7]
	v_mfma_f32_16x16x32_bf16 v[0:3], v[200:203], v[168:171], v[0:3]
	v_mfma_f32_16x16x32_bf16 v[28:31], v[196:199], v[148:151], v[28:31]
	v_mfma_f32_16x16x32_bf16 v[24:27], v[204:207], v[148:151], v[24:27]
	v_mfma_f32_16x16x32_bf16 v[20:23], v[196:199], v[156:159], v[20:23]
	v_mfma_f32_16x16x32_bf16 v[16:19], v[204:207], v[156:159], v[16:19]
	v_mfma_f32_16x16x32_bf16 v[12:15], v[196:199], v[164:167], v[12:15]
	v_mfma_f32_16x16x32_bf16 v[8:11], v[204:207], v[164:167], v[8:11]
	v_mfma_f32_16x16x32_bf16 v[4:7], v[196:199], v[172:175], v[4:7]
	s_barrier
	v_mfma_f32_16x16x32_bf16 v[0:3], v[204:207], v[172:175], v[0:3]
	s_setprio 0
	s_add_i32 s47, 0, 0x18000
	v_add_u32_e32 v140, s47, v217
	ds_read_b128 v[128:131], v140
	ds_read_b128 v[132:135], v140 offset:1024
	ds_read_b128 v[136:139], v140 offset:2048
	ds_read_b128 v[140:143], v140 offset:3072
	s_add_u32 s24, s24, 0x20000
	s_addc_u32 s25, s25, 0
	s_mov_b32 m0, s30
	ds_read_b128 v[144:147], v221 offset:32768
	ds_read_b128 v[148:151], v221 offset:33792
	ds_read_b128 v[152:155], v221 offset:34816
	ds_read_b128 v[156:159], v221 offset:35840
	ds_read_b128 v[160:163], v221 offset:36864
	ds_read_b128 v[164:167], v221 offset:37888
	ds_read_b128 v[168:171], v221 offset:38912
	ds_read_b128 v[172:175], v221 offset:39936
	global_load_lds_dwordx4 v176, s[24:25]
	s_mov_b32 m0, s31
	s_nop 0
	global_load_lds_dwordx4 v180, s[24:25]
	s_waitcnt lgkmcnt(8)
	s_waitcnt vmcnt(10)
	s_barrier
	s_waitcnt lgkmcnt(0)
	s_setprio 1
	s_waitcnt lgkmcnt(0)
	v_mfma_f32_16x16x32_bf16 v[124:127], v[128:131], v[144:147], v[124:127]
	v_mfma_f32_16x16x32_bf16 v[120:123], v[136:139], v[144:147], v[120:123]
	v_mfma_f32_16x16x32_bf16 v[116:119], v[128:131], v[152:155], v[116:119]
	v_mfma_f32_16x16x32_bf16 v[112:115], v[136:139], v[152:155], v[112:115]
	v_mfma_f32_16x16x32_bf16 v[108:111], v[128:131], v[160:163], v[108:111]
	v_mfma_f32_16x16x32_bf16 v[104:107], v[136:139], v[160:163], v[104:107]
	v_mfma_f32_16x16x32_bf16 v[100:103], v[128:131], v[168:171], v[100:103]
	v_mfma_f32_16x16x32_bf16 v[96:99], v[136:139], v[168:171], v[96:99]
	v_mfma_f32_16x16x32_bf16 v[124:127], v[132:135], v[148:151], v[124:127]
	v_mfma_f32_16x16x32_bf16 v[120:123], v[140:143], v[148:151], v[120:123]
	v_mfma_f32_16x16x32_bf16 v[116:119], v[132:135], v[156:159], v[116:119]
	v_mfma_f32_16x16x32_bf16 v[112:115], v[140:143], v[156:159], v[112:115]
	v_mfma_f32_16x16x32_bf16 v[108:111], v[132:135], v[164:167], v[108:111]
	v_mfma_f32_16x16x32_bf16 v[104:107], v[140:143], v[164:167], v[104:107]
	v_mfma_f32_16x16x32_bf16 v[100:103], v[132:135], v[172:175], v[100:103]
	s_barrier
	v_mfma_f32_16x16x32_bf16 v[96:99], v[140:143], v[172:175], v[96:99]
	s_setprio 0
	s_add_i32 s24, 0, 0x1c000
	s_add_i32 s25, s47, s28
	v_add_u32_e32 v204, s24, v217
	s_mov_b32 m0, s25
	ds_read_b128 v[192:195], v204
	ds_read_b128 v[196:199], v204 offset:1024
	ds_read_b128 v[200:203], v204 offset:2048
	ds_read_b128 v[204:207], v204 offset:3072
	global_load_lds_dwordx4 v178, s[98:99]
	s_add_i32 m0, s25, 0x2000
	s_nop 0
	global_load_lds_dwordx4 v182, s[98:99]
	s_waitcnt vmcnt(10)
	s_barrier
	s_waitcnt lgkmcnt(0)
	s_setprio 1
	s_waitcnt lgkmcnt(0)
	v_mfma_f32_16x16x32_bf16 v[60:63], v[192:195], v[144:147], v[60:63]
	v_mfma_f32_16x16x32_bf16 v[56:59], v[200:203], v[144:147], v[56:59]
	v_mfma_f32_16x16x32_bf16 v[52:55], v[192:195], v[152:155], v[52:55]
	v_mfma_f32_16x16x32_bf16 v[48:51], v[200:203], v[152:155], v[48:51]
	v_mfma_f32_16x16x32_bf16 v[44:47], v[192:195], v[160:163], v[44:47]
	v_mfma_f32_16x16x32_bf16 v[40:43], v[200:203], v[160:163], v[40:43]
	v_mfma_f32_16x16x32_bf16 v[36:39], v[192:195], v[168:171], v[36:39]
	v_mfma_f32_16x16x32_bf16 v[32:35], v[200:203], v[168:171], v[32:35]
	v_mfma_f32_16x16x32_bf16 v[60:63], v[196:199], v[148:151], v[60:63]
	v_mfma_f32_16x16x32_bf16 v[56:59], v[204:207], v[148:151], v[56:59]
	v_mfma_f32_16x16x32_bf16 v[52:55], v[196:199], v[156:159], v[52:55]
	v_mfma_f32_16x16x32_bf16 v[48:51], v[204:207], v[156:159], v[48:51]
	v_mfma_f32_16x16x32_bf16 v[44:47], v[196:199], v[164:167], v[44:47]
	v_mfma_f32_16x16x32_bf16 v[40:43], v[204:207], v[164:167], v[40:43]
	v_mfma_f32_16x16x32_bf16 v[36:39], v[196:199], v[172:175], v[36:39]
	s_barrier
	v_mfma_f32_16x16x32_bf16 v[32:35], v[204:207], v[172:175], v[32:35]
	s_setprio 0
	s_mov_b32 m0, s34
	ds_read_b128 v[144:147], v221 offset:49152
	ds_read_b128 v[148:151], v221 offset:50176
	ds_read_b128 v[152:155], v221 offset:51200
	ds_read_b128 v[156:159], v221 offset:52224
	ds_read_b128 v[160:163], v221 offset:53248
	ds_read_b128 v[164:167], v221 offset:54272
	ds_read_b128 v[168:171], v221 offset:55296
	ds_read_b128 v[172:175], v221 offset:56320
	global_load_lds_dwordx4 v176, s[100:101]
	s_mov_b32 m0, s35
	s_nop 0
	global_load_lds_dwordx4 v180, s[100:101]
	s_waitcnt vmcnt(10)
	s_barrier
; #define PG8_STAGE(bufoff, gbase, voff) do { _Pragma("unroll") for (int _i = 0; _i < 2; ++_i) \
;         __builtin_amdgcn_global_load_lds((const unsigned*)((const char*)(gbase) + (voff)[_i]), (LAS unsigned*)(lds + (bufoff) + ldsw + _i * 8192), 16, 0, 0); } while (0)
; #define PG8_MMA(ai, bj, At, Bt) do { __builtin_amdgcn_s_setprio(1); _Pragma("unroll") for (int m = 0; m < 4; ++m) _Pragma("unroll") for (int n = 0; n < 2; ++n) _Pragma("unroll") for (int k = 0; k < 2; ++k) \
;         acc[ai][bj][m][n] = __builtin_amdgcn_mfma_f32_16x16x32_bf16(Bt[n][k], At[m][k], acc[ai][bj][m][n], 0, 0, 0); __builtin_amdgcn_s_setprio(0); } while (0)
; #define PG8_WAIT_V(n) asm volatile("s_waitcnt vmcnt(" #n ")" ::: "memory")
; #define PG8_WAIT_L(n) asm volatile("s_waitcnt lgkmcnt(" #n ")" ::: "memory")
; #define PG8_BAR __builtin_amdgcn_s_barrier()
; #define PG8_SCHED __builtin_amdgcn_sched_barrier(0)
; template <class Epi>
; __device__ __forceinline__ void gemm_phase(ldsp lds, const Gemm g, const StaticOrder& S, const Epi& E) {
;     ...
;             PG8_WAIT_V(10); PG8_BAR; PG8_WAIT_L(0); PG8_MMA(1, 0, At, B0); PG8_BAR; PG8_SCHED;
;             PG8_STAGE(PG8_SB(1, 1), b3 + hstep, voffB);
;             PG8_WAIT_V(10); PG8_BAR; PG8_MMA(1, 1, At, B1); PG8_BAR;
;         }
;         E(acc, cur, wr, wc, fr, fq, pre);
;     __device__ __forceinline__ void operator()(EPI_ARGS) const {
;         const int row0 = u.pm * 256 + wr * 64 + fr, col0 = u.pn * 256 + wc * 32 + 8 * fq;
; #pragma unroll
;         for (int bj = 0; bj < 2; ++bj) { const f32x4 b0 = *(const f32x4*)(bias + col0 + bj * 128), b1 = *(const f32x4*)(bias + col0 + bj * 128 + 4);
;             u32x4 hw[2][4];
; #pragma unroll
;             for (int ai = 0; ai < 2; ++ai)
; #pragma unroll
;                 for (int m = 0; m < 4; ++m) hw[ai][m] = *(const u32x4*)(H + (size_t)(row0 + ai * 128 + m * 16) * 512 + col0 + bj * 128);
	s_waitcnt lgkmcnt(0)
	s_setprio 1
	s_waitcnt lgkmcnt(0)
	v_mfma_f32_16x16x32_bf16 v[92:95], v[128:131], v[144:147], v[92:95]
	v_mfma_f32_16x16x32_bf16 v[88:91], v[136:139], v[144:147], v[88:91]
	v_mfma_f32_16x16x32_bf16 v[84:87], v[128:131], v[152:155], v[84:87]
	v_mfma_f32_16x16x32_bf16 v[80:83], v[136:139], v[152:155], v[80:83]
	v_mfma_f32_16x16x32_bf16 v[76:79], v[128:131], v[160:163], v[76:79]
	v_mfma_f32_16x16x32_bf16 v[72:75], v[136:139], v[160:163], v[72:75]
	v_mfma_f32_16x16x32_bf16 v[68:71], v[128:131], v[168:171], v[68:71]
	v_mfma_f32_16x16x32_bf16 v[64:67], v[136:139], v[168:171], v[64:67]
	v_mfma_f32_16x16x32_bf16 v[92:95], v[132:135], v[148:151], v[92:95]
	v_mfma_f32_16x16x32_bf16 v[88:91], v[140:143], v[148:151], v[88:91]
	v_mfma_f32_16x16x32_bf16 v[84:87], v[132:135], v[156:159], v[84:87]
	v_mfma_f32_16x16x32_bf16 v[80:83], v[140:143], v[156:159], v[80:83]
	v_mfma_f32_16x16x32_bf16 v[76:79], v[132:135], v[164:167], v[76:79]
	v_mfma_f32_16x16x32_bf16 v[72:75], v[140:143], v[164:167], v[72:75]
	v_mfma_f32_16x16x32_bf16 v[68:71], v[132:135], v[172:175], v[68:71]
	s_barrier
	v_mfma_f32_16x16x32_bf16 v[64:67], v[140:143], v[172:175], v[64:67]
	s_setprio 0
	s_add_u32 s22, s22, 0x20080
	s_addc_u32 s23, s23, 0
	s_add_i32 s24, s24, s28
	s_mov_b32 m0, s24
	s_nop 0
	global_load_lds_dwordx4 v178, s[22:23]
	s_add_i32 m0, s24, 0x2000
	s_nop 0
	global_load_lds_dwordx4 v182, s[22:23]
	s_waitcnt vmcnt(10)
	s_barrier
	s_setprio 1
	v_mfma_f32_16x16x32_bf16 v[28:31], v[192:195], v[144:147], v[28:31]
	v_mfma_f32_16x16x32_bf16 v[24:27], v[200:203], v[144:147], v[24:27]
	v_mfma_f32_16x16x32_bf16 v[20:23], v[192:195], v[152:155], v[20:23]
	v_mfma_f32_16x16x32_bf16 v[16:19], v[200:203], v[152:155], v[16:19]
	v_mfma_f32_16x16x32_bf16 v[12:15], v[192:195], v[160:163], v[12:15]
	v_mfma_f32_16x16x32_bf16 v[8:11], v[200:203], v[160:163], v[8:11]
	v_mfma_f32_16x16x32_bf16 v[4:7], v[192:195], v[168:171], v[4:7]
	v_mfma_f32_16x16x32_bf16 v[0:3], v[200:203], v[168:171], v[0:3]
	v_mfma_f32_16x16x32_bf16 v[28:31], v[196:199], v[148:151], v[28:31]
	v_mfma_f32_16x16x32_bf16 v[24:27], v[204:207], v[148:151], v[24:27]
	v_mfma_f32_16x16x32_bf16 v[20:23], v[196:199], v[156:159], v[20:23]
	v_mfma_f32_16x16x32_bf16 v[16:19], v[204:207], v[156:159], v[16:19]
	v_mfma_f32_16x16x32_bf16 v[12:15], v[196:199], v[164:167], v[12:15]
	v_mfma_f32_16x16x32_bf16 v[8:11], v[204:207], v[164:167], v[8:11]
	v_mfma_f32_16x16x32_bf16 v[4:7], v[196:199], v[172:175], v[4:7]
	s_barrier
	v_mfma_f32_16x16x32_bf16 v[0:3], v[204:207], v[172:175], v[0:3]
	s_setprio 0
	s_add_i32 s46, s46, 2
	s_add_u32 s20, s20, 0x100
	s_addc_u32 s21, s21, 0
	s_add_u32 s44, s44, 0x100
	s_addc_u32 s45, s45, 0
	s_cmp_gt_u32 s46, 5
	s_cbranch_scc0 .LBB0_574
	v_lshl_or_b32 v136, s41, 8, v218
	v_readlane_b32 s72, v246, 6
	v_ashrrev_i32_e32 v137, 31, v136
	v_readlane_b32 s86, v246, 20
	v_readlane_b32 s87, v246, 21
	v_lshl_add_u32 v140, s18, 8, v216
	v_ashrrev_i32_e32 v141, 31, v140
	v_lshl_add_u64 v[192:193], v[136:137], 2, s[86:87]
	v_lshlrev_b64 v[194:195], 1, v[136:137]
	global_load_dwordx4 v[132:135], v[192:193], off
	global_load_dwordx4 v[128:131], v[192:193], off offset:16
	v_lshlrev_b64 v[136:137], 10, v[140:141]
	v_lshl_add_u64 v[150:151], s[4:5], 0, v[194:195]
	v_lshl_add_u64 v[142:143], v[150:151], 0, v[136:137]
	global_load_dwordx4 v[136:139], v[142:143], off
	v_or_b32_e32 v210, 16, v140
	v_or_b32_e32 v206, 48, v140
	v_add_u32_e32 v204, 0x80, v140
	v_add_u32_e32 v198, 0xb0, v140
	v_ashrrev_i32_e32 v211, 31, v210
	v_ashrrev_i32_e32 v207, 31, v206
	v_ashrrev_i32_e32 v205, 31, v204
	v_ashrrev_i32_e32 v199, 31, v198
	v_lshlrev_b64 v[144:145], 10, v[210:211]
	v_lshlrev_b64 v[152:153], 10, v[206:207]
	v_lshlrev_b64 v[154:155], 10, v[204:205]
	v_lshlrev_b64 v[160:161], 10, v[198:199]
	v_lshl_add_u64 v[148:149], v[150:151], 0, v[144:145]
	v_lshl_add_u64 v[144:145], v[150:151], 0, v[152:153]
	v_lshl_add_u64 v[168:169], v[150:151], 0, v[154:155]
	v_lshl_add_u64 v[212:213], v[150:151], 0, v[160:161]
	global_load_dwordx4 v[152:155], v[148:149], off
	global_load_dwordx4 v[160:163], v[142:143], off offset:256
	v_or_b32_e32 v208, 32, v140
	v_add_u32_e32 v202, 0x90, v140
	v_add_u32_e32 v200, 0xa0, v140
	v_ashrrev_i32_e32 v209, 31, v208
	v_ashrrev_i32_e32 v203, 31, v202
	v_ashrrev_i32_e32 v201, 31, v200
	v_lshlrev_b64 v[146:147], 10, v[208:209]
	v_lshlrev_b64 v[156:157], 10, v[202:203]
	v_lshlrev_b64 v[158:159], 10, v[200:201]
	v_lshl_add_u64 v[146:147], v[150:151], 0, v[146:147]
	v_lshl_add_u64 v[166:167], v[150:151], 0, v[156:157]
	v_lshl_add_u64 v[164:165], v[150:151], 0, v[158:159]
	v_mov_b64_e32 v[196:197], s[6:7]
	s_and_b64 vcc, exec, s[2:3]
	s_mov_b32 s18, s12
	s_mov_b32 s41, s10
	s_mov_b64 s[22:23], s[16:17]
	v_readlane_b32 s73, v246, 7
	v_readlane_b32 s74, v246, 8
	v_readlane_b32 s75, v246, 9
	v_readlane_b32 s76, v246, 10
	v_readlane_b32 s77, v246, 11
	v_readlane_b32 s78, v246, 12
	v_readlane_b32 s79, v246, 13
	v_readlane_b32 s80, v246, 14
	v_readlane_b32 s81, v246, 15
	v_readlane_b32 s82, v246, 16
	v_readlane_b32 s83, v246, 17
	v_readlane_b32 s84, v246, 18
	v_readlane_b32 s85, v246, 19
	s_waitcnt vmcnt(0)
; __device__ __forceinline__ float sigm(float x) { return __builtin_amdgcn_rcpf(1.0f + __builtin_amdgcn_exp2f(-1.4426950408889634f * x)); }
;     __device__ __forceinline__ void operator()(EPI_ARGS) const {
;     ...
;         for (int bj = 0; bj < 2; ++bj) { const f32x4 b0 = *(const f32x4*)(bias + col0 + bj * 128), b1 = *(const f32x4*)(bias + col0 + bj * 128 + 4);
;             u32x4 hw[2][4];
; #pragma unroll
;             for (int ai = 0; ai < 2; ++ai)
; #pragma unroll
;                 for (int m = 0; m < 4; ++m) hw[ai][m] = *(const u32x4*)(H + (size_t)(row0 + ai * 128 + m * 16) * 512 + col0 + bj * 128);
; #pragma unroll
;             for (int ai = 0; ai < 2; ++ai)
; #pragma unroll
;                 for (int m = 0; m < 4; ++m) { const size_t off = (size_t)(row0 + ai * 128 + m * 16) * 512 + col0 + bj * 128;
;                     f32x4 h0, h1; unpack8(hw[ai][m], h0, h1);
;                     f32x4 v0 = acc[ai][bj][m][0] + b0, v1 = acc[ai][bj][m][1] + b1;
; #pragma unroll
;                     for (int j = 0; j < 4; ++j) { v0[j] = h0[j] * sigm(v0[j]); v1[j] = h1[j] * sigm(v1[j]); }
;                     *(u32x4*)(O + (size_t)(row0 + ai * 128 + m * 16) * KAB + 1024 + col0 + bj * 128) = pack8(v0, v1); } }
	v_pk_add_f32 v[124:125], v[124:125], v[132:133]
	v_pk_add_f32 v[126:127], v[126:127], v[134:135]
	v_pk_add_f32 v[122:123], v[122:123], v[130:131]
	v_pk_add_f32 v[120:121], v[120:121], v[128:129]
	v_mul_f32_e32 v124, 0xbfb8aa3b, v124
	v_mul_f32_e32 v125, 0xbfb8aa3b, v125
	v_mul_f32_e32 v120, 0xbfb8aa3b, v120
	v_mul_f32_e32 v141, 0xbfb8aa3b, v121
	v_mul_f32_e32 v126, 0xbfb8aa3b, v126
	v_mul_f32_e32 v142, 0xbfb8aa3b, v122
	v_mul_f32_e32 v127, 0xbfb8aa3b, v127
	v_mul_f32_e32 v143, 0xbfb8aa3b, v123
	v_exp_f32_e32 v150, v124
	v_exp_f32_e32 v156, v125
	v_exp_f32_e32 v151, v120
	v_lshlrev_b32_e32 v120, 16, v136
	v_and_b32_e32 v121, 0xffff0000, v136
	v_exp_f32_e32 v136, v141
	v_lshlrev_b32_e32 v122, 16, v138
	v_and_b32_e32 v123, 0xffff0000, v138
	v_exp_f32_e32 v138, v126
	v_exp_f32_e32 v141, v142
	v_exp_f32_e32 v142, v127
	v_lshlrev_b32_e32 v124, 16, v137
	v_and_b32_e32 v125, 0xffff0000, v137
	v_exp_f32_e32 v137, v143
	v_lshlrev_b32_e32 v126, 16, v139
	v_and_b32_e32 v127, 0xffff0000, v139
	v_add_f32_e32 v139, 1.0, v150
	v_add_f32_e32 v150, 1.0, v156
	v_add_f32_e32 v143, 1.0, v151
	v_add_f32_e32 v151, 1.0, v136
	v_add_f32_e32 v156, 1.0, v138
	v_add_f32_e32 v141, 1.0, v141
	v_add_f32_e32 v157, 1.0, v142
	v_add_f32_e32 v158, 1.0, v137
	v_rcp_f32_e32 v136, v139
	v_rcp_f32_e32 v137, v150
	v_rcp_f32_e32 v138, v143
	v_rcp_f32_e32 v139, v151
	v_rcp_f32_e32 v142, v156
	v_rcp_f32_e32 v150, v141
	v_rcp_f32_e32 v143, v157
	v_rcp_f32_e32 v151, v158
	v_pk_mul_f32 v[120:121], v[136:137], v[120:121]
	v_pk_mul_f32 v[122:123], v[138:139], v[122:123]
	v_pk_mul_f32 v[124:125], v[142:143], v[124:125]
	v_pk_mul_f32 v[126:127], v[150:151], v[126:127]
	v_cvt_pk_bf16_f32 v224, v120, v121
	v_mad_i64_i32 v[120:121], s[20:21], v140, s40, v[196:197]
	v_cvt_pk_bf16_f32 v225, v124, v125
	v_cvt_pk_bf16_f32 v226, v122, v123
	v_cvt_pk_bf16_f32 v227, v126, v127
	v_lshl_add_u64 v[214:215], v[120:121], 0, v[194:195]
	global_load_dwordx4 v[156:159], v[148:149], off offset:256
	global_load_dwordx4 v[228:231], v[146:147], off
	s_nop 0
	global_load_dwordx4 v[148:151], v[146:147], off offset:256
	global_load_dwordx4 v[232:235], v[144:145], off
	s_nop 0
	global_load_dwordx4 v[144:147], v[144:145], off offset:256
	s_nop 0
	global_load_dwordx4 v[236:239], v[168:169], off
	global_load_dwordx4 v[140:143], v[168:169], off offset:256
	global_load_dwordx4 v[172:175], v[166:167], off
	global_load_dwordx4 v[136:139], v[166:167], off offset:256
	s_nop 0
	global_load_dwordx4 v[168:171], v[164:165], off
	global_load_dwordx4 v[124:127], v[164:165], off offset:256
	s_nop 0
	global_load_dwordx4 v[164:167], v[212:213], off
	global_load_dwordx4 v[120:123], v[212:213], off offset:256
	v_pk_add_f32 v[116:117], v[116:117], v[132:133]
	v_pk_add_f32 v[114:115], v[114:115], v[130:131]
	v_mul_f32_e32 v116, 0xbfb8aa3b, v116
	v_mul_f32_e32 v117, 0xbfb8aa3b, v117
	v_exp_f32_e32 v116, v116
	v_exp_f32_e32 v117, v117
	v_pk_add_f32 v[118:119], v[118:119], v[134:135]
	v_pk_add_f32 v[112:113], v[112:113], v[128:129]
	v_add_f32_e32 v116, 1.0, v116
	v_add_f32_e32 v117, 1.0, v117
	v_rcp_f32_e32 v116, v116
	v_rcp_f32_e32 v117, v117
	v_mul_f32_e32 v114, 0xbfb8aa3b, v114
	v_mul_f32_e32 v112, 0xbfb8aa3b, v112
	v_mul_f32_e32 v113, 0xbfb8aa3b, v113
	v_lshlrev_b32_e32 v212, 16, v152
	v_and_b32_e32 v213, 0xffff0000, v152
	v_mul_f32_e32 v118, 0xbfb8aa3b, v118
	v_exp_f32_e32 v152, v114
	v_mul_f32_e32 v114, 0xbfb8aa3b, v119
	v_exp_f32_e32 v112, v112
	v_exp_f32_e32 v113, v113
	v_exp_f32_e32 v118, v118
	v_exp_f32_e32 v119, v114
	v_mul_f32_e32 v115, 0xbfb8aa3b, v115
	v_pk_mul_f32 v[116:117], v[116:117], v[212:213]
	v_lshlrev_b32_e32 v212, 16, v154
	v_and_b32_e32 v213, 0xffff0000, v154
	v_exp_f32_e32 v154, v115
	v_pk_add_f32 v[108:109], v[108:109], v[132:133]
	v_pk_add_f32 v[104:105], v[104:105], v[128:129]
	v_mul_f32_e32 v108, 0xbfb8aa3b, v108
	v_mul_f32_e32 v109, 0xbfb8aa3b, v109
	v_add_f32_e32 v112, 1.0, v112
	v_add_f32_e32 v113, 1.0, v113
	v_add_f32_e32 v118, 1.0, v118
	v_add_f32_e32 v119, 1.0, v119
	v_exp_f32_e32 v108, v108
	v_mul_f32_e32 v104, 0xbfb8aa3b, v104
	v_exp_f32_e32 v109, v109
	v_mul_f32_e32 v105, 0xbfb8aa3b, v105
	v_rcp_f32_e32 v112, v112
	v_rcp_f32_e32 v113, v113
	v_rcp_f32_e32 v114, v118
	v_add_f32_e32 v118, 1.0, v152
	v_rcp_f32_e32 v115, v119
	v_add_f32_e32 v119, 1.0, v154
	v_exp_f32_e32 v104, v104
	v_exp_f32_e32 v105, v105
	v_rcp_f32_e32 v118, v118
	v_rcp_f32_e32 v119, v119
	v_lshlrev_b32_e32 v152, 16, v153
	v_and_b32_e32 v153, 0xffff0000, v153
	v_add_f32_e32 v108, 1.0, v108
	v_add_f32_e32 v109, 1.0, v109
	v_pk_mul_f32 v[112:113], v[112:113], v[212:213]
	v_pk_mul_f32 v[152:153], v[114:115], v[152:153]
	v_lshlrev_b32_e32 v114, 16, v155
	v_and_b32_e32 v115, 0xffff0000, v155
	v_rcp_f32_e32 v108, v108
	v_add_f32_e32 v104, 1.0, v104
	v_rcp_f32_e32 v109, v109
	v_add_f32_e32 v105, 1.0, v105
	v_pk_mul_f32 v[118:119], v[118:119], v[114:115]
	v_cvt_pk_bf16_f32 v114, v116, v117
	v_cvt_pk_bf16_f32 v116, v112, v113
	v_mad_i64_i32 v[112:113], s[20:21], v210, s40, v[196:197]
	v_rcp_f32_e32 v104, v104
	v_rcp_f32_e32 v105, v105
	v_cvt_pk_bf16_f32 v115, v152, v153
	v_cvt_pk_bf16_f32 v117, v118, v119
	v_lshl_add_u64 v[112:113], v[112:113], 0, v[194:195]
	global_store_dwordx4 v[112:113], v[114:117], off offset:2048
	v_pk_add_f32 v[106:107], v[106:107], v[130:131]
	v_pk_add_f32 v[110:111], v[110:111], v[134:135]
	s_waitcnt vmcnt(0)
; __device__ __forceinline__ float sigm(float x) { return __builtin_amdgcn_rcpf(1.0f + __builtin_amdgcn_exp2f(-1.4426950408889634f * x)); }
;     __device__ __forceinline__ void operator()(EPI_ARGS) const {
;     ...
;             for (int ai = 0; ai < 2; ++ai)
; #pragma unroll
;                 for (int m = 0; m < 4; ++m) { const size_t off = (size_t)(row0 + ai * 128 + m * 16) * 512 + col0 + bj * 128;
;                     f32x4 h0, h1; unpack8(hw[ai][m], h0, h1);
;                     f32x4 v0 = acc[ai][bj][m][0] + b0, v1 = acc[ai][bj][m][1] + b1;
; #pragma unroll
;                     for (int j = 0; j < 4; ++j) { v0[j] = h0[j] * sigm(v0[j]); v1[j] = h1[j] * sigm(v1[j]); }
;                     *(u32x4*)(O + (size_t)(row0 + ai * 128 + m * 16) * KAB + 1024 + col0 + bj * 128) = pack8(v0, v1); } }
	v_lshlrev_b32_e32 v114, 16, v228
	v_and_b32_e32 v115, 0xffff0000, v228
	v_pk_mul_f32 v[108:109], v[108:109], v[114:115]
	v_lshlrev_b32_e32 v114, 16, v230
	v_and_b32_e32 v115, 0xffff0000, v230
	v_mul_f32_e32 v106, 0xbfb8aa3b, v106
	v_mul_f32_e32 v110, 0xbfb8aa3b, v110
	v_pk_mul_f32 v[104:105], v[104:105], v[114:115]
	v_exp_f32_e32 v114, v106
	v_mul_f32_e32 v106, 0xbfb8aa3b, v111
	v_exp_f32_e32 v110, v110
	v_exp_f32_e32 v111, v106
	v_mul_f32_e32 v107, 0xbfb8aa3b, v107
	v_exp_f32_e32 v116, v107
	v_pk_add_f32 v[100:101], v[100:101], v[132:133]
	v_pk_add_f32 v[96:97], v[96:97], v[128:129]
	v_mul_f32_e32 v100, 0xbfb8aa3b, v100
	v_mul_f32_e32 v101, 0xbfb8aa3b, v101
	v_add_f32_e32 v110, 1.0, v110
	v_add_f32_e32 v111, 1.0, v111
	v_exp_f32_e32 v100, v100
	v_mul_f32_e32 v96, 0xbfb8aa3b, v96
	v_exp_f32_e32 v101, v101
	v_mul_f32_e32 v97, 0xbfb8aa3b, v97
	v_rcp_f32_e32 v106, v110
	v_add_f32_e32 v110, 1.0, v114
	v_rcp_f32_e32 v107, v111
	v_add_f32_e32 v111, 1.0, v116
	v_exp_f32_e32 v96, v96
	v_exp_f32_e32 v97, v97
	v_rcp_f32_e32 v110, v110
	v_rcp_f32_e32 v111, v111
	v_lshlrev_b32_e32 v114, 16, v229
	v_and_b32_e32 v115, 0xffff0000, v229
	v_add_f32_e32 v100, 1.0, v100
	v_add_f32_e32 v101, 1.0, v101
	v_pk_mul_f32 v[114:115], v[106:107], v[114:115]
	v_lshlrev_b32_e32 v106, 16, v231
	v_and_b32_e32 v107, 0xffff0000, v231
	v_rcp_f32_e32 v100, v100
	v_add_f32_e32 v96, 1.0, v96
	v_rcp_f32_e32 v101, v101
	v_add_f32_e32 v97, 1.0, v97
	v_pk_mul_f32 v[110:111], v[110:111], v[106:107]
	v_cvt_pk_bf16_f32 v106, v108, v109
	v_cvt_pk_bf16_f32 v108, v104, v105
	v_mad_i64_i32 v[104:105], s[20:21], v208, s40, v[196:197]
	v_rcp_f32_e32 v96, v96
	v_rcp_f32_e32 v97, v97
	v_cvt_pk_bf16_f32 v107, v114, v115
	v_cvt_pk_bf16_f32 v109, v110, v111
	v_lshl_add_u64 v[104:105], v[104:105], 0, v[194:195]
	global_store_dwordx4 v[104:105], v[106:109], off offset:2048
	v_pk_add_f32 v[98:99], v[98:99], v[130:131]
	v_pk_add_f32 v[102:103], v[102:103], v[134:135]
	v_lshlrev_b32_e32 v106, 16, v232
	v_and_b32_e32 v107, 0xffff0000, v232
	v_pk_mul_f32 v[100:101], v[100:101], v[106:107]
	v_lshlrev_b32_e32 v106, 16, v234
	v_and_b32_e32 v107, 0xffff0000, v234
	v_mul_f32_e32 v98, 0xbfb8aa3b, v98
	v_mul_f32_e32 v102, 0xbfb8aa3b, v102
	v_pk_mul_f32 v[96:97], v[96:97], v[106:107]
	v_exp_f32_e32 v106, v98
	v_mul_f32_e32 v98, 0xbfb8aa3b, v103
	v_exp_f32_e32 v102, v102
	v_exp_f32_e32 v103, v98
	v_mul_f32_e32 v99, 0xbfb8aa3b, v99
	v_exp_f32_e32 v108, v99
	v_pk_add_f32 v[92:93], v[92:93], v[132:133]
	v_pk_add_f32 v[88:89], v[88:89], v[128:129]
	v_mul_f32_e32 v92, 0xbfb8aa3b, v92
	v_mul_f32_e32 v93, 0xbfb8aa3b, v93
	v_add_f32_e32 v102, 1.0, v102
	v_add_f32_e32 v103, 1.0, v103
	v_exp_f32_e32 v92, v92
	v_mul_f32_e32 v88, 0xbfb8aa3b, v88
	v_exp_f32_e32 v93, v93
	v_mul_f32_e32 v89, 0xbfb8aa3b, v89
	v_rcp_f32_e32 v98, v102
	v_add_f32_e32 v102, 1.0, v106
	v_rcp_f32_e32 v99, v103
	v_add_f32_e32 v103, 1.0, v108
	v_exp_f32_e32 v88, v88
	v_exp_f32_e32 v89, v89
	v_rcp_f32_e32 v102, v102
	v_rcp_f32_e32 v103, v103
	v_lshlrev_b32_e32 v106, 16, v233
	v_and_b32_e32 v107, 0xffff0000, v233
	v_add_f32_e32 v92, 1.0, v92
	v_add_f32_e32 v93, 1.0, v93
	v_pk_mul_f32 v[106:107], v[98:99], v[106:107]
	v_lshlrev_b32_e32 v98, 16, v235
	v_and_b32_e32 v99, 0xffff0000, v235
	v_rcp_f32_e32 v92, v92
	v_add_f32_e32 v88, 1.0, v88
	v_rcp_f32_e32 v93, v93
	v_add_f32_e32 v89, 1.0, v89
	v_pk_mul_f32 v[102:103], v[102:103], v[98:99]
	v_cvt_pk_bf16_f32 v98, v100, v101
	v_cvt_pk_bf16_f32 v100, v96, v97
	v_mad_i64_i32 v[96:97], s[20:21], v206, s40, v[196:197]
	v_rcp_f32_e32 v88, v88
	v_rcp_f32_e32 v89, v89
	v_cvt_pk_bf16_f32 v99, v106, v107
	v_cvt_pk_bf16_f32 v101, v102, v103
	v_lshl_add_u64 v[96:97], v[96:97], 0, v[194:195]
	global_store_dwordx4 v[96:97], v[98:101], off offset:2048
	v_pk_add_f32 v[90:91], v[90:91], v[130:131]
	v_pk_add_f32 v[94:95], v[94:95], v[134:135]
	v_lshlrev_b32_e32 v98, 16, v236
	v_and_b32_e32 v99, 0xffff0000, v236
	v_pk_mul_f32 v[92:93], v[92:93], v[98:99]
	v_lshlrev_b32_e32 v98, 16, v238
	v_and_b32_e32 v99, 0xffff0000, v238
	v_mul_f32_e32 v90, 0xbfb8aa3b, v90
	v_mul_f32_e32 v94, 0xbfb8aa3b, v94
	v_pk_mul_f32 v[88:89], v[88:89], v[98:99]
	v_exp_f32_e32 v98, v90
	v_mul_f32_e32 v90, 0xbfb8aa3b, v95
	v_exp_f32_e32 v94, v94
	v_exp_f32_e32 v95, v90
	v_mul_f32_e32 v91, 0xbfb8aa3b, v91
	v_exp_f32_e32 v100, v91
	v_pk_add_f32 v[84:85], v[84:85], v[132:133]
	v_pk_add_f32 v[80:81], v[80:81], v[128:129]
	v_mul_f32_e32 v84, 0xbfb8aa3b, v84
	v_mul_f32_e32 v85, 0xbfb8aa3b, v85
	v_add_f32_e32 v94, 1.0, v94
	v_add_f32_e32 v95, 1.0, v95
	v_exp_f32_e32 v84, v84
	v_mul_f32_e32 v80, 0xbfb8aa3b, v80
	v_exp_f32_e32 v85, v85
	v_mul_f32_e32 v81, 0xbfb8aa3b, v81
	v_rcp_f32_e32 v90, v94
	v_add_f32_e32 v94, 1.0, v98
	v_rcp_f32_e32 v91, v95
	v_add_f32_e32 v95, 1.0, v100
	v_exp_f32_e32 v80, v80
	v_exp_f32_e32 v81, v81
	v_rcp_f32_e32 v94, v94
	v_rcp_f32_e32 v95, v95
	v_lshlrev_b32_e32 v98, 16, v237
	v_and_b32_e32 v99, 0xffff0000, v237
	v_add_f32_e32 v84, 1.0, v84
	v_add_f32_e32 v85, 1.0, v85
	v_pk_mul_f32 v[98:99], v[90:91], v[98:99]
	v_lshlrev_b32_e32 v90, 16, v239
	v_and_b32_e32 v91, 0xffff0000, v239
	v_rcp_f32_e32 v84, v84
	v_add_f32_e32 v80, 1.0, v80
	v_rcp_f32_e32 v85, v85
	v_add_f32_e32 v81, 1.0, v81
	v_pk_mul_f32 v[94:95], v[94:95], v[90:91]
	v_cvt_pk_bf16_f32 v90, v92, v93
	v_cvt_pk_bf16_f32 v92, v88, v89
	v_mad_i64_i32 v[88:89], s[20:21], v204, s40, v[196:197]
	v_rcp_f32_e32 v80, v80
	v_rcp_f32_e32 v81, v81
	v_cvt_pk_bf16_f32 v91, v98, v99
	v_cvt_pk_bf16_f32 v93, v94, v95
	v_lshl_add_u64 v[88:89], v[88:89], 0, v[194:195]
	global_store_dwordx4 v[88:89], v[90:93], off offset:2048
	v_pk_add_f32 v[82:83], v[82:83], v[130:131]
; __device__ __forceinline__ float sigm(float x) { return __builtin_amdgcn_rcpf(1.0f + __builtin_amdgcn_exp2f(-1.4426950408889634f * x)); }
;     __device__ __forceinline__ void operator()(EPI_ARGS) const {
;     ...
;         for (int bj = 0; bj < 2; ++bj) { const f32x4 b0 = *(const f32x4*)(bias + col0 + bj * 128), b1 = *(const f32x4*)(bias + col0 + bj * 128 + 4);
;             u32x4 hw[2][4];
; #pragma unroll
;             for (int ai = 0; ai < 2; ++ai)
; #pragma unroll
;                 for (int m = 0; m < 4; ++m) hw[ai][m] = *(const u32x4*)(H + (size_t)(row0 + ai * 128 + m * 16) * 512 + col0 + bj * 128);
; #pragma unroll
;             for (int ai = 0; ai < 2; ++ai)
; #pragma unroll
;                 for (int m = 0; m < 4; ++m) { const size_t off = (size_t)(row0 + ai * 128 + m * 16) * 512 + col0 + bj * 128;
;                     f32x4 h0, h1; unpack8(hw[ai][m], h0, h1);
;                     f32x4 v0 = acc[ai][bj][m][0] + b0, v1 = acc[ai][bj][m][1] + b1;
; #pragma unroll
;                     for (int j = 0; j < 4; ++j) { v0[j] = h0[j] * sigm(v0[j]); v1[j] = h1[j] * sigm(v1[j]); }
;                     *(u32x4*)(O + (size_t)(row0 + ai * 128 + m * 16) * KAB + 1024 + col0 + bj * 128) = pack8(v0, v1); } }
	v_pk_add_f32 v[86:87], v[86:87], v[134:135]
	v_lshlrev_b32_e32 v90, 16, v172
	v_and_b32_e32 v91, 0xffff0000, v172
	v_pk_mul_f32 v[84:85], v[84:85], v[90:91]
	v_lshlrev_b32_e32 v90, 16, v174
	v_and_b32_e32 v91, 0xffff0000, v174
	v_mul_f32_e32 v82, 0xbfb8aa3b, v82
	v_mul_f32_e32 v86, 0xbfb8aa3b, v86
	v_pk_mul_f32 v[80:81], v[80:81], v[90:91]
	v_exp_f32_e32 v90, v82
	v_mul_f32_e32 v82, 0xbfb8aa3b, v87
	v_exp_f32_e32 v86, v86
	v_exp_f32_e32 v87, v82
	v_mul_f32_e32 v83, 0xbfb8aa3b, v83
	v_exp_f32_e32 v92, v83
	v_pk_add_f32 v[76:77], v[76:77], v[132:133]
	v_pk_add_f32 v[72:73], v[72:73], v[128:129]
	v_mul_f32_e32 v76, 0xbfb8aa3b, v76
	v_mul_f32_e32 v77, 0xbfb8aa3b, v77
	v_add_f32_e32 v86, 1.0, v86
	v_add_f32_e32 v87, 1.0, v87
	v_exp_f32_e32 v76, v76
	v_mul_f32_e32 v72, 0xbfb8aa3b, v72
	v_exp_f32_e32 v77, v77
	v_mul_f32_e32 v73, 0xbfb8aa3b, v73
	v_rcp_f32_e32 v82, v86
	v_add_f32_e32 v86, 1.0, v90
	v_rcp_f32_e32 v83, v87
	v_add_f32_e32 v87, 1.0, v92
	v_exp_f32_e32 v72, v72
	v_exp_f32_e32 v73, v73
	v_rcp_f32_e32 v86, v86
	v_rcp_f32_e32 v87, v87
	v_lshlrev_b32_e32 v90, 16, v173
	v_and_b32_e32 v91, 0xffff0000, v173
	v_add_f32_e32 v76, 1.0, v76
	v_add_f32_e32 v77, 1.0, v77
	v_pk_mul_f32 v[90:91], v[82:83], v[90:91]
	v_lshlrev_b32_e32 v82, 16, v175
	v_and_b32_e32 v83, 0xffff0000, v175
	v_rcp_f32_e32 v76, v76
	v_add_f32_e32 v72, 1.0, v72
	v_rcp_f32_e32 v77, v77
	v_add_f32_e32 v73, 1.0, v73
	v_pk_mul_f32 v[86:87], v[86:87], v[82:83]
	v_cvt_pk_bf16_f32 v82, v84, v85
	v_cvt_pk_bf16_f32 v84, v80, v81
	v_mad_i64_i32 v[80:81], s[20:21], v202, s40, v[196:197]
	v_rcp_f32_e32 v72, v72
	v_rcp_f32_e32 v73, v73
	v_cvt_pk_bf16_f32 v83, v90, v91
	v_cvt_pk_bf16_f32 v85, v86, v87
	v_lshl_add_u64 v[80:81], v[80:81], 0, v[194:195]
	global_store_dwordx4 v[80:81], v[82:85], off offset:2048
	v_pk_add_f32 v[74:75], v[74:75], v[130:131]
	v_pk_add_f32 v[78:79], v[78:79], v[134:135]
	v_lshlrev_b32_e32 v82, 16, v168
	v_and_b32_e32 v83, 0xffff0000, v168
	v_pk_mul_f32 v[76:77], v[76:77], v[82:83]
	v_lshlrev_b32_e32 v82, 16, v170
	v_and_b32_e32 v83, 0xffff0000, v170
	v_mul_f32_e32 v74, 0xbfb8aa3b, v74
	v_mul_f32_e32 v78, 0xbfb8aa3b, v78
	v_pk_mul_f32 v[72:73], v[72:73], v[82:83]
	v_exp_f32_e32 v82, v74
	v_mul_f32_e32 v74, 0xbfb8aa3b, v79
	v_exp_f32_e32 v78, v78
	v_exp_f32_e32 v79, v74
	v_mul_f32_e32 v75, 0xbfb8aa3b, v75
	v_exp_f32_e32 v84, v75
	v_pk_add_f32 v[68:69], v[68:69], v[132:133]
	v_pk_add_f32 v[64:65], v[64:65], v[128:129]
	v_mul_f32_e32 v68, 0xbfb8aa3b, v68
	v_mul_f32_e32 v69, 0xbfb8aa3b, v69
	v_exp_f32_e32 v68, v68
	v_mul_f32_e32 v64, 0xbfb8aa3b, v64
	v_exp_f32_e32 v69, v69
	v_mul_f32_e32 v65, 0xbfb8aa3b, v65
	v_add_f32_e32 v78, 1.0, v78
	v_add_f32_e32 v79, 1.0, v79
	v_exp_f32_e32 v64, v64
	v_exp_f32_e32 v65, v65
	v_rcp_f32_e32 v74, v78
	v_add_f32_e32 v78, 1.0, v82
	v_rcp_f32_e32 v75, v79
	v_add_f32_e32 v79, 1.0, v84
	v_rcp_f32_e32 v78, v78
	v_rcp_f32_e32 v79, v79
	v_add_f32_e32 v68, 1.0, v68
	v_add_f32_e32 v69, 1.0, v69
	v_lshlrev_b32_e32 v82, 16, v169
	v_and_b32_e32 v83, 0xffff0000, v169
	v_rcp_f32_e32 v68, v68
	v_add_f32_e32 v64, 1.0, v64
	v_rcp_f32_e32 v69, v69
	v_add_f32_e32 v65, 1.0, v65
	v_pk_mul_f32 v[74:75], v[74:75], v[82:83]
	v_lshlrev_b32_e32 v82, 16, v171
	v_and_b32_e32 v83, 0xffff0000, v171
	v_pk_add_f32 v[70:71], v[70:71], v[134:135]
	v_rcp_f32_e32 v64, v64
	v_rcp_f32_e32 v65, v65
	v_pk_mul_f32 v[82:83], v[78:79], v[82:83]
	v_cvt_pk_bf16_f32 v78, v72, v73
	v_mad_i64_i32 v[72:73], s[20:21], v200, s40, v[196:197]
	v_mul_f32_e32 v70, 0xbfb8aa3b, v70
	v_cvt_pk_bf16_f32 v76, v76, v77
	v_cvt_pk_bf16_f32 v77, v74, v75
	v_lshl_add_u64 v[74:75], v[72:73], 0, v[194:195]
	v_lshlrev_b32_e32 v72, 16, v164
	v_and_b32_e32 v73, 0xffff0000, v164
	v_exp_f32_e32 v70, v70
	v_pk_add_f32 v[66:67], v[66:67], v[130:131]
	v_pk_mul_f32 v[68:69], v[68:69], v[72:73]
	v_lshlrev_b32_e32 v72, 16, v166
	v_and_b32_e32 v73, 0xffff0000, v166
	v_pk_mul_f32 v[72:73], v[64:65], v[72:73]
	v_mul_f32_e32 v65, 0xbfb8aa3b, v66
	v_exp_f32_e32 v65, v65
	v_mul_f32_e32 v66, 0xbfb8aa3b, v71
	v_add_f32_e32 v64, 1.0, v70
	v_exp_f32_e32 v70, v66
	v_mul_f32_e32 v67, 0xbfb8aa3b, v67
	v_exp_f32_e32 v67, v67
	v_add_f32_e32 v65, 1.0, v65
	v_rcp_f32_e32 v66, v65
	v_add_f32_e32 v65, 1.0, v70
	v_rcp_f32_e32 v64, v64
	v_rcp_f32_e32 v65, v65
	v_add_f32_e32 v67, 1.0, v67
	v_rcp_f32_e32 v67, v67
	v_lshlrev_b32_e32 v70, 16, v165
	v_and_b32_e32 v71, 0xffff0000, v165
	v_cvt_pk_bf16_f32 v79, v82, v83
	v_pk_mul_f32 v[70:71], v[64:65], v[70:71]
	v_lshlrev_b32_e32 v64, 16, v167
	v_and_b32_e32 v65, 0xffff0000, v167
	global_store_dwordx4 v[74:75], v[76:79], off offset:2048
	global_store_dwordx4 v[214:215], v[224:227], off offset:2048
	s_nop 0
	v_pk_mul_f32 v[76:77], v[66:67], v[64:65]
	v_cvt_pk_bf16_f32 v64, v68, v69
	v_mad_i64_i32 v[68:69], s[20:21], v198, s40, v[196:197]
	v_cvt_pk_bf16_f32 v65, v70, v71
	v_cvt_pk_bf16_f32 v66, v72, v73
	v_cvt_pk_bf16_f32 v67, v76, v77
	v_lshl_add_u64 v[72:73], v[68:69], 0, v[194:195]
	global_store_dwordx4 v[72:73], v[64:67], off offset:2048
	global_load_dwordx4 v[68:71], v[192:193], off offset:512
	s_nop 0
	global_load_dwordx4 v[64:67], v[192:193], off offset:528
	v_lshlrev_b32_e32 v76, 16, v160
	v_and_b32_e32 v77, 0xffff0000, v160
	s_mov_b64 s[20:21], s[14:15]
	s_waitcnt vmcnt(0)
; __device__ __forceinline__ float sigm(float x) { return __builtin_amdgcn_rcpf(1.0f + __builtin_amdgcn_exp2f(-1.4426950408889634f * x)); }
;     __device__ __forceinline__ void operator()(EPI_ARGS) const {
;     ...
;             for (int ai = 0; ai < 2; ++ai)
; #pragma unroll
;                 for (int m = 0; m < 4; ++m) { const size_t off = (size_t)(row0 + ai * 128 + m * 16) * 512 + col0 + bj * 128;
;                     f32x4 h0, h1; unpack8(hw[ai][m], h0, h1);
;                     f32x4 v0 = acc[ai][bj][m][0] + b0, v1 = acc[ai][bj][m][1] + b1;
; #pragma unroll
;                     for (int j = 0; j < 4; ++j) { v0[j] = h0[j] * sigm(v0[j]); v1[j] = h1[j] * sigm(v1[j]); }
;                     *(u32x4*)(O + (size_t)(row0 + ai * 128 + m * 16) * KAB + 1024 + col0 + bj * 128) = pack8(v0, v1); } }
	v_pk_add_f32 v[60:61], v[60:61], v[68:69]
	s_nop 0
	v_mul_f32_e32 v60, 0xbfb8aa3b, v60
	v_pk_add_f32 v[56:57], v[56:57], v[64:65]
	v_mul_f32_e32 v61, 0xbfb8aa3b, v61
	v_exp_f32_e32 v60, v60
	v_mul_f32_e32 v56, 0xbfb8aa3b, v56
	v_exp_f32_e32 v61, v61
	v_mul_f32_e32 v57, 0xbfb8aa3b, v57
	v_exp_f32_e32 v56, v56
	v_exp_f32_e32 v57, v57
	v_add_f32_e32 v60, 1.0, v60
	v_add_f32_e32 v61, 1.0, v61
	v_rcp_f32_e32 v60, v60
	v_add_f32_e32 v56, 1.0, v56
	v_rcp_f32_e32 v61, v61
	v_add_f32_e32 v57, 1.0, v57
	v_pk_add_f32 v[62:63], v[62:63], v[70:71]
	v_rcp_f32_e32 v56, v56
	v_rcp_f32_e32 v57, v57
	v_mul_f32_e32 v62, 0xbfb8aa3b, v62
	v_exp_f32_e32 v62, v62
	v_pk_add_f32 v[58:59], v[58:59], v[66:67]
	v_pk_mul_f32 v[60:61], v[60:61], v[76:77]
	v_lshlrev_b32_e32 v76, 16, v162
	v_and_b32_e32 v77, 0xffff0000, v162
	v_pk_mul_f32 v[76:77], v[56:57], v[76:77]
	v_mul_f32_e32 v57, 0xbfb8aa3b, v58
	v_exp_f32_e32 v57, v57
	v_mul_f32_e32 v58, 0xbfb8aa3b, v63
	v_add_f32_e32 v56, 1.0, v62
	v_exp_f32_e32 v62, v58
	v_mul_f32_e32 v59, 0xbfb8aa3b, v59
	v_exp_f32_e32 v59, v59
	v_pk_add_f32 v[52:53], v[52:53], v[68:69]
	v_add_f32_e32 v57, 1.0, v57
	v_mul_f32_e32 v52, 0xbfb8aa3b, v52
	v_pk_add_f32 v[48:49], v[48:49], v[64:65]
	v_mul_f32_e32 v53, 0xbfb8aa3b, v53
	v_rcp_f32_e32 v58, v57
	v_add_f32_e32 v57, 1.0, v62
	v_exp_f32_e32 v52, v52
	v_mul_f32_e32 v48, 0xbfb8aa3b, v48
	v_exp_f32_e32 v53, v53
	v_mul_f32_e32 v49, 0xbfb8aa3b, v49
	v_rcp_f32_e32 v56, v56
	v_rcp_f32_e32 v57, v57
	v_add_f32_e32 v59, 1.0, v59
	v_exp_f32_e32 v48, v48
	v_exp_f32_e32 v49, v49
	v_rcp_f32_e32 v59, v59
	v_lshlrev_b32_e32 v62, 16, v161
	v_and_b32_e32 v63, 0xffff0000, v161
	v_add_f32_e32 v52, 1.0, v52
	v_add_f32_e32 v53, 1.0, v53
	v_pk_mul_f32 v[62:63], v[56:57], v[62:63]
	v_lshlrev_b32_e32 v56, 16, v163
	v_and_b32_e32 v57, 0xffff0000, v163
	v_rcp_f32_e32 v52, v52
	v_add_f32_e32 v48, 1.0, v48
	v_rcp_f32_e32 v53, v53
	v_add_f32_e32 v49, 1.0, v49
	v_pk_mul_f32 v[78:79], v[58:59], v[56:57]
	v_pk_add_f32 v[54:55], v[54:55], v[70:71]
	v_rcp_f32_e32 v48, v48
	v_rcp_f32_e32 v49, v49
	v_cvt_pk_bf16_f32 v56, v60, v61
	v_cvt_pk_bf16_f32 v57, v62, v63
	v_cvt_pk_bf16_f32 v58, v76, v77
	v_cvt_pk_bf16_f32 v59, v78, v79
	v_mul_f32_e32 v54, 0xbfb8aa3b, v54
	global_store_dwordx4 v[214:215], v[56:59], off offset:2304
	v_exp_f32_e32 v54, v54
	v_pk_add_f32 v[50:51], v[50:51], v[66:67]
	v_lshlrev_b32_e32 v56, 16, v156
	v_and_b32_e32 v57, 0xffff0000, v156
	v_pk_mul_f32 v[52:53], v[52:53], v[56:57]
	v_lshlrev_b32_e32 v56, 16, v158
	v_and_b32_e32 v57, 0xffff0000, v158
	v_pk_mul_f32 v[56:57], v[48:49], v[56:57]
	v_mul_f32_e32 v49, 0xbfb8aa3b, v50
	v_exp_f32_e32 v49, v49
	v_mul_f32_e32 v50, 0xbfb8aa3b, v55
	v_add_f32_e32 v48, 1.0, v54
	v_exp_f32_e32 v54, v50
	v_mul_f32_e32 v51, 0xbfb8aa3b, v51
	v_exp_f32_e32 v51, v51
	v_pk_add_f32 v[44:45], v[44:45], v[68:69]
	v_add_f32_e32 v49, 1.0, v49
	v_mul_f32_e32 v44, 0xbfb8aa3b, v44
	v_pk_add_f32 v[40:41], v[40:41], v[64:65]
	v_mul_f32_e32 v45, 0xbfb8aa3b, v45
	v_rcp_f32_e32 v50, v49
	v_add_f32_e32 v49, 1.0, v54
	v_exp_f32_e32 v44, v44
	v_mul_f32_e32 v40, 0xbfb8aa3b, v40
	v_exp_f32_e32 v45, v45
	v_mul_f32_e32 v41, 0xbfb8aa3b, v41
	v_rcp_f32_e32 v48, v48
	v_rcp_f32_e32 v49, v49
	v_add_f32_e32 v51, 1.0, v51
	v_exp_f32_e32 v40, v40
	v_exp_f32_e32 v41, v41
	v_rcp_f32_e32 v51, v51
	v_lshlrev_b32_e32 v54, 16, v157
	v_and_b32_e32 v55, 0xffff0000, v157
	v_add_f32_e32 v44, 1.0, v44
	v_add_f32_e32 v45, 1.0, v45
	v_pk_mul_f32 v[54:55], v[48:49], v[54:55]
	v_lshlrev_b32_e32 v48, 16, v159
	v_and_b32_e32 v49, 0xffff0000, v159
	v_rcp_f32_e32 v44, v44
	v_add_f32_e32 v40, 1.0, v40
	v_rcp_f32_e32 v45, v45
	v_add_f32_e32 v41, 1.0, v41
	v_pk_mul_f32 v[58:59], v[50:51], v[48:49]
	v_pk_add_f32 v[46:47], v[46:47], v[70:71]
	v_rcp_f32_e32 v40, v40
	v_rcp_f32_e32 v41, v41
	v_cvt_pk_bf16_f32 v48, v52, v53
	v_cvt_pk_bf16_f32 v49, v54, v55
	v_cvt_pk_bf16_f32 v50, v56, v57
	v_cvt_pk_bf16_f32 v51, v58, v59
	v_mul_f32_e32 v46, 0xbfb8aa3b, v46
	global_store_dwordx4 v[112:113], v[48:51], off offset:2304
	v_exp_f32_e32 v46, v46
	v_pk_add_f32 v[42:43], v[42:43], v[66:67]
	v_lshlrev_b32_e32 v48, 16, v148
	v_and_b32_e32 v49, 0xffff0000, v148
	v_pk_mul_f32 v[44:45], v[44:45], v[48:49]
	v_lshlrev_b32_e32 v48, 16, v150
	v_and_b32_e32 v49, 0xffff0000, v150
	v_pk_mul_f32 v[48:49], v[40:41], v[48:49]
	v_mul_f32_e32 v41, 0xbfb8aa3b, v42
	v_exp_f32_e32 v41, v41
	v_mul_f32_e32 v42, 0xbfb8aa3b, v47
	v_add_f32_e32 v40, 1.0, v46
	v_exp_f32_e32 v46, v42
	v_mul_f32_e32 v43, 0xbfb8aa3b, v43
	v_exp_f32_e32 v43, v43
	v_pk_add_f32 v[36:37], v[36:37], v[68:69]
	v_add_f32_e32 v41, 1.0, v41
	v_mul_f32_e32 v36, 0xbfb8aa3b, v36
	v_pk_add_f32 v[32:33], v[32:33], v[64:65]
	v_mul_f32_e32 v37, 0xbfb8aa3b, v37
	v_rcp_f32_e32 v42, v41
	v_add_f32_e32 v41, 1.0, v46
	v_exp_f32_e32 v36, v36
	v_mul_f32_e32 v32, 0xbfb8aa3b, v32
	v_exp_f32_e32 v37, v37
	v_mul_f32_e32 v33, 0xbfb8aa3b, v33
	v_rcp_f32_e32 v40, v40
	v_rcp_f32_e32 v41, v41
	v_add_f32_e32 v43, 1.0, v43
	v_exp_f32_e32 v32, v32
	v_exp_f32_e32 v33, v33
	v_rcp_f32_e32 v43, v43
	v_lshlrev_b32_e32 v46, 16, v149
	v_and_b32_e32 v47, 0xffff0000, v149
	v_add_f32_e32 v36, 1.0, v36
	v_add_f32_e32 v37, 1.0, v37
	v_pk_mul_f32 v[46:47], v[40:41], v[46:47]
	v_lshlrev_b32_e32 v40, 16, v151
	v_and_b32_e32 v41, 0xffff0000, v151
	v_rcp_f32_e32 v36, v36
	v_add_f32_e32 v32, 1.0, v32
	v_rcp_f32_e32 v37, v37
	v_add_f32_e32 v33, 1.0, v33
	v_pk_mul_f32 v[50:51], v[42:43], v[40:41]
	v_pk_add_f32 v[38:39], v[38:39], v[70:71]
	v_rcp_f32_e32 v32, v32
	v_rcp_f32_e32 v33, v33
	v_cvt_pk_bf16_f32 v40, v44, v45
	v_cvt_pk_bf16_f32 v41, v46, v47
	v_cvt_pk_bf16_f32 v42, v48, v49
	v_cvt_pk_bf16_f32 v43, v50, v51
	v_mul_f32_e32 v38, 0xbfb8aa3b, v38
; __device__ __forceinline__ float sigm(float x) { return __builtin_amdgcn_rcpf(1.0f + __builtin_amdgcn_exp2f(-1.4426950408889634f * x)); }
;     __device__ __forceinline__ void operator()(EPI_ARGS) const {
;     ...
;             for (int ai = 0; ai < 2; ++ai)
; #pragma unroll
;                 for (int m = 0; m < 4; ++m) { const size_t off = (size_t)(row0 + ai * 128 + m * 16) * 512 + col0 + bj * 128;
;                     f32x4 h0, h1; unpack8(hw[ai][m], h0, h1);
;                     f32x4 v0 = acc[ai][bj][m][0] + b0, v1 = acc[ai][bj][m][1] + b1;
; #pragma unroll
;                     for (int j = 0; j < 4; ++j) { v0[j] = h0[j] * sigm(v0[j]); v1[j] = h1[j] * sigm(v1[j]); }
;                     *(u32x4*)(O + (size_t)(row0 + ai * 128 + m * 16) * KAB + 1024 + col0 + bj * 128) = pack8(v0, v1); } }
	global_store_dwordx4 v[104:105], v[40:43], off offset:2304
	v_exp_f32_e32 v38, v38
	v_pk_add_f32 v[34:35], v[34:35], v[66:67]
	v_lshlrev_b32_e32 v40, 16, v144
	v_and_b32_e32 v41, 0xffff0000, v144
	v_pk_mul_f32 v[36:37], v[36:37], v[40:41]
	v_lshlrev_b32_e32 v40, 16, v146
	v_and_b32_e32 v41, 0xffff0000, v146
	v_pk_mul_f32 v[40:41], v[32:33], v[40:41]
	v_mul_f32_e32 v33, 0xbfb8aa3b, v34
	v_exp_f32_e32 v33, v33
	v_mul_f32_e32 v34, 0xbfb8aa3b, v39
	v_add_f32_e32 v32, 1.0, v38
	v_exp_f32_e32 v38, v34
	v_mul_f32_e32 v35, 0xbfb8aa3b, v35
	v_exp_f32_e32 v35, v35
	v_pk_add_f32 v[28:29], v[28:29], v[68:69]
	v_add_f32_e32 v33, 1.0, v33
	v_mul_f32_e32 v28, 0xbfb8aa3b, v28
	v_pk_add_f32 v[24:25], v[24:25], v[64:65]
	v_mul_f32_e32 v29, 0xbfb8aa3b, v29
	v_rcp_f32_e32 v34, v33
	v_add_f32_e32 v33, 1.0, v38
	v_exp_f32_e32 v28, v28
	v_mul_f32_e32 v24, 0xbfb8aa3b, v24
	v_exp_f32_e32 v29, v29
	v_mul_f32_e32 v25, 0xbfb8aa3b, v25
	v_rcp_f32_e32 v32, v32
	v_rcp_f32_e32 v33, v33
	v_add_f32_e32 v35, 1.0, v35
	v_exp_f32_e32 v24, v24
	v_exp_f32_e32 v25, v25
	v_rcp_f32_e32 v35, v35
	v_lshlrev_b32_e32 v38, 16, v145
	v_and_b32_e32 v39, 0xffff0000, v145
	v_add_f32_e32 v28, 1.0, v28
	v_add_f32_e32 v29, 1.0, v29
	v_pk_mul_f32 v[38:39], v[32:33], v[38:39]
	v_lshlrev_b32_e32 v32, 16, v147
	v_and_b32_e32 v33, 0xffff0000, v147
	v_rcp_f32_e32 v28, v28
	v_add_f32_e32 v24, 1.0, v24
	v_rcp_f32_e32 v29, v29
	v_add_f32_e32 v25, 1.0, v25
	v_pk_mul_f32 v[42:43], v[34:35], v[32:33]
	v_pk_add_f32 v[30:31], v[30:31], v[70:71]
	v_rcp_f32_e32 v24, v24
	v_rcp_f32_e32 v25, v25
	v_cvt_pk_bf16_f32 v32, v36, v37
	v_cvt_pk_bf16_f32 v33, v38, v39
	v_cvt_pk_bf16_f32 v34, v40, v41
	v_cvt_pk_bf16_f32 v35, v42, v43
	v_mul_f32_e32 v30, 0xbfb8aa3b, v30
	global_store_dwordx4 v[96:97], v[32:35], off offset:2304
	v_exp_f32_e32 v30, v30
	v_pk_add_f32 v[26:27], v[26:27], v[66:67]
	v_lshlrev_b32_e32 v32, 16, v140
	v_and_b32_e32 v33, 0xffff0000, v140
	v_pk_mul_f32 v[28:29], v[28:29], v[32:33]
	v_lshlrev_b32_e32 v32, 16, v142
	v_and_b32_e32 v33, 0xffff0000, v142
	v_pk_mul_f32 v[32:33], v[24:25], v[32:33]
	v_mul_f32_e32 v25, 0xbfb8aa3b, v26
	v_exp_f32_e32 v25, v25
	v_mul_f32_e32 v26, 0xbfb8aa3b, v31
	v_add_f32_e32 v24, 1.0, v30
	v_exp_f32_e32 v30, v26
	v_mul_f32_e32 v27, 0xbfb8aa3b, v27
	v_exp_f32_e32 v27, v27
	v_pk_add_f32 v[20:21], v[20:21], v[68:69]
	v_add_f32_e32 v25, 1.0, v25
	v_mul_f32_e32 v20, 0xbfb8aa3b, v20
	v_pk_add_f32 v[16:17], v[16:17], v[64:65]
	v_mul_f32_e32 v21, 0xbfb8aa3b, v21
	v_rcp_f32_e32 v26, v25
	v_add_f32_e32 v25, 1.0, v30
	v_exp_f32_e32 v20, v20
	v_mul_f32_e32 v16, 0xbfb8aa3b, v16
	v_exp_f32_e32 v21, v21
	v_mul_f32_e32 v17, 0xbfb8aa3b, v17
	v_rcp_f32_e32 v24, v24
	v_rcp_f32_e32 v25, v25
	v_add_f32_e32 v27, 1.0, v27
	v_exp_f32_e32 v16, v16
	v_exp_f32_e32 v17, v17
	v_rcp_f32_e32 v27, v27
	v_lshlrev_b32_e32 v30, 16, v141
	v_and_b32_e32 v31, 0xffff0000, v141
	v_add_f32_e32 v20, 1.0, v20
	v_add_f32_e32 v21, 1.0, v21
	v_pk_mul_f32 v[30:31], v[24:25], v[30:31]
	v_lshlrev_b32_e32 v24, 16, v143
	v_and_b32_e32 v25, 0xffff0000, v143
	v_rcp_f32_e32 v20, v20
	v_add_f32_e32 v16, 1.0, v16
	v_rcp_f32_e32 v21, v21
	v_add_f32_e32 v17, 1.0, v17
	v_pk_mul_f32 v[34:35], v[26:27], v[24:25]
	v_pk_add_f32 v[22:23], v[22:23], v[70:71]
	v_rcp_f32_e32 v16, v16
	v_rcp_f32_e32 v17, v17
	v_cvt_pk_bf16_f32 v24, v28, v29
	v_cvt_pk_bf16_f32 v25, v30, v31
	v_cvt_pk_bf16_f32 v26, v32, v33
	v_cvt_pk_bf16_f32 v27, v34, v35
	v_mul_f32_e32 v22, 0xbfb8aa3b, v22
	global_store_dwordx4 v[88:89], v[24:27], off offset:2304
	v_exp_f32_e32 v22, v22
	v_pk_add_f32 v[18:19], v[18:19], v[66:67]
	v_lshlrev_b32_e32 v24, 16, v136
	v_and_b32_e32 v25, 0xffff0000, v136
	v_pk_mul_f32 v[20:21], v[20:21], v[24:25]
	v_lshlrev_b32_e32 v24, 16, v138
	v_and_b32_e32 v25, 0xffff0000, v138
	v_pk_mul_f32 v[24:25], v[16:17], v[24:25]
	v_mul_f32_e32 v17, 0xbfb8aa3b, v18
	v_exp_f32_e32 v17, v17
	v_mul_f32_e32 v18, 0xbfb8aa3b, v23
	v_add_f32_e32 v16, 1.0, v22
	v_exp_f32_e32 v22, v18
	v_mul_f32_e32 v19, 0xbfb8aa3b, v19
	v_exp_f32_e32 v19, v19
; __device__ __forceinline__ float sigm(float x) { return __builtin_amdgcn_rcpf(1.0f + __builtin_amdgcn_exp2f(-1.4426950408889634f * x)); }
; #define PG8_WAIT_V(n) asm volatile("s_waitcnt vmcnt(" #n ")" ::: "memory")
; #define PG8_BAR __builtin_amdgcn_s_barrier()
; template <class Epi>
; __device__ __forceinline__ void gemm_phase(ldsp lds, const Gemm g, const StaticOrder& S, const Epi& E) {
;     ...
;         if (!has_next) break;
; #pragma unroll
;         for (int a = 0; a < 2; ++a)
; #pragma unroll
;             for (int b = 0; b < 2; ++b)
; #pragma unroll
;                 for (int m = 0; m < 4; ++m)
; #pragma unroll
;                     for (int n = 0; n < 2; ++n) acc[a][b][m][n] = (f32x4){0.f, 0.f, 0.f, 0.f};
;         cur = nxt; cA = nA; cB = nB; ++ui;
;     }
;     PG8_WAIT_V(0);
;     if (wr == 0) PG8_BAR;
;     PG8_BAR;
;     __device__ __forceinline__ void operator()(EPI_ARGS) const {
;     ...
;             for (int ai = 0; ai < 2; ++ai)
; #pragma unroll
;                 for (int m = 0; m < 4; ++m) { const size_t off = (size_t)(row0 + ai * 128 + m * 16) * 512 + col0 + bj * 128;
;                     f32x4 h0, h1; unpack8(hw[ai][m], h0, h1);
;                     f32x4 v0 = acc[ai][bj][m][0] + b0, v1 = acc[ai][bj][m][1] + b1;
; #pragma unroll
;                     for (int j = 0; j < 4; ++j) { v0[j] = h0[j] * sigm(v0[j]); v1[j] = h1[j] * sigm(v1[j]); }
;                     *(u32x4*)(O + (size_t)(row0 + ai * 128 + m * 16) * KAB + 1024 + col0 + bj * 128) = pack8(v0, v1); } }
	v_pk_add_f32 v[12:13], v[12:13], v[68:69]
	v_add_f32_e32 v17, 1.0, v17
	v_mul_f32_e32 v12, 0xbfb8aa3b, v12
	v_pk_add_f32 v[8:9], v[8:9], v[64:65]
	v_mul_f32_e32 v13, 0xbfb8aa3b, v13
	v_rcp_f32_e32 v18, v17
	v_add_f32_e32 v17, 1.0, v22
	v_exp_f32_e32 v12, v12
	v_mul_f32_e32 v8, 0xbfb8aa3b, v8
	v_exp_f32_e32 v13, v13
	v_mul_f32_e32 v9, 0xbfb8aa3b, v9
	v_rcp_f32_e32 v16, v16
	v_rcp_f32_e32 v17, v17
	v_add_f32_e32 v19, 1.0, v19
	v_exp_f32_e32 v8, v8
	v_exp_f32_e32 v9, v9
	v_rcp_f32_e32 v19, v19
	v_lshlrev_b32_e32 v22, 16, v137
	v_and_b32_e32 v23, 0xffff0000, v137
	v_add_f32_e32 v12, 1.0, v12
	v_add_f32_e32 v13, 1.0, v13
	v_pk_mul_f32 v[22:23], v[16:17], v[22:23]
	v_lshlrev_b32_e32 v16, 16, v139
	v_and_b32_e32 v17, 0xffff0000, v139
	v_rcp_f32_e32 v12, v12
	v_add_f32_e32 v8, 1.0, v8
	v_rcp_f32_e32 v13, v13
	v_add_f32_e32 v9, 1.0, v9
	v_pk_mul_f32 v[26:27], v[18:19], v[16:17]
	v_pk_add_f32 v[14:15], v[14:15], v[70:71]
	v_rcp_f32_e32 v8, v8
	v_rcp_f32_e32 v9, v9
	v_cvt_pk_bf16_f32 v16, v20, v21
	v_cvt_pk_bf16_f32 v17, v22, v23
	v_cvt_pk_bf16_f32 v18, v24, v25
	v_cvt_pk_bf16_f32 v19, v26, v27
	v_mul_f32_e32 v14, 0xbfb8aa3b, v14
	global_store_dwordx4 v[80:81], v[16:19], off offset:2304
	v_exp_f32_e32 v14, v14
	v_pk_add_f32 v[10:11], v[10:11], v[66:67]
	v_lshlrev_b32_e32 v16, 16, v124
	v_and_b32_e32 v17, 0xffff0000, v124
	v_pk_mul_f32 v[12:13], v[12:13], v[16:17]
	v_lshlrev_b32_e32 v16, 16, v126
	v_and_b32_e32 v17, 0xffff0000, v126
	v_pk_mul_f32 v[16:17], v[8:9], v[16:17]
	v_mul_f32_e32 v9, 0xbfb8aa3b, v10
	v_exp_f32_e32 v9, v9
	v_mul_f32_e32 v10, 0xbfb8aa3b, v15
	v_add_f32_e32 v8, 1.0, v14
	v_exp_f32_e32 v14, v10
	v_mul_f32_e32 v11, 0xbfb8aa3b, v11
	v_exp_f32_e32 v11, v11
	v_pk_add_f32 v[4:5], v[4:5], v[68:69]
	v_add_f32_e32 v9, 1.0, v9
	v_mul_f32_e32 v4, 0xbfb8aa3b, v4
	v_pk_add_f32 v[0:1], v[0:1], v[64:65]
	v_mul_f32_e32 v5, 0xbfb8aa3b, v5
	v_rcp_f32_e32 v10, v9
	v_add_f32_e32 v9, 1.0, v14
	v_exp_f32_e32 v4, v4
	v_mul_f32_e32 v0, 0xbfb8aa3b, v0
	v_exp_f32_e32 v5, v5
	v_mul_f32_e32 v1, 0xbfb8aa3b, v1
	v_rcp_f32_e32 v8, v8
	v_rcp_f32_e32 v9, v9
	v_add_f32_e32 v11, 1.0, v11
	v_exp_f32_e32 v0, v0
	v_exp_f32_e32 v1, v1
	v_rcp_f32_e32 v11, v11
	v_lshlrev_b32_e32 v14, 16, v125
	v_and_b32_e32 v15, 0xffff0000, v125
	v_add_f32_e32 v4, 1.0, v4
	v_add_f32_e32 v5, 1.0, v5
	v_pk_mul_f32 v[14:15], v[8:9], v[14:15]
	v_lshlrev_b32_e32 v8, 16, v127
	v_and_b32_e32 v9, 0xffff0000, v127
	v_rcp_f32_e32 v4, v4
	v_add_f32_e32 v0, 1.0, v0
	v_rcp_f32_e32 v5, v5
	v_add_f32_e32 v1, 1.0, v1
	v_pk_mul_f32 v[18:19], v[10:11], v[8:9]
	v_pk_add_f32 v[6:7], v[6:7], v[70:71]
	v_rcp_f32_e32 v0, v0
	v_rcp_f32_e32 v1, v1
	v_cvt_pk_bf16_f32 v8, v12, v13
	v_cvt_pk_bf16_f32 v9, v14, v15
	v_cvt_pk_bf16_f32 v10, v16, v17
	v_cvt_pk_bf16_f32 v11, v18, v19
	v_mul_f32_e32 v6, 0xbfb8aa3b, v6
	global_store_dwordx4 v[74:75], v[8:11], off offset:2304
	v_exp_f32_e32 v6, v6
	v_pk_add_f32 v[2:3], v[2:3], v[66:67]
	v_lshlrev_b32_e32 v8, 16, v120
	v_and_b32_e32 v9, 0xffff0000, v120
	v_pk_mul_f32 v[4:5], v[4:5], v[8:9]
	v_lshlrev_b32_e32 v8, 16, v122
	v_and_b32_e32 v9, 0xffff0000, v122
	v_pk_mul_f32 v[8:9], v[0:1], v[8:9]
	v_mul_f32_e32 v1, 0xbfb8aa3b, v2
	v_exp_f32_e32 v1, v1
	v_mul_f32_e32 v2, 0xbfb8aa3b, v7
	v_add_f32_e32 v0, 1.0, v6
	v_exp_f32_e32 v6, v2
	v_mul_f32_e32 v3, 0xbfb8aa3b, v3
	v_exp_f32_e32 v3, v3
	v_add_f32_e32 v1, 1.0, v1
	v_rcp_f32_e32 v2, v1
	v_add_f32_e32 v1, 1.0, v6
	v_rcp_f32_e32 v0, v0
	v_rcp_f32_e32 v1, v1
	v_add_f32_e32 v3, 1.0, v3
	v_rcp_f32_e32 v3, v3
	v_lshlrev_b32_e32 v6, 16, v121
	v_and_b32_e32 v7, 0xffff0000, v121
	v_pk_mul_f32 v[6:7], v[0:1], v[6:7]
	v_lshlrev_b32_e32 v0, 16, v123
	v_and_b32_e32 v1, 0xffff0000, v123
	v_pk_mul_f32 v[10:11], v[2:3], v[0:1]
	v_cvt_pk_bf16_f32 v0, v4, v5
	v_cvt_pk_bf16_f32 v1, v6, v7
	v_cvt_pk_bf16_f32 v2, v8, v9
	v_cvt_pk_bf16_f32 v3, v10, v11
	global_store_dwordx4 v[72:73], v[0:3], off offset:2304
	s_cbranch_vccz .LBB0_567
	s_waitcnt vmcnt(0)
	s_cmpk_gt_u32 s26, 0xff
	s_cbranch_scc1 .LBB0_578
	s_barrier

; #define PG8_STAGE(bufoff, gbase, voff) do { _Pragma("unroll") for (int _i = 0; _i < 2; ++_i) \
;         __builtin_amdgcn_global_load_lds((const unsigned*)((const char*)(gbase) + (voff)[_i]), (LAS unsigned*)(lds + (bufoff) + ldsw + _i * 8192), 16, 0, 0); } while (0)
; #define PG8_LDA(dst, b, h) do { _Pragma("unroll") for (int m = 0; m < 4; ++m) _Pragma("unroll") for (int k = 0; k < 2; ++k) dst[m][k] = *(const LAS bf16x8*)(lds + PG8_SA(b, h) + aoff + m * 2048 + k * 1024); } while (0)
; #define PG8_LDB(dst, b, h) do { _Pragma("unroll") for (int n = 0; n < 2; ++n) _Pragma("unroll") for (int k = 0; k < 2; ++k) dst[n][k] = *(const LAS bf16x8*)(lds + PG8_SB(b, h) + boff + n * 2048 + k * 1024); } while (0)
; #define PG8_MMA(ai, bj, At, Bt) do { __builtin_amdgcn_s_setprio(1); _Pragma("unroll") for (int m = 0; m < 4; ++m) _Pragma("unroll") for (int n = 0; n < 2; ++n) _Pragma("unroll") for (int k = 0; k < 2; ++k) \
;         acc[ai][bj][m][n] = __builtin_amdgcn_mfma_f32_16x16x32_bf16(Bt[n][k], At[m][k], acc[ai][bj][m][n], 0, 0, 0); __builtin_amdgcn_s_setprio(0); } while (0)
; #define PG8_WAIT_V(n) asm volatile("s_waitcnt vmcnt(" #n ")" ::: "memory")
; template <class Epi>
; __device__ __forceinline__ void gemm_phase(ldsp lds, const Gemm g, const StaticOrder& S, const Epi& E) {
;     ...
;         for (int t = 0; t < nt; t += 2) {
;             const bool last = (t == nt - 2);
;             const char* a1 = cA + (size_t)(t + 1) * kstep;
;             const char* a2 = last ? nA : cA + (size_t)(t + 2) * kstep; const char* b2 = last ? nB : cB + (size_t)(t + 2) * kstep;
;             const char* a3 = a2 + kstep; const char* b3 = b2 + kstep;
;             if constexpr (Epi::NPRE > 0) { if (last) E.pre(pre, cur, wr, fr); }
;             if constexpr (Epi::MID_T > 0) { if (t == Epi::MID_T) E.mid(acc, cur, wr, wc, fr, fq); }
;             PG8_LDB(B0, 0, 0); PG8_SCHED; PG8_LDA(At, 0, 0); PG8_STAGE(PG8_SA(1, 1), a1 + hstep, voffA);
;             PG8_WAIT_L(8); PG8_WAIT_V(10); PG8_BAR; PG8_WAIT_L(0); PG8_MMA(0, 0, At, B0); PG8_BAR; PG8_SCHED;
;             PG8_LDB(B1, 0, 1); PG8_STAGE(PG8_SB(0, 0), b2, voffB);
;             PG8_WAIT_V(10); PG8_BAR; PG8_WAIT_L(0); PG8_MMA(0, 1, At, B1); PG8_BAR;
;             PG8_LDA(At, 0, 1); PG8_STAGE(PG8_SA(0, 0), a2, voffA);
;             PG8_WAIT_V(10); PG8_BAR; PG8_WAIT_L(0); PG8_MMA(1, 0, At, B0); PG8_BAR; PG8_SCHED;
.LBB0_654:
	v_add_u32_e32 v140, s45, v222
	s_add_u32 s26, s22, s24
	ds_read_b128 v[128:131], v140
	ds_read_b128 v[132:135], v140 offset:1024
	ds_read_b128 v[136:139], v140 offset:2048
	ds_read_b128 v[140:143], v140 offset:3072
	s_addc_u32 s27, s23, s25
	s_add_u32 s26, s26, 0x100
	s_addc_u32 s27, s27, 0
	s_add_u32 s54, s51, s24
	s_addc_u32 s55, s52, s25
	s_cmpk_eq_i32 s24, 0xb00
	s_cselect_b32 s29, s1, s27
	s_cselect_b32 s28, s0, s26
	s_cselect_b32 s27, s5, s55
	s_cselect_b32 s26, s4, s54
	v_lshl_add_u64 v[176:177], v[212:213], 0, s[24:25]
	s_add_i32 m0, s36, 0xc000
	s_waitcnt vmcnt(0)
	ds_read_b128 v[144:147], v224
	ds_read_b128 v[148:151], v224 offset:1024
	ds_read_b128 v[152:155], v224 offset:2048
	ds_read_b128 v[156:159], v224 offset:3072
	ds_read_b128 v[160:163], v224 offset:4096
	ds_read_b128 v[164:167], v224 offset:5120
	ds_read_b128 v[168:171], v224 offset:6144
	ds_read_b128 v[172:175], v224 offset:7168
	global_load_lds_dwordx4 v[176:177], off
	v_lshl_add_u64 v[176:177], v[214:215], 0, s[24:25]
	s_add_i32 m0, s36, 0xe000
	s_nop 0
	global_load_lds_dwordx4 v[176:177], off
	s_waitcnt lgkmcnt(8)
	s_waitcnt vmcnt(10)
	s_barrier
	s_waitcnt lgkmcnt(0)
	s_setprio 1
	s_waitcnt lgkmcnt(0)
	v_mfma_f32_16x16x32_bf16 v[124:127], v[128:131], v[144:147], v[124:127]
	v_mfma_f32_16x16x32_bf16 v[120:123], v[136:139], v[144:147], v[120:123]
	v_mfma_f32_16x16x32_bf16 v[116:119], v[128:131], v[152:155], v[116:119]
	v_mfma_f32_16x16x32_bf16 v[104:107], v[136:139], v[152:155], v[104:107]
	v_mfma_f32_16x16x32_bf16 v[96:99], v[128:131], v[160:163], v[96:99]
	v_mfma_f32_16x16x32_bf16 v[88:91], v[136:139], v[160:163], v[88:91]
	v_mfma_f32_16x16x32_bf16 v[80:83], v[128:131], v[168:171], v[80:83]
	v_mfma_f32_16x16x32_bf16 v[72:75], v[136:139], v[168:171], v[72:75]
	v_mfma_f32_16x16x32_bf16 v[124:127], v[132:135], v[148:151], v[124:127]
	v_mfma_f32_16x16x32_bf16 v[120:123], v[140:143], v[148:151], v[120:123]
	v_mfma_f32_16x16x32_bf16 v[116:119], v[132:135], v[156:159], v[116:119]
	v_mfma_f32_16x16x32_bf16 v[104:107], v[140:143], v[156:159], v[104:107]
	v_mfma_f32_16x16x32_bf16 v[96:99], v[132:135], v[164:167], v[96:99]
	v_mfma_f32_16x16x32_bf16 v[88:91], v[140:143], v[164:167], v[88:91]
	v_mfma_f32_16x16x32_bf16 v[80:83], v[132:135], v[172:175], v[80:83]
	s_barrier
	v_mfma_f32_16x16x32_bf16 v[72:75], v[140:143], v[172:175], v[72:75]
	s_setprio 0
	s_add_i32 s54, s45, s35
	v_add_u32_e32 v188, s46, v222
	s_add_u32 s98, s26, 0x80
	s_addc_u32 s99, s27, 0
	s_mov_b32 m0, s54
	ds_read_b128 v[176:179], v188
	ds_read_b128 v[180:183], v188 offset:1024
	ds_read_b128 v[184:187], v188 offset:2048
	ds_read_b128 v[188:191], v188 offset:3072
	global_load_lds_dwordx4 v194, s[26:27]
	s_add_i32 m0, s54, 0x2000
	s_nop 0
	global_load_lds_dwordx4 v198, s[26:27]
	s_waitcnt vmcnt(10)
	s_barrier
	s_waitcnt lgkmcnt(0)
	s_setprio 1
	s_waitcnt lgkmcnt(0)
	v_mfma_f32_16x16x32_bf16 v[112:115], v[176:179], v[144:147], v[112:115]
	v_mfma_f32_16x16x32_bf16 v[108:111], v[184:187], v[144:147], v[108:111]
	v_mfma_f32_16x16x32_bf16 v[100:103], v[176:179], v[152:155], v[100:103]
	v_mfma_f32_16x16x32_bf16 v[92:95], v[184:187], v[152:155], v[92:95]
	v_mfma_f32_16x16x32_bf16 v[84:87], v[176:179], v[160:163], v[84:87]
	v_mfma_f32_16x16x32_bf16 v[76:79], v[184:187], v[160:163], v[76:79]
	v_mfma_f32_16x16x32_bf16 v[68:71], v[176:179], v[168:171], v[68:71]
	v_mfma_f32_16x16x32_bf16 v[64:67], v[184:187], v[168:171], v[64:67]
	v_mfma_f32_16x16x32_bf16 v[112:115], v[180:183], v[148:151], v[112:115]
	v_mfma_f32_16x16x32_bf16 v[108:111], v[188:191], v[148:151], v[108:111]
	v_mfma_f32_16x16x32_bf16 v[100:103], v[180:183], v[156:159], v[100:103]
	v_mfma_f32_16x16x32_bf16 v[92:95], v[188:191], v[156:159], v[92:95]
	v_mfma_f32_16x16x32_bf16 v[84:87], v[180:183], v[164:167], v[84:87]
	v_mfma_f32_16x16x32_bf16 v[76:79], v[188:191], v[164:167], v[76:79]
	v_mfma_f32_16x16x32_bf16 v[68:71], v[180:183], v[172:175], v[68:71]
	s_barrier
	v_mfma_f32_16x16x32_bf16 v[64:67], v[188:191], v[172:175], v[64:67]
	s_setprio 0
	s_mov_b32 m0, s36
	s_add_u32 s100, s28, 0x80
	s_addc_u32 s101, s29, 0
	ds_read_b128 v[144:147], v224 offset:16384
	ds_read_b128 v[148:151], v224 offset:17408
	ds_read_b128 v[152:155], v224 offset:18432
	ds_read_b128 v[156:159], v224 offset:19456
	ds_read_b128 v[160:163], v224 offset:20480
	ds_read_b128 v[164:167], v224 offset:21504
	ds_read_b128 v[168:171], v224 offset:22528
	ds_read_b128 v[172:175], v224 offset:23552
	global_load_lds_dwordx4 v192, s[28:29]
	s_mov_b32 m0, s37
	s_nop 0
	global_load_lds_dwordx4 v196, s[28:29]
	s_waitcnt vmcnt(10)
	s_barrier
	s_waitcnt lgkmcnt(0)
	s_setprio 1
	s_waitcnt lgkmcnt(0)
	v_mfma_f32_16x16x32_bf16 v[60:63], v[128:131], v[144:147], v[60:63]
	v_mfma_f32_16x16x32_bf16 v[56:59], v[136:139], v[144:147], v[56:59]
	v_mfma_f32_16x16x32_bf16 v[48:51], v[128:131], v[152:155], v[48:51]
	v_mfma_f32_16x16x32_bf16 v[40:43], v[136:139], v[152:155], v[40:43]
	v_mfma_f32_16x16x32_bf16 v[32:35], v[128:131], v[160:163], v[32:35]
	v_mfma_f32_16x16x32_bf16 v[24:27], v[136:139], v[160:163], v[24:27]
	v_mfma_f32_16x16x32_bf16 v[16:19], v[128:131], v[168:171], v[16:19]
	v_mfma_f32_16x16x32_bf16 v[8:11], v[136:139], v[168:171], v[8:11]
	v_mfma_f32_16x16x32_bf16 v[60:63], v[132:135], v[148:151], v[60:63]
	v_mfma_f32_16x16x32_bf16 v[56:59], v[140:143], v[148:151], v[56:59]
	v_mfma_f32_16x16x32_bf16 v[48:51], v[132:135], v[156:159], v[48:51]
	v_mfma_f32_16x16x32_bf16 v[40:43], v[140:143], v[156:159], v[40:43]
	v_mfma_f32_16x16x32_bf16 v[32:35], v[132:135], v[164:167], v[32:35]
	v_mfma_f32_16x16x32_bf16 v[24:27], v[140:143], v[164:167], v[24:27]
	v_mfma_f32_16x16x32_bf16 v[16:19], v[132:135], v[172:175], v[16:19]
	s_barrier
; #define PG8_STAGE(bufoff, gbase, voff) do { _Pragma("unroll") for (int _i = 0; _i < 2; ++_i) \
;         __builtin_amdgcn_global_load_lds((const unsigned*)((const char*)(gbase) + (voff)[_i]), (LAS unsigned*)(lds + (bufoff) + ldsw + _i * 8192), 16, 0, 0); } while (0)
; #define PG8_LDA(dst, b, h) do { _Pragma("unroll") for (int m = 0; m < 4; ++m) _Pragma("unroll") for (int k = 0; k < 2; ++k) dst[m][k] = *(const LAS bf16x8*)(lds + PG8_SA(b, h) + aoff + m * 2048 + k * 1024); } while (0)
; #define PG8_LDB(dst, b, h) do { _Pragma("unroll") for (int n = 0; n < 2; ++n) _Pragma("unroll") for (int k = 0; k < 2; ++k) dst[n][k] = *(const LAS bf16x8*)(lds + PG8_SB(b, h) + boff + n * 2048 + k * 1024); } while (0)
; #define PG8_MMA(ai, bj, At, Bt) do { __builtin_amdgcn_s_setprio(1); _Pragma("unroll") for (int m = 0; m < 4; ++m) _Pragma("unroll") for (int n = 0; n < 2; ++n) _Pragma("unroll") for (int k = 0; k < 2; ++k) \
;         acc[ai][bj][m][n] = __builtin_amdgcn_mfma_f32_16x16x32_bf16(Bt[n][k], At[m][k], acc[ai][bj][m][n], 0, 0, 0); __builtin_amdgcn_s_setprio(0); } while (0)
; #define PG8_WAIT_V(n) asm volatile("s_waitcnt vmcnt(" #n ")" ::: "memory")
; #define PG8_WAIT_L(n) asm volatile("s_waitcnt lgkmcnt(" #n ")" ::: "memory")
; #define PG8_BAR __builtin_amdgcn_s_barrier()
; #define PG8_SCHED __builtin_amdgcn_sched_barrier(0)
; template <class Epi>
; __device__ __forceinline__ void gemm_phase(ldsp lds, const Gemm g, const StaticOrder& S, const Epi& E) {
;     ...
;             PG8_WAIT_V(10); PG8_BAR; PG8_WAIT_L(0); PG8_MMA(1, 0, At, B0); PG8_BAR; PG8_SCHED;
;             PG8_STAGE(PG8_SB(0, 1), b2 + hstep, voffB);
;             PG8_WAIT_V(10); PG8_BAR; PG8_MMA(1, 1, At, B1); PG8_BAR;
;             PG8_LDB(B0, 1, 0); PG8_SCHED; PG8_LDA(At, 1, 0); PG8_STAGE(PG8_SA(0, 1), a2 + hstep, voffA);
;             PG8_WAIT_L(8); PG8_WAIT_V(10); PG8_BAR; PG8_WAIT_L(0); PG8_MMA(0, 0, At, B0); PG8_BAR; PG8_SCHED;
;             PG8_LDB(B1, 1, 1); PG8_STAGE(PG8_SB(1, 0), b3, voffB);
	v_mfma_f32_16x16x32_bf16 v[8:11], v[140:143], v[172:175], v[8:11]
	s_setprio 0
	s_add_u32 s54, s26, 0x60000
	s_addc_u32 s55, s27, 0
	s_add_i32 s56, s46, s35
	s_mov_b32 m0, s56
	s_nop 0
	global_load_lds_dwordx4 v194, s[54:55]
	s_add_i32 m0, s56, 0x2000
	s_nop 0
	global_load_lds_dwordx4 v198, s[54:55]
	s_waitcnt vmcnt(10)
	s_barrier
	s_setprio 1
	v_mfma_f32_16x16x32_bf16 v[52:55], v[176:179], v[144:147], v[52:55]
	v_mfma_f32_16x16x32_bf16 v[44:47], v[184:187], v[144:147], v[44:47]
	v_mfma_f32_16x16x32_bf16 v[36:39], v[176:179], v[152:155], v[36:39]
	v_mfma_f32_16x16x32_bf16 v[28:31], v[184:187], v[152:155], v[28:31]
	v_mfma_f32_16x16x32_bf16 v[20:23], v[176:179], v[160:163], v[20:23]
	v_mfma_f32_16x16x32_bf16 v[12:15], v[184:187], v[160:163], v[12:15]
	v_mfma_f32_16x16x32_bf16 v[4:7], v[176:179], v[168:171], v[4:7]
	v_mfma_f32_16x16x32_bf16 v[0:3], v[184:187], v[168:171], v[0:3]
	v_mfma_f32_16x16x32_bf16 v[52:55], v[180:183], v[148:151], v[52:55]
	v_mfma_f32_16x16x32_bf16 v[44:47], v[188:191], v[148:151], v[44:47]
	v_mfma_f32_16x16x32_bf16 v[36:39], v[180:183], v[156:159], v[36:39]
	v_mfma_f32_16x16x32_bf16 v[28:31], v[188:191], v[156:159], v[28:31]
	v_mfma_f32_16x16x32_bf16 v[20:23], v[180:183], v[164:167], v[20:23]
	v_mfma_f32_16x16x32_bf16 v[12:15], v[188:191], v[164:167], v[12:15]
	v_mfma_f32_16x16x32_bf16 v[4:7], v[180:183], v[172:175], v[4:7]
	s_barrier
	v_mfma_f32_16x16x32_bf16 v[0:3], v[188:191], v[172:175], v[0:3]
	s_setprio 0
	s_add_i32 s54, 0, 0x18000
	v_add_u32_e32 v140, s54, v222
	ds_read_b128 v[128:131], v140
	ds_read_b128 v[132:135], v140 offset:1024
	ds_read_b128 v[136:139], v140 offset:2048
	ds_read_b128 v[140:143], v140 offset:3072
	s_add_u32 s28, s28, 0x60000
	s_addc_u32 s29, s29, 0
	s_mov_b32 m0, s38
	ds_read_b128 v[144:147], v224 offset:32768
	ds_read_b128 v[148:151], v224 offset:33792
	ds_read_b128 v[152:155], v224 offset:34816
	ds_read_b128 v[156:159], v224 offset:35840
	ds_read_b128 v[160:163], v224 offset:36864
	ds_read_b128 v[164:167], v224 offset:37888
	ds_read_b128 v[168:171], v224 offset:38912
	ds_read_b128 v[172:175], v224 offset:39936
	global_load_lds_dwordx4 v192, s[28:29]
	s_mov_b32 m0, s39
	s_nop 0
	global_load_lds_dwordx4 v196, s[28:29]
	s_waitcnt lgkmcnt(8)
	s_waitcnt vmcnt(10)
	s_barrier
	s_waitcnt lgkmcnt(0)
	s_setprio 1
	s_waitcnt lgkmcnt(0)
	v_mfma_f32_16x16x32_bf16 v[124:127], v[128:131], v[144:147], v[124:127]
	v_mfma_f32_16x16x32_bf16 v[120:123], v[136:139], v[144:147], v[120:123]
	v_mfma_f32_16x16x32_bf16 v[116:119], v[128:131], v[152:155], v[116:119]
	v_mfma_f32_16x16x32_bf16 v[104:107], v[136:139], v[152:155], v[104:107]
	v_mfma_f32_16x16x32_bf16 v[96:99], v[128:131], v[160:163], v[96:99]
	v_mfma_f32_16x16x32_bf16 v[88:91], v[136:139], v[160:163], v[88:91]
	v_mfma_f32_16x16x32_bf16 v[80:83], v[128:131], v[168:171], v[80:83]
	v_mfma_f32_16x16x32_bf16 v[72:75], v[136:139], v[168:171], v[72:75]
	v_mfma_f32_16x16x32_bf16 v[124:127], v[132:135], v[148:151], v[124:127]
	v_mfma_f32_16x16x32_bf16 v[120:123], v[140:143], v[148:151], v[120:123]
	v_mfma_f32_16x16x32_bf16 v[116:119], v[132:135], v[156:159], v[116:119]
	v_mfma_f32_16x16x32_bf16 v[104:107], v[140:143], v[156:159], v[104:107]
	v_mfma_f32_16x16x32_bf16 v[96:99], v[132:135], v[164:167], v[96:99]
	v_mfma_f32_16x16x32_bf16 v[88:91], v[140:143], v[164:167], v[88:91]
	v_mfma_f32_16x16x32_bf16 v[80:83], v[132:135], v[172:175], v[80:83]
	s_barrier
	v_mfma_f32_16x16x32_bf16 v[72:75], v[140:143], v[172:175], v[72:75]
	s_setprio 0
	s_add_i32 s28, 0, 0x1c000
	s_add_i32 s29, s54, s35
	v_add_u32_e32 v188, s28, v222
	s_mov_b32 m0, s29
	ds_read_b128 v[176:179], v188
	ds_read_b128 v[180:183], v188 offset:1024
	ds_read_b128 v[184:187], v188 offset:2048
	ds_read_b128 v[188:191], v188 offset:3072
	global_load_lds_dwordx4 v194, s[98:99]
	s_add_i32 m0, s29, 0x2000
	s_nop 0
	global_load_lds_dwordx4 v198, s[98:99]
	s_waitcnt vmcnt(10)
	s_barrier
; #define PG8_STAGE(bufoff, gbase, voff) do { _Pragma("unroll") for (int _i = 0; _i < 2; ++_i) \
;         __builtin_amdgcn_global_load_lds((const unsigned*)((const char*)(gbase) + (voff)[_i]), (LAS unsigned*)(lds + (bufoff) + ldsw + _i * 8192), 16, 0, 0); } while (0)
; #define PG8_LDA(dst, b, h) do { _Pragma("unroll") for (int m = 0; m < 4; ++m) _Pragma("unroll") for (int k = 0; k < 2; ++k) dst[m][k] = *(const LAS bf16x8*)(lds + PG8_SA(b, h) + aoff + m * 2048 + k * 1024); } while (0)
; #define PG8_LDB(dst, b, h) do { _Pragma("unroll") for (int n = 0; n < 2; ++n) _Pragma("unroll") for (int k = 0; k < 2; ++k) dst[n][k] = *(const LAS bf16x8*)(lds + PG8_SB(b, h) + boff + n * 2048 + k * 1024); } while (0)
; #define PG8_MMA(ai, bj, At, Bt) do { __builtin_amdgcn_s_setprio(1); _Pragma("unroll") for (int m = 0; m < 4; ++m) _Pragma("unroll") for (int n = 0; n < 2; ++n) _Pragma("unroll") for (int k = 0; k < 2; ++k) \
;         acc[ai][bj][m][n] = __builtin_amdgcn_mfma_f32_16x16x32_bf16(Bt[n][k], At[m][k], acc[ai][bj][m][n], 0, 0, 0); __builtin_amdgcn_s_setprio(0); } while (0)
; #define PG8_WAIT_V(n) asm volatile("s_waitcnt vmcnt(" #n ")" ::: "memory")
; #define PG8_WAIT_L(n) asm volatile("s_waitcnt lgkmcnt(" #n ")" ::: "memory")
; #define PG8_BAR __builtin_amdgcn_s_barrier()
; #define PG8_SCHED __builtin_amdgcn_sched_barrier(0)
; template <class Epi>
; __device__ __forceinline__ void gemm_phase(ldsp lds, const Gemm g, const StaticOrder& S, const Epi& E) {
;     ...
;             PG8_WAIT_L(8); PG8_WAIT_V(10); PG8_BAR; PG8_WAIT_L(0); PG8_MMA(0, 0, At, B0); PG8_BAR; PG8_SCHED;
;             PG8_LDB(B1, 1, 1); PG8_STAGE(PG8_SB(1, 0), b3, voffB);
;             PG8_WAIT_V(10); PG8_BAR; PG8_WAIT_L(0); PG8_MMA(0, 1, At, B1); PG8_BAR;
;             PG8_LDA(At, 1, 1); PG8_STAGE(PG8_SA(1, 0), a3, voffA);
;             PG8_WAIT_V(10); PG8_BAR; PG8_WAIT_L(0); PG8_MMA(1, 0, At, B0); PG8_BAR; PG8_SCHED;
;             PG8_STAGE(PG8_SB(1, 1), b3 + hstep, voffB);
;             PG8_WAIT_V(10); PG8_BAR; PG8_MMA(1, 1, At, B1); PG8_BAR;
;         }
	s_waitcnt lgkmcnt(0)
	s_setprio 1
	s_waitcnt lgkmcnt(0)
	v_mfma_f32_16x16x32_bf16 v[112:115], v[176:179], v[144:147], v[112:115]
	v_mfma_f32_16x16x32_bf16 v[108:111], v[184:187], v[144:147], v[108:111]
	v_mfma_f32_16x16x32_bf16 v[100:103], v[176:179], v[152:155], v[100:103]
	v_mfma_f32_16x16x32_bf16 v[92:95], v[184:187], v[152:155], v[92:95]
	v_mfma_f32_16x16x32_bf16 v[84:87], v[176:179], v[160:163], v[84:87]
	v_mfma_f32_16x16x32_bf16 v[76:79], v[184:187], v[160:163], v[76:79]
	v_mfma_f32_16x16x32_bf16 v[68:71], v[176:179], v[168:171], v[68:71]
	v_mfma_f32_16x16x32_bf16 v[64:67], v[184:187], v[168:171], v[64:67]
	v_mfma_f32_16x16x32_bf16 v[112:115], v[180:183], v[148:151], v[112:115]
	v_mfma_f32_16x16x32_bf16 v[108:111], v[188:191], v[148:151], v[108:111]
	v_mfma_f32_16x16x32_bf16 v[100:103], v[180:183], v[156:159], v[100:103]
	v_mfma_f32_16x16x32_bf16 v[92:95], v[188:191], v[156:159], v[92:95]
	v_mfma_f32_16x16x32_bf16 v[84:87], v[180:183], v[164:167], v[84:87]
	v_mfma_f32_16x16x32_bf16 v[76:79], v[188:191], v[164:167], v[76:79]
	v_mfma_f32_16x16x32_bf16 v[68:71], v[180:183], v[172:175], v[68:71]
	s_barrier
	v_mfma_f32_16x16x32_bf16 v[64:67], v[188:191], v[172:175], v[64:67]
	s_setprio 0
	s_mov_b32 m0, s41
	ds_read_b128 v[144:147], v224 offset:49152
	ds_read_b128 v[148:151], v224 offset:50176
	ds_read_b128 v[152:155], v224 offset:51200
	ds_read_b128 v[156:159], v224 offset:52224
	ds_read_b128 v[160:163], v224 offset:53248
	ds_read_b128 v[164:167], v224 offset:54272
	ds_read_b128 v[168:171], v224 offset:55296
	ds_read_b128 v[172:175], v224 offset:56320
	global_load_lds_dwordx4 v192, s[100:101]
	s_mov_b32 m0, s42
	s_nop 0
	global_load_lds_dwordx4 v196, s[100:101]
	s_waitcnt vmcnt(10)
	s_barrier
	s_waitcnt lgkmcnt(0)
	s_setprio 1
	s_waitcnt lgkmcnt(0)
	v_mfma_f32_16x16x32_bf16 v[60:63], v[128:131], v[144:147], v[60:63]
	v_mfma_f32_16x16x32_bf16 v[56:59], v[136:139], v[144:147], v[56:59]
	v_mfma_f32_16x16x32_bf16 v[48:51], v[128:131], v[152:155], v[48:51]
	v_mfma_f32_16x16x32_bf16 v[40:43], v[136:139], v[152:155], v[40:43]
	v_mfma_f32_16x16x32_bf16 v[32:35], v[128:131], v[160:163], v[32:35]
	v_mfma_f32_16x16x32_bf16 v[24:27], v[136:139], v[160:163], v[24:27]
	v_mfma_f32_16x16x32_bf16 v[16:19], v[128:131], v[168:171], v[16:19]
	v_mfma_f32_16x16x32_bf16 v[8:11], v[136:139], v[168:171], v[8:11]
	v_mfma_f32_16x16x32_bf16 v[60:63], v[132:135], v[148:151], v[60:63]
	v_mfma_f32_16x16x32_bf16 v[56:59], v[140:143], v[148:151], v[56:59]
	v_mfma_f32_16x16x32_bf16 v[48:51], v[132:135], v[156:159], v[48:51]
	v_mfma_f32_16x16x32_bf16 v[40:43], v[140:143], v[156:159], v[40:43]
	v_mfma_f32_16x16x32_bf16 v[32:35], v[132:135], v[164:167], v[32:35]
	v_mfma_f32_16x16x32_bf16 v[24:27], v[140:143], v[164:167], v[24:27]
	v_mfma_f32_16x16x32_bf16 v[16:19], v[132:135], v[172:175], v[16:19]
	s_barrier
	v_mfma_f32_16x16x32_bf16 v[8:11], v[140:143], v[172:175], v[8:11]
	s_setprio 0
	s_add_u32 s26, s26, 0x60080
	s_addc_u32 s27, s27, 0
	s_add_i32 s28, s28, s35
	s_mov_b32 m0, s28
	s_nop 0
	global_load_lds_dwordx4 v194, s[26:27]
	s_add_i32 m0, s28, 0x2000
	s_nop 0
	global_load_lds_dwordx4 v198, s[26:27]
	s_waitcnt vmcnt(10)
	s_barrier
	s_setprio 1
	v_mfma_f32_16x16x32_bf16 v[52:55], v[176:179], v[144:147], v[52:55]
	v_mfma_f32_16x16x32_bf16 v[44:47], v[184:187], v[144:147], v[44:47]
	v_mfma_f32_16x16x32_bf16 v[36:39], v[176:179], v[152:155], v[36:39]
	v_mfma_f32_16x16x32_bf16 v[28:31], v[184:187], v[152:155], v[28:31]
	v_mfma_f32_16x16x32_bf16 v[20:23], v[176:179], v[160:163], v[20:23]
	v_mfma_f32_16x16x32_bf16 v[12:15], v[184:187], v[160:163], v[12:15]
	v_mfma_f32_16x16x32_bf16 v[4:7], v[176:179], v[168:171], v[4:7]
	v_mfma_f32_16x16x32_bf16 v[0:3], v[184:187], v[168:171], v[0:3]
	v_mfma_f32_16x16x32_bf16 v[52:55], v[180:183], v[148:151], v[52:55]
	v_mfma_f32_16x16x32_bf16 v[44:47], v[188:191], v[148:151], v[44:47]
	v_mfma_f32_16x16x32_bf16 v[36:39], v[180:183], v[156:159], v[36:39]
	v_mfma_f32_16x16x32_bf16 v[28:31], v[188:191], v[156:159], v[28:31]
	v_mfma_f32_16x16x32_bf16 v[20:23], v[180:183], v[164:167], v[20:23]
	v_mfma_f32_16x16x32_bf16 v[12:15], v[188:191], v[164:167], v[12:15]
	v_mfma_f32_16x16x32_bf16 v[4:7], v[180:183], v[172:175], v[4:7]
	s_barrier
	v_mfma_f32_16x16x32_bf16 v[0:3], v[188:191], v[172:175], v[0:3]
	s_setprio 0
	s_add_i32 s53, s53, 2
	s_add_u32 s24, s24, 0x100
	s_addc_u32 s25, s25, 0
	s_cmp_gt_u32 s53, 21
	s_cbranch_scc1 .LBB0_642

; #define PG8_STAGE(bufoff, gbase, voff) do { _Pragma("unroll") for (int _i = 0; _i < 2; ++_i) \
;         __builtin_amdgcn_global_load_lds((const unsigned*)((const char*)(gbase) + (voff)[_i]), (LAS unsigned*)(lds + (bufoff) + ldsw + _i * 8192), 16, 0, 0); } while (0)
; #define PG8_WAIT_V(n) asm volatile("s_waitcnt vmcnt(" #n ")" ::: "memory")
; #define PG8_WAIT_L(n) asm volatile("s_waitcnt lgkmcnt(" #n ")" ::: "memory")
; template <class Epi>
; __device__ __forceinline__ void gemm_phase(ldsp lds, const Gemm g, const StaticOrder& S, const Epi& E) {
;     ...
;         for (int t = 0; t < nt; t += 2) {
;             const bool last = (t == nt - 2);
;             const char* a1 = cA + (size_t)(t + 1) * kstep;
;             const char* a2 = last ? nA : cA + (size_t)(t + 2) * kstep; const char* b2 = last ? nB : cB + (size_t)(t + 2) * kstep;
;             const char* a3 = a2 + kstep; const char* b3 = b2 + kstep;
;             if constexpr (Epi::NPRE > 0) { if (last) E.pre(pre, cur, wr, fr); }
;             if constexpr (Epi::MID_T > 0) { if (t == Epi::MID_T) E.mid(acc, cur, wr, wc, fr, fq); }
;             PG8_LDB(B0, 0, 0); PG8_SCHED; PG8_LDA(At, 0, 0); PG8_STAGE(PG8_SA(1, 1), a1 + hstep, voffA);
;             PG8_WAIT_L(8); PG8_WAIT_V(10); PG8_BAR; PG8_WAIT_L(0); PG8_MMA(0, 0, At, B0); PG8_BAR; PG8_SCHED;
;             PG8_LDB(B1, 0, 1); PG8_STAGE(PG8_SB(0, 0), b2, voffB);
;             PG8_WAIT_V(10); PG8_BAR; PG8_WAIT_L(0); PG8_MMA(0, 1, At, B1); PG8_BAR;
;             PG8_LDA(At, 0, 1); PG8_STAGE(PG8_SA(0, 0), a2, voffA);
;             PG8_WAIT_V(10); PG8_BAR; PG8_WAIT_L(0); PG8_MMA(1, 0, At, B0); PG8_BAR; PG8_SCHED;
;             PG8_STAGE(PG8_SB(0, 1), b2 + hstep, voffB);
;             PG8_WAIT_V(10); PG8_BAR; PG8_MMA(1, 1, At, B1); PG8_BAR;
;             PG8_LDB(B0, 1, 0); PG8_SCHED; PG8_LDA(At, 1, 0); PG8_STAGE(PG8_SA(0, 1), a2 + hstep, voffA);
;             PG8_WAIT_L(8); PG8_WAIT_V(10); PG8_BAR; PG8_WAIT_L(0); PG8_MMA(0, 0, At, B0); PG8_BAR; PG8_SCHED;
;             PG8_LDB(B1, 1, 1); PG8_STAGE(PG8_SB(1, 0), b3, voffB);
;             PG8_WAIT_V(10); PG8_BAR; PG8_WAIT_L(0); PG8_MMA(0, 1, At, B1); PG8_BAR;
;             PG8_LDA(At, 1, 1); PG8_STAGE(PG8_SA(1, 0), a3, voffA);
;             PG8_WAIT_V(10); PG8_BAR; PG8_WAIT_L(0); PG8_MMA(1, 0, At, B0); PG8_BAR; PG8_SCHED;
;             PG8_STAGE(PG8_SB(1, 1), b3 + hstep, voffB);
.LBB0_733:
	ds_read_b128 v[128:131], v211
	ds_read_b128 v[132:135], v211 offset:1024
	ds_read_b128 v[136:139], v211 offset:2048
	ds_read_b128 v[140:143], v211 offset:3072
	s_add_u32 s24, s22, 0xfff80080
	s_addc_u32 s25, s23, -1
	s_cmp_eq_u32 s46, 28
	s_cselect_b32 s27, s13, s25
	s_cselect_b32 s26, s19, s24
	s_cselect_b32 s25, s11, s45
	s_cselect_b32 s24, s43, s44
	s_add_i32 m0, s21, 0xc000
	ds_read_b128 v[144:147], v212
	ds_read_b128 v[148:151], v212 offset:1024
	ds_read_b128 v[152:155], v212 offset:2048
	ds_read_b128 v[156:159], v212 offset:3072
	ds_read_b128 v[160:163], v212 offset:4096
	ds_read_b128 v[164:167], v212 offset:5120
	ds_read_b128 v[168:171], v212 offset:6144
	ds_read_b128 v[172:175], v212 offset:7168
	global_load_lds_dwordx4 v184, s[22:23]
	s_add_i32 m0, s21, 0xe000
	s_nop 0
	global_load_lds_dwordx4 v186, s[22:23]
	s_waitcnt lgkmcnt(8)
	s_waitcnt vmcnt(10)
	s_barrier
	s_waitcnt lgkmcnt(0)
	s_setprio 1
	s_waitcnt lgkmcnt(0)
	v_mfma_f32_16x16x32_bf16 v[124:127], v[128:131], v[144:147], v[124:127]
	v_mfma_f32_16x16x32_bf16 v[120:123], v[136:139], v[144:147], v[120:123]
	v_mfma_f32_16x16x32_bf16 v[108:111], v[128:131], v[152:155], v[108:111]
	v_mfma_f32_16x16x32_bf16 v[104:107], v[136:139], v[152:155], v[104:107]
	v_mfma_f32_16x16x32_bf16 v[92:95], v[128:131], v[160:163], v[92:95]
	v_mfma_f32_16x16x32_bf16 v[88:91], v[136:139], v[160:163], v[88:91]
	v_mfma_f32_16x16x32_bf16 v[76:79], v[128:131], v[168:171], v[76:79]
	v_mfma_f32_16x16x32_bf16 v[72:75], v[136:139], v[168:171], v[72:75]
	v_mfma_f32_16x16x32_bf16 v[124:127], v[132:135], v[148:151], v[124:127]
	v_mfma_f32_16x16x32_bf16 v[120:123], v[140:143], v[148:151], v[120:123]
	v_mfma_f32_16x16x32_bf16 v[108:111], v[132:135], v[156:159], v[108:111]
	v_mfma_f32_16x16x32_bf16 v[104:107], v[140:143], v[156:159], v[104:107]
	v_mfma_f32_16x16x32_bf16 v[92:95], v[132:135], v[164:167], v[92:95]
	v_mfma_f32_16x16x32_bf16 v[88:91], v[140:143], v[164:167], v[88:91]
	v_mfma_f32_16x16x32_bf16 v[76:79], v[132:135], v[172:175], v[76:79]
	s_barrier
	v_mfma_f32_16x16x32_bf16 v[72:75], v[140:143], v[172:175], v[72:75]
	s_setprio 0
	s_add_i32 s47, s40, s29
	s_add_u32 s98, s24, 0x80
	s_addc_u32 s99, s25, 0
	s_mov_b32 m0, s47
	ds_read_b128 v[192:195], v213
	ds_read_b128 v[196:199], v213 offset:1024
	ds_read_b128 v[200:203], v213 offset:2048
	ds_read_b128 v[204:207], v213 offset:3072
	global_load_lds_dwordx4 v178, s[24:25]
	s_add_i32 m0, s47, 0x2000
	s_nop 0
	global_load_lds_dwordx4 v182, s[24:25]
	s_waitcnt vmcnt(10)
	s_barrier
	s_waitcnt lgkmcnt(0)
	s_setprio 1
	s_waitcnt lgkmcnt(0)
	v_mfma_f32_16x16x32_bf16 v[116:119], v[192:195], v[144:147], v[116:119]
	v_mfma_f32_16x16x32_bf16 v[112:115], v[200:203], v[144:147], v[112:115]
	v_mfma_f32_16x16x32_bf16 v[100:103], v[192:195], v[152:155], v[100:103]
	v_mfma_f32_16x16x32_bf16 v[96:99], v[200:203], v[152:155], v[96:99]
	v_mfma_f32_16x16x32_bf16 v[84:87], v[192:195], v[160:163], v[84:87]
	v_mfma_f32_16x16x32_bf16 v[80:83], v[200:203], v[160:163], v[80:83]
	v_mfma_f32_16x16x32_bf16 v[68:71], v[192:195], v[168:171], v[68:71]
	v_mfma_f32_16x16x32_bf16 v[64:67], v[200:203], v[168:171], v[64:67]
	v_mfma_f32_16x16x32_bf16 v[116:119], v[196:199], v[148:151], v[116:119]
	v_mfma_f32_16x16x32_bf16 v[112:115], v[204:207], v[148:151], v[112:115]
	v_mfma_f32_16x16x32_bf16 v[100:103], v[196:199], v[156:159], v[100:103]
	v_mfma_f32_16x16x32_bf16 v[96:99], v[204:207], v[156:159], v[96:99]
	v_mfma_f32_16x16x32_bf16 v[84:87], v[196:199], v[164:167], v[84:87]
	v_mfma_f32_16x16x32_bf16 v[80:83], v[204:207], v[164:167], v[80:83]
	v_mfma_f32_16x16x32_bf16 v[68:71], v[196:199], v[172:175], v[68:71]
	s_barrier
	v_mfma_f32_16x16x32_bf16 v[64:67], v[204:207], v[172:175], v[64:67]
	s_setprio 0
	s_mov_b32 m0, s21
	s_add_u32 s100, s26, 0x80
	s_addc_u32 s101, s27, 0
	ds_read_b128 v[144:147], v212 offset:16384
	ds_read_b128 v[148:151], v212 offset:17408
	ds_read_b128 v[152:155], v212 offset:18432
	ds_read_b128 v[156:159], v212 offset:19456
	ds_read_b128 v[160:163], v212 offset:20480
	ds_read_b128 v[164:167], v212 offset:21504
	ds_read_b128 v[168:171], v212 offset:22528
	ds_read_b128 v[172:175], v212 offset:23552
	global_load_lds_dwordx4 v176, s[26:27]
	s_mov_b32 m0, s30
	s_nop 0
	global_load_lds_dwordx4 v180, s[26:27]
	s_waitcnt vmcnt(10)
	s_barrier
	s_waitcnt lgkmcnt(0)
	s_setprio 1
	s_waitcnt lgkmcnt(0)
	v_mfma_f32_16x16x32_bf16 v[60:63], v[128:131], v[144:147], v[60:63]
	v_mfma_f32_16x16x32_bf16 v[56:59], v[136:139], v[144:147], v[56:59]
	v_mfma_f32_16x16x32_bf16 v[44:47], v[128:131], v[152:155], v[44:47]
	v_mfma_f32_16x16x32_bf16 v[40:43], v[136:139], v[152:155], v[40:43]
	v_mfma_f32_16x16x32_bf16 v[28:31], v[128:131], v[160:163], v[28:31]
	v_mfma_f32_16x16x32_bf16 v[24:27], v[136:139], v[160:163], v[24:27]
	v_mfma_f32_16x16x32_bf16 v[12:15], v[128:131], v[168:171], v[12:15]
	v_mfma_f32_16x16x32_bf16 v[8:11], v[136:139], v[168:171], v[8:11]
	v_mfma_f32_16x16x32_bf16 v[60:63], v[132:135], v[148:151], v[60:63]
	v_mfma_f32_16x16x32_bf16 v[56:59], v[140:143], v[148:151], v[56:59]
	v_mfma_f32_16x16x32_bf16 v[44:47], v[132:135], v[156:159], v[44:47]
	v_mfma_f32_16x16x32_bf16 v[40:43], v[140:143], v[156:159], v[40:43]
	v_mfma_f32_16x16x32_bf16 v[28:31], v[132:135], v[164:167], v[28:31]
	v_mfma_f32_16x16x32_bf16 v[24:27], v[140:143], v[164:167], v[24:27]
	v_mfma_f32_16x16x32_bf16 v[12:15], v[132:135], v[172:175], v[12:15]
	s_barrier
	v_mfma_f32_16x16x32_bf16 v[8:11], v[140:143], v[172:175], v[8:11]
	s_setprio 0
	s_add_u32 s50, s24, 0x80000
	s_addc_u32 s51, s25, 0
	s_add_i32 s47, s41, s29
	s_mov_b32 m0, s47
	s_nop 0
	global_load_lds_dwordx4 v178, s[50:51]
	s_add_i32 m0, s47, 0x2000
	s_nop 0
	global_load_lds_dwordx4 v182, s[50:51]
	s_waitcnt vmcnt(10)
	s_barrier
; #define PG8_STAGE(bufoff, gbase, voff) do { _Pragma("unroll") for (int _i = 0; _i < 2; ++_i) \
;         __builtin_amdgcn_global_load_lds((const unsigned*)((const char*)(gbase) + (voff)[_i]), (LAS unsigned*)(lds + (bufoff) + ldsw + _i * 8192), 16, 0, 0); } while (0)
; #define PG8_LDA(dst, b, h) do { _Pragma("unroll") for (int m = 0; m < 4; ++m) _Pragma("unroll") for (int k = 0; k < 2; ++k) dst[m][k] = *(const LAS bf16x8*)(lds + PG8_SA(b, h) + aoff + m * 2048 + k * 1024); } while (0)
; #define PG8_LDB(dst, b, h) do { _Pragma("unroll") for (int n = 0; n < 2; ++n) _Pragma("unroll") for (int k = 0; k < 2; ++k) dst[n][k] = *(const LAS bf16x8*)(lds + PG8_SB(b, h) + boff + n * 2048 + k * 1024); } while (0)
; #define PG8_MMA(ai, bj, At, Bt) do { __builtin_amdgcn_s_setprio(1); _Pragma("unroll") for (int m = 0; m < 4; ++m) _Pragma("unroll") for (int n = 0; n < 2; ++n) _Pragma("unroll") for (int k = 0; k < 2; ++k) \
;         acc[ai][bj][m][n] = __builtin_amdgcn_mfma_f32_16x16x32_bf16(Bt[n][k], At[m][k], acc[ai][bj][m][n], 0, 0, 0); __builtin_amdgcn_s_setprio(0); } while (0)
; #define PG8_WAIT_V(n) asm volatile("s_waitcnt vmcnt(" #n ")" ::: "memory")
; #define PG8_WAIT_L(n) asm volatile("s_waitcnt lgkmcnt(" #n ")" ::: "memory")
; #define PG8_BAR __builtin_amdgcn_s_barrier()
; #define PG8_SCHED __builtin_amdgcn_sched_barrier(0)
; template <class Epi>
; __device__ __forceinline__ void gemm_phase(ldsp lds, const Gemm g, const StaticOrder& S, const Epi& E) {
;     ...
;             PG8_WAIT_V(10); PG8_BAR; PG8_MMA(1, 1, At, B1); PG8_BAR;
;             PG8_LDB(B0, 1, 0); PG8_SCHED; PG8_LDA(At, 1, 0); PG8_STAGE(PG8_SA(0, 1), a2 + hstep, voffA);
;             PG8_WAIT_L(8); PG8_WAIT_V(10); PG8_BAR; PG8_WAIT_L(0); PG8_MMA(0, 0, At, B0); PG8_BAR; PG8_SCHED;
;             PG8_LDB(B1, 1, 1); PG8_STAGE(PG8_SB(1, 0), b3, voffB);
;             PG8_WAIT_V(10); PG8_BAR; PG8_WAIT_L(0); PG8_MMA(0, 1, At, B1); PG8_BAR;
;             PG8_LDA(At, 1, 1); PG8_STAGE(PG8_SA(1, 0), a3, voffA);
	s_setprio 1
	v_mfma_f32_16x16x32_bf16 v[52:55], v[192:195], v[144:147], v[52:55]
	v_mfma_f32_16x16x32_bf16 v[48:51], v[200:203], v[144:147], v[48:51]
	v_mfma_f32_16x16x32_bf16 v[36:39], v[192:195], v[152:155], v[36:39]
	v_mfma_f32_16x16x32_bf16 v[32:35], v[200:203], v[152:155], v[32:35]
	v_mfma_f32_16x16x32_bf16 v[20:23], v[192:195], v[160:163], v[20:23]
	v_mfma_f32_16x16x32_bf16 v[16:19], v[200:203], v[160:163], v[16:19]
	v_mfma_f32_16x16x32_bf16 v[4:7], v[192:195], v[168:171], v[4:7]
	v_mfma_f32_16x16x32_bf16 v[0:3], v[200:203], v[168:171], v[0:3]
	v_mfma_f32_16x16x32_bf16 v[52:55], v[196:199], v[148:151], v[52:55]
	v_mfma_f32_16x16x32_bf16 v[48:51], v[204:207], v[148:151], v[48:51]
	v_mfma_f32_16x16x32_bf16 v[36:39], v[196:199], v[156:159], v[36:39]
	v_mfma_f32_16x16x32_bf16 v[32:35], v[204:207], v[156:159], v[32:35]
	v_mfma_f32_16x16x32_bf16 v[20:23], v[196:199], v[164:167], v[20:23]
	v_mfma_f32_16x16x32_bf16 v[16:19], v[204:207], v[164:167], v[16:19]
	v_mfma_f32_16x16x32_bf16 v[4:7], v[196:199], v[172:175], v[4:7]
	s_barrier
	v_mfma_f32_16x16x32_bf16 v[0:3], v[204:207], v[172:175], v[0:3]
	s_setprio 0
	s_add_i32 s47, 0, 0x18000
	v_add_u32_e32 v140, s47, v209
	ds_read_b128 v[128:131], v140
	ds_read_b128 v[132:135], v140 offset:1024
	ds_read_b128 v[136:139], v140 offset:2048
	ds_read_b128 v[140:143], v140 offset:3072
	s_add_u32 s26, s26, 0x80000
	s_addc_u32 s27, s27, 0
	s_mov_b32 m0, s31
	ds_read_b128 v[144:147], v212 offset:32768
	ds_read_b128 v[148:151], v212 offset:33792
	ds_read_b128 v[152:155], v212 offset:34816
	ds_read_b128 v[156:159], v212 offset:35840
	ds_read_b128 v[160:163], v212 offset:36864
	ds_read_b128 v[164:167], v212 offset:37888
	ds_read_b128 v[168:171], v212 offset:38912
	ds_read_b128 v[172:175], v212 offset:39936
	global_load_lds_dwordx4 v176, s[26:27]
	s_mov_b32 m0, s33
	s_nop 0
	global_load_lds_dwordx4 v180, s[26:27]
	s_waitcnt lgkmcnt(8)
	s_waitcnt vmcnt(10)
	s_barrier
	s_waitcnt lgkmcnt(0)
	s_setprio 1
	s_waitcnt lgkmcnt(0)
	v_mfma_f32_16x16x32_bf16 v[124:127], v[128:131], v[144:147], v[124:127]
	v_mfma_f32_16x16x32_bf16 v[120:123], v[136:139], v[144:147], v[120:123]
	v_mfma_f32_16x16x32_bf16 v[108:111], v[128:131], v[152:155], v[108:111]
	v_mfma_f32_16x16x32_bf16 v[104:107], v[136:139], v[152:155], v[104:107]
	v_mfma_f32_16x16x32_bf16 v[92:95], v[128:131], v[160:163], v[92:95]
	v_mfma_f32_16x16x32_bf16 v[88:91], v[136:139], v[160:163], v[88:91]
	v_mfma_f32_16x16x32_bf16 v[76:79], v[128:131], v[168:171], v[76:79]
	v_mfma_f32_16x16x32_bf16 v[72:75], v[136:139], v[168:171], v[72:75]
	v_mfma_f32_16x16x32_bf16 v[124:127], v[132:135], v[148:151], v[124:127]
	v_mfma_f32_16x16x32_bf16 v[120:123], v[140:143], v[148:151], v[120:123]
	v_mfma_f32_16x16x32_bf16 v[108:111], v[132:135], v[156:159], v[108:111]
	v_mfma_f32_16x16x32_bf16 v[104:107], v[140:143], v[156:159], v[104:107]
	v_mfma_f32_16x16x32_bf16 v[92:95], v[132:135], v[164:167], v[92:95]
	v_mfma_f32_16x16x32_bf16 v[88:91], v[140:143], v[164:167], v[88:91]
	v_mfma_f32_16x16x32_bf16 v[76:79], v[132:135], v[172:175], v[76:79]
	s_barrier
	v_mfma_f32_16x16x32_bf16 v[72:75], v[140:143], v[172:175], v[72:75]
	s_setprio 0
	s_add_i32 s26, 0, 0x1c000
	s_add_i32 s27, s47, s29
	v_add_u32_e32 v204, s26, v209
	s_mov_b32 m0, s27
	ds_read_b128 v[192:195], v204
	ds_read_b128 v[196:199], v204 offset:1024
	ds_read_b128 v[200:203], v204 offset:2048
	ds_read_b128 v[204:207], v204 offset:3072
	global_load_lds_dwordx4 v178, s[98:99]
	s_add_i32 m0, s27, 0x2000
	s_nop 0
	global_load_lds_dwordx4 v182, s[98:99]
	s_waitcnt vmcnt(10)
	s_barrier
	s_waitcnt lgkmcnt(0)
	s_setprio 1
	s_waitcnt lgkmcnt(0)
	v_mfma_f32_16x16x32_bf16 v[116:119], v[192:195], v[144:147], v[116:119]
	v_mfma_f32_16x16x32_bf16 v[112:115], v[200:203], v[144:147], v[112:115]
	v_mfma_f32_16x16x32_bf16 v[100:103], v[192:195], v[152:155], v[100:103]
	v_mfma_f32_16x16x32_bf16 v[96:99], v[200:203], v[152:155], v[96:99]
	v_mfma_f32_16x16x32_bf16 v[84:87], v[192:195], v[160:163], v[84:87]
	v_mfma_f32_16x16x32_bf16 v[80:83], v[200:203], v[160:163], v[80:83]
	v_mfma_f32_16x16x32_bf16 v[68:71], v[192:195], v[168:171], v[68:71]
	v_mfma_f32_16x16x32_bf16 v[64:67], v[200:203], v[168:171], v[64:67]
	v_mfma_f32_16x16x32_bf16 v[116:119], v[196:199], v[148:151], v[116:119]
	v_mfma_f32_16x16x32_bf16 v[112:115], v[204:207], v[148:151], v[112:115]
	v_mfma_f32_16x16x32_bf16 v[100:103], v[196:199], v[156:159], v[100:103]
	v_mfma_f32_16x16x32_bf16 v[96:99], v[204:207], v[156:159], v[96:99]
	v_mfma_f32_16x16x32_bf16 v[84:87], v[196:199], v[164:167], v[84:87]
	v_mfma_f32_16x16x32_bf16 v[80:83], v[204:207], v[164:167], v[80:83]
	v_mfma_f32_16x16x32_bf16 v[68:71], v[196:199], v[172:175], v[68:71]
	s_barrier
	v_mfma_f32_16x16x32_bf16 v[64:67], v[204:207], v[172:175], v[64:67]
	s_setprio 0
	s_mov_b32 m0, s35
	ds_read_b128 v[144:147], v212 offset:49152
	ds_read_b128 v[148:151], v212 offset:50176
	ds_read_b128 v[152:155], v212 offset:51200
	ds_read_b128 v[156:159], v212 offset:52224
	ds_read_b128 v[160:163], v212 offset:53248
	ds_read_b128 v[164:167], v212 offset:54272
	ds_read_b128 v[168:171], v212 offset:55296
	ds_read_b128 v[172:175], v212 offset:56320
	global_load_lds_dwordx4 v176, s[100:101]
	s_mov_b32 m0, s36
	s_nop 0
	global_load_lds_dwordx4 v180, s[100:101]
	s_waitcnt vmcnt(10)
	s_barrier
; #define PG8_STAGE(bufoff, gbase, voff) do { _Pragma("unroll") for (int _i = 0; _i < 2; ++_i) \
;         __builtin_amdgcn_global_load_lds((const unsigned*)((const char*)(gbase) + (voff)[_i]), (LAS unsigned*)(lds + (bufoff) + ldsw + _i * 8192), 16, 0, 0); } while (0)
; #define PG8_LDA(dst, b, h) do { _Pragma("unroll") for (int m = 0; m < 4; ++m) _Pragma("unroll") for (int k = 0; k < 2; ++k) dst[m][k] = *(const LAS bf16x8*)(lds + PG8_SA(b, h) + aoff + m * 2048 + k * 1024); } while (0)
; #define PG8_MMA(ai, bj, At, Bt) do { __builtin_amdgcn_s_setprio(1); _Pragma("unroll") for (int m = 0; m < 4; ++m) _Pragma("unroll") for (int n = 0; n < 2; ++n) _Pragma("unroll") for (int k = 0; k < 2; ++k) \
;         acc[ai][bj][m][n] = __builtin_amdgcn_mfma_f32_16x16x32_bf16(Bt[n][k], At[m][k], acc[ai][bj][m][n], 0, 0, 0); __builtin_amdgcn_s_setprio(0); } while (0)
; #define PG8_WAIT_V(n) asm volatile("s_waitcnt vmcnt(" #n ")" ::: "memory")
; #define PG8_WAIT_L(n) asm volatile("s_waitcnt lgkmcnt(" #n ")" ::: "memory")
; #define PG8_BAR __builtin_amdgcn_s_barrier()
; #define PG8_SCHED __builtin_amdgcn_sched_barrier(0)
; template <class Epi>
; __device__ __forceinline__ void gemm_phase(ldsp lds, const Gemm g, const StaticOrder& S, const Epi& E) {
;     ...
;             PG8_WAIT_V(10); PG8_BAR; PG8_WAIT_L(0); PG8_MMA(0, 1, At, B1); PG8_BAR;
;             PG8_LDA(At, 1, 1); PG8_STAGE(PG8_SA(1, 0), a3, voffA);
;             PG8_WAIT_V(10); PG8_BAR; PG8_WAIT_L(0); PG8_MMA(1, 0, At, B0); PG8_BAR; PG8_SCHED;
;             PG8_STAGE(PG8_SB(1, 1), b3 + hstep, voffB);
;             PG8_WAIT_V(10); PG8_BAR; PG8_MMA(1, 1, At, B1); PG8_BAR;
;         }
	s_waitcnt lgkmcnt(0)
	s_setprio 1
	s_waitcnt lgkmcnt(0)
	v_mfma_f32_16x16x32_bf16 v[60:63], v[128:131], v[144:147], v[60:63]
	v_mfma_f32_16x16x32_bf16 v[56:59], v[136:139], v[144:147], v[56:59]
	v_mfma_f32_16x16x32_bf16 v[44:47], v[128:131], v[152:155], v[44:47]
	v_mfma_f32_16x16x32_bf16 v[40:43], v[136:139], v[152:155], v[40:43]
	v_mfma_f32_16x16x32_bf16 v[28:31], v[128:131], v[160:163], v[28:31]
	v_mfma_f32_16x16x32_bf16 v[24:27], v[136:139], v[160:163], v[24:27]
	v_mfma_f32_16x16x32_bf16 v[12:15], v[128:131], v[168:171], v[12:15]
	v_mfma_f32_16x16x32_bf16 v[8:11], v[136:139], v[168:171], v[8:11]
	v_mfma_f32_16x16x32_bf16 v[60:63], v[132:135], v[148:151], v[60:63]
	v_mfma_f32_16x16x32_bf16 v[56:59], v[140:143], v[148:151], v[56:59]
	v_mfma_f32_16x16x32_bf16 v[44:47], v[132:135], v[156:159], v[44:47]
	v_mfma_f32_16x16x32_bf16 v[40:43], v[140:143], v[156:159], v[40:43]
	v_mfma_f32_16x16x32_bf16 v[28:31], v[132:135], v[164:167], v[28:31]
	v_mfma_f32_16x16x32_bf16 v[24:27], v[140:143], v[164:167], v[24:27]
	v_mfma_f32_16x16x32_bf16 v[12:15], v[132:135], v[172:175], v[12:15]
	s_barrier
	v_mfma_f32_16x16x32_bf16 v[8:11], v[140:143], v[172:175], v[8:11]
	s_setprio 0
	s_add_u32 s24, s24, 0x80080
	s_addc_u32 s25, s25, 0
	s_add_i32 s26, s26, s29
	s_mov_b32 m0, s26
	s_nop 0
	global_load_lds_dwordx4 v178, s[24:25]
	s_add_i32 m0, s26, 0x2000
	s_nop 0
	global_load_lds_dwordx4 v182, s[24:25]
	s_waitcnt vmcnt(10)
	s_barrier
	s_setprio 1
	v_mfma_f32_16x16x32_bf16 v[52:55], v[192:195], v[144:147], v[52:55]
	v_mfma_f32_16x16x32_bf16 v[48:51], v[200:203], v[144:147], v[48:51]
	v_mfma_f32_16x16x32_bf16 v[36:39], v[192:195], v[152:155], v[36:39]
	v_mfma_f32_16x16x32_bf16 v[32:35], v[200:203], v[152:155], v[32:35]
	v_mfma_f32_16x16x32_bf16 v[20:23], v[192:195], v[160:163], v[20:23]
	v_mfma_f32_16x16x32_bf16 v[16:19], v[200:203], v[160:163], v[16:19]
	v_mfma_f32_16x16x32_bf16 v[4:7], v[192:195], v[168:171], v[4:7]
	v_mfma_f32_16x16x32_bf16 v[0:3], v[200:203], v[168:171], v[0:3]
	v_mfma_f32_16x16x32_bf16 v[52:55], v[196:199], v[148:151], v[52:55]
	v_mfma_f32_16x16x32_bf16 v[48:51], v[204:207], v[148:151], v[48:51]
	v_mfma_f32_16x16x32_bf16 v[36:39], v[196:199], v[156:159], v[36:39]
	v_mfma_f32_16x16x32_bf16 v[32:35], v[204:207], v[156:159], v[32:35]
	v_mfma_f32_16x16x32_bf16 v[20:23], v[196:199], v[164:167], v[20:23]
	v_mfma_f32_16x16x32_bf16 v[16:19], v[204:207], v[164:167], v[16:19]
	v_mfma_f32_16x16x32_bf16 v[4:7], v[196:199], v[172:175], v[4:7]
	s_barrier
	v_mfma_f32_16x16x32_bf16 v[0:3], v[204:207], v[172:175], v[0:3]
	s_setprio 0
	s_add_i32 s46, s46, 2
	s_add_u32 s22, s22, 0x100
	s_addc_u32 s23, s23, 0
	s_add_u32 s44, s44, 0x100
	s_addc_u32 s45, s45, 0
	s_cmp_gt_u32 s46, 29
	s_cbranch_scc0 .LBB0_733
;     __device__ __forceinline__ void ld(f32x4 (&xv)[2][2][2], int row0, int col0, int ai, int mh) const {
; #pragma unroll
;         for (int mm = 0; mm < 2; ++mm)
; #pragma unroll
;             for (int bj = 0; bj < 2; ++bj) { const size_t off = (size_t)(row0 + ai * 128 + (2 * mh + mm) * 16) * 2048 + col0 + bj * 128;
;                 xv[mm][bj][0] = *(const f32x4*)(base + off); xv[mm][bj][1] = *(const f32x4*)(base + off + 4); }
;     }
;     __device__ __forceinline__ void fin(const f32x4 (&acc)[2][2][4][2], const f32x4 (&xv)[2][2][2], int row0, int col0, int fq, int ai, int mh) const {
; #pragma unroll
;         for (int mm = 0; mm < 2; ++mm) { const int m = 2 * mh + mm; const int row = row0 + ai * 128 + m * 16; float sq = 0.f;
; #pragma unroll
;             for (int bj = 0; bj < 2; ++bj) { const size_t off = (size_t)row * 2048 + col0 + bj * 128;
;                 const f32x4 y0 = xv[mm][bj][0] + acc[ai][bj][m][0], y1 = xv[mm][bj][1] + acc[ai][bj][m][1];
;                 *(f32x4*)(out + off) = y0; *(f32x4*)(out + off + 4) = y1;
;                 if (ob) *(u32x4*)(ob + off) = pack8(y0, y1);
;                 sq += (y0[0] * y0[0] + y0[1] * y0[1]) + (y0[2] * y0[2] + y0[3] * y0[3]) + (y1[0] * y1[0] + y1[1] * y1[1]) + (y1[2] * y1[2] + y1[3] * y1[3]); }
;             sq += __shfl_xor(sq, 16); sq += __shfl_xor(sq, 32);
;             if (fq == 0) atomicAdd(ssq + row, (unsigned long long)(sq * 16777216.0f + 0.5f)); }
;     }
;     __device__ __forceinline__ void operator()(EPI_ARGS) const {
;         const int row0 = u.pm * 256 + wr * 64 + fr, col0 = u.pn * 256 + wc * 32 + 8 * fq;
;         f32x4 xa[2][2][2], xb[2][2][2];
;         ld(xa, row0, col0, 0, 0);
;         ld(xb, row0, col0, 0, 1); fin(acc, xa, row0, col0, fq, 0, 0);
;         ld(xa, row0, col0, 1, 0); fin(acc, xb, row0, col0, fq, 0, 1);
;         ld(xb, row0, col0, 1, 1); fin(acc, xa, row0, col0, fq, 1, 0);
;         fin(acc, xb, row0, col0, fq, 1, 1);
	v_lshl_add_u32 v194, s18, 8, v208
	v_lshl_or_b32 v192, s20, 8, v210
	v_ashrrev_i32_e32 v195, 31, v194
	v_ashrrev_i32_e32 v193, 31, v192
	v_lshlrev_b64 v[128:129], 11, v[194:195]
	v_lshl_add_u64 v[218:219], v[128:129], 0, v[192:193]
	v_lshlrev_b64 v[238:239], 2, v[218:219]
	v_lshl_add_u64 v[128:129], s[64:65], 0, v[238:239]
	global_load_dwordx4 v[222:225], v[128:129], off
	global_load_dwordx4 v[226:229], v[128:129], off offset:16
	global_load_dwordx4 v[230:233], v[128:129], off offset:512
	global_load_dwordx4 v[234:237], v[128:129], off offset:528
	v_or_b32_e32 v204, 16, v194
	v_or_b32_e32 v200, 32, v194
	v_or_b32_e32 v196, 48, v194
	v_ashrrev_i32_e32 v205, 31, v204
	v_ashrrev_i32_e32 v201, 31, v200
	v_ashrrev_i32_e32 v197, 31, v196
	v_lshlrev_b64 v[128:129], 11, v[204:205]
	v_lshlrev_b64 v[130:131], 11, v[200:201]
	v_lshlrev_b64 v[132:133], 11, v[196:197]
	v_lshl_add_u64 v[206:207], v[128:129], 0, v[192:193]
	v_lshl_add_u64 v[202:203], v[130:131], 0, v[192:193]
	v_lshl_add_u64 v[198:199], v[132:133], 0, v[192:193]
	v_lshl_add_u64 v[128:129], v[206:207], 2, s[64:65]
	v_lshl_add_u64 v[130:131], v[202:203], 2, s[64:65]
	v_lshl_add_u64 v[132:133], v[198:199], 2, s[64:65]
	global_load_dwordx4 v[168:171], v[128:129], off offset:16
	global_load_dwordx4 v[172:175], v[128:129], off
	global_load_dwordx4 v[160:163], v[128:129], off offset:528
	global_load_dwordx4 v[164:167], v[128:129], off offset:512
	global_load_dwordx4 v[152:155], v[130:131], off offset:16
	global_load_dwordx4 v[156:159], v[130:131], off
	global_load_dwordx4 v[144:147], v[130:131], off offset:528
	global_load_dwordx4 v[148:151], v[130:131], off offset:512
	global_load_dwordx4 v[136:139], v[132:133], off offset:16
	global_load_dwordx4 v[140:143], v[132:133], off
	s_nop 0
	global_load_dwordx4 v[128:131], v[132:133], off offset:528
	s_nop 0
	global_load_dwordx4 v[132:135], v[132:133], off offset:512
	v_and_b32_e32 v216, 64, v214
	v_xor_b32_e32 v215, 16, v214
	v_add_u32_e32 v216, 64, v216
	v_xor_b32_e32 v217, 32, v214
	v_cmp_lt_i32_e32 vcc, v215, v216
	v_lshl_add_u64 v[238:239], s[70:71], 0, v[238:239]
	v_lshlrev_b64 v[218:219], 1, v[218:219]
	v_cndmask_b32_e32 v215, v214, v215, vcc
	v_cmp_lt_i32_e32 vcc, v217, v216
	v_lshlrev_b32_e32 v216, 2, v215
	v_lshl_add_u64 v[240:241], s[58:59], 0, v[218:219]
	v_cndmask_b32_e32 v217, v214, v217, vcc
	v_lshlrev_b32_e32 v215, 2, v217
	v_or_b32_e32 v218, 0x100, v218
	s_waitcnt vmcnt(0)
	v_pk_add_f32 v[126:127], v[126:127], v[224:225]
	v_pk_add_f32 v[124:125], v[124:125], v[222:223]
	v_pk_add_f32 v[118:119], v[118:119], v[232:233]
	v_pk_add_f32 v[116:117], v[116:117], v[230:231]
	v_pk_add_f32 v[122:123], v[122:123], v[228:229]
	v_pk_add_f32 v[120:121], v[120:121], v[226:227]
	v_pk_add_f32 v[112:113], v[112:113], v[234:235]
	global_store_dwordx4 v[238:239], v[124:127], off
	global_store_dwordx4 v[238:239], v[120:123], off offset:16
	v_cvt_pk_bf16_f32 v222, v124, v125
	v_cvt_pk_bf16_f32 v223, v126, v127
	v_mul_f32_e32 v125, v125, v125
	v_mul_f32_e32 v127, v127, v127
	v_mul_f32_e32 v217, v117, v117
	v_mul_f32_e32 v221, v119, v119
	v_pk_add_f32 v[114:115], v[114:115], v[236:237]
	v_cvt_pk_bf16_f32 v224, v120, v121
	v_cvt_pk_bf16_f32 v225, v122, v123
	v_mul_f32_e32 v121, v121, v121
	v_mul_f32_e32 v123, v123, v123
	v_mul_f32_e32 v226, v113, v113
	v_fmac_f32_e32 v125, v124, v124
	v_fmac_f32_e32 v127, v126, v126
	v_fmac_f32_e32 v217, v116, v116
	v_fmac_f32_e32 v221, v118, v118
	v_mul_f32_e32 v227, v115, v115
	v_fmac_f32_e32 v121, v120, v120
	v_fmac_f32_e32 v123, v122, v122
	v_fmac_f32_e32 v226, v112, v112
	v_add_f32_e32 v120, v125, v127
	v_add_f32_e32 v122, v217, v221
	v_fmac_f32_e32 v227, v114, v114
	v_add_f32_e32 v120, v120, v121
	v_add_f32_e32 v121, v122, v226
	v_add_f32_e32 v120, v123, v120
	v_add_f32_e32 v121, v227, v121
	v_add_f32_e32 v120, v120, v121
	ds_bpermute_b32 v121, v216, v120
	global_store_dwordx4 v[240:241], v[222:225], off
	global_store_dwordx4 v[238:239], v[116:119], off offset:512
	global_store_dwordx4 v[238:239], v[112:115], off offset:528
	s_nop 0
	v_cvt_pk_bf16_f32 v116, v116, v117
	v_cvt_pk_bf16_f32 v117, v118, v119
	v_cvt_pk_bf16_f32 v118, v112, v113
	s_waitcnt lgkmcnt(0)
	v_add_f32_e32 v112, v120, v121
	ds_bpermute_b32 v113, v215, v112
	v_cvt_pk_bf16_f32 v119, v114, v115
	v_lshl_add_u64 v[114:115], s[58:59], 0, v[218:219]
	global_store_dwordx4 v[114:115], v[116:119], off
	s_and_saveexec_b64 s[18:19], s[2:3]
	s_cbranch_execz .LBB0_736
	s_waitcnt lgkmcnt(0)
	v_add_f32_e32 v112, v112, v113
	v_fma_f32 v112, v112, s42, 0.5
	v_trunc_f32_e32 v112, v112
	v_mul_f32_e32 v113, 0x2f800000, v112
	v_floor_f32_e32 v113, v113
	v_fmac_f32_e32 v112, 0xcf800000, v113
	v_cvt_u32_f32_e32 v112, v112
	v_cvt_u32_f32_e32 v113, v113
	v_lshl_add_u64 v[114:115], v[194:195], 3, s[0:1]
	global_atomic_add_x2 v[114:115], v[112:113], off

; #define PG8_STAGE(bufoff, gbase, voff) do { _Pragma("unroll") for (int _i = 0; _i < 2; ++_i) \
;         __builtin_amdgcn_global_load_lds((const unsigned*)((const char*)(gbase) + (voff)[_i]), (LAS unsigned*)(lds + (bufoff) + ldsw + _i * 8192), 16, 0, 0); } while (0)
; #define PG8_LDA(dst, b, h) do { _Pragma("unroll") for (int m = 0; m < 4; ++m) _Pragma("unroll") for (int k = 0; k < 2; ++k) dst[m][k] = *(const LAS bf16x8*)(lds + PG8_SA(b, h) + aoff + m * 2048 + k * 1024); } while (0)
; #define PG8_LDB(dst, b, h) do { _Pragma("unroll") for (int n = 0; n < 2; ++n) _Pragma("unroll") for (int k = 0; k < 2; ++k) dst[n][k] = *(const LAS bf16x8*)(lds + PG8_SB(b, h) + boff + n * 2048 + k * 1024); } while (0)
; #define PG8_MMA(ai, bj, At, Bt) do { __builtin_amdgcn_s_setprio(1); _Pragma("unroll") for (int m = 0; m < 4; ++m) _Pragma("unroll") for (int n = 0; n < 2; ++n) _Pragma("unroll") for (int k = 0; k < 2; ++k) \
;         acc[ai][bj][m][n] = __builtin_amdgcn_mfma_f32_16x16x32_bf16(Bt[n][k], At[m][k], acc[ai][bj][m][n], 0, 0, 0); __builtin_amdgcn_s_setprio(0); } while (0)
; #define PG8_BAR __builtin_amdgcn_s_barrier()
; template <class Epi>
; __device__ __forceinline__ void gemm_phase(ldsp lds, const Gemm g, const StaticOrder& S, const Epi& E) {
;     ...
;         for (int t = 0; t < nt; t += 2) {
;             const bool last = (t == nt - 2);
;             const char* a1 = cA + (size_t)(t + 1) * kstep;
;             const char* a2 = last ? nA : cA + (size_t)(t + 2) * kstep; const char* b2 = last ? nB : cB + (size_t)(t + 2) * kstep;
;             const char* a3 = a2 + kstep; const char* b3 = b2 + kstep;
;             if constexpr (Epi::NPRE > 0) { if (last) E.pre(pre, cur, wr, fr); }
;             if constexpr (Epi::MID_T > 0) { if (t == Epi::MID_T) E.mid(acc, cur, wr, wc, fr, fq); }
;             PG8_LDB(B0, 0, 0); PG8_SCHED; PG8_LDA(At, 0, 0); PG8_STAGE(PG8_SA(1, 1), a1 + hstep, voffA);
;             PG8_WAIT_L(8); PG8_WAIT_V(10); PG8_BAR; PG8_WAIT_L(0); PG8_MMA(0, 0, At, B0); PG8_BAR; PG8_SCHED;
;             PG8_LDB(B1, 0, 1); PG8_STAGE(PG8_SB(0, 0), b2, voffB);
;             PG8_WAIT_V(10); PG8_BAR; PG8_WAIT_L(0); PG8_MMA(0, 1, At, B1); PG8_BAR;
;             PG8_LDA(At, 0, 1); PG8_STAGE(PG8_SA(0, 0), a2, voffA);
;             PG8_WAIT_V(10); PG8_BAR; PG8_WAIT_L(0); PG8_MMA(1, 0, At, B0); PG8_BAR; PG8_SCHED;
;             PG8_STAGE(PG8_SB(0, 1), b2 + hstep, voffB);
.LBB0_816:
	v_add_u32_e32 v161, s39, v175
	ds_read_b128 v[164:167], v161
	ds_read_b128 v[168:171], v161 offset:1024
	ds_read_b128 v[178:181], v161 offset:2048
	ds_read_b128 v[182:185], v161 offset:3072
	s_add_u32 s26, s22, 0xfff80080
	s_addc_u32 s27, s23, -1
	s_and_b64 s[24:25], s[24:25], exec
	s_cselect_b32 s27, s17, s27
	s_cselect_b32 s26, s44, s26
	s_cselect_b32 s25, s15, s47
	s_cselect_b32 s24, s45, s46
	s_add_i32 m0, s29, 0xc000
	ds_read_b128 v[186:189], v177
	ds_read_b128 v[190:193], v177 offset:1024
	ds_read_b128 v[194:197], v177 offset:2048
	ds_read_b128 v[198:201], v177 offset:3072
	ds_read_b128 v[202:205], v177 offset:4096
	ds_read_b128 v[206:209], v177 offset:5120
	ds_read_b128 v[210:213], v177 offset:6144
	ds_read_b128 v[214:217], v177 offset:7168
	global_load_lds_dwordx4 v136, s[22:23]
	s_add_i32 m0, s29, 0xe000
	s_nop 0
	global_load_lds_dwordx4 v138, s[22:23]
	s_waitcnt lgkmcnt(8)
	s_waitcnt vmcnt(10)
	s_barrier
	s_waitcnt lgkmcnt(0)
	s_setprio 1
	s_waitcnt lgkmcnt(0)
	v_mfma_f32_16x16x32_bf16 v[124:127], v[164:167], v[186:189], v[124:127]
	v_mfma_f32_16x16x32_bf16 v[120:123], v[178:181], v[186:189], v[120:123]
	v_mfma_f32_16x16x32_bf16 v[112:115], v[164:167], v[194:197], v[112:115]
	v_mfma_f32_16x16x32_bf16 v[104:107], v[178:181], v[194:197], v[104:107]
	v_mfma_f32_16x16x32_bf16 v[92:95], v[164:167], v[202:205], v[92:95]
	v_mfma_f32_16x16x32_bf16 v[88:91], v[178:181], v[202:205], v[88:91]
	v_mfma_f32_16x16x32_bf16 v[80:83], v[164:167], v[210:213], v[80:83]
	v_mfma_f32_16x16x32_bf16 v[72:75], v[178:181], v[210:213], v[72:75]
	v_mfma_f32_16x16x32_bf16 v[124:127], v[168:171], v[190:193], v[124:127]
	v_mfma_f32_16x16x32_bf16 v[120:123], v[182:185], v[190:193], v[120:123]
	v_mfma_f32_16x16x32_bf16 v[112:115], v[168:171], v[198:201], v[112:115]
	v_mfma_f32_16x16x32_bf16 v[104:107], v[182:185], v[198:201], v[104:107]
	v_mfma_f32_16x16x32_bf16 v[92:95], v[168:171], v[206:209], v[92:95]
	v_mfma_f32_16x16x32_bf16 v[88:91], v[182:185], v[206:209], v[88:91]
	v_mfma_f32_16x16x32_bf16 v[80:83], v[168:171], v[214:217], v[80:83]
	s_barrier
	v_mfma_f32_16x16x32_bf16 v[72:75], v[182:185], v[214:217], v[72:75]
	s_setprio 0
	s_add_i32 s51, s39, s11
	v_add_u32_e32 v161, s40, v175
	s_add_u32 s98, s24, 0x80
	s_addc_u32 s99, s25, 0
	s_mov_b32 m0, s51
	ds_read_b128 v[222:225], v161
	ds_read_b128 v[226:229], v161 offset:1024
	ds_read_b128 v[230:233], v161 offset:2048
	ds_read_b128 v[234:237], v161 offset:3072
	global_load_lds_dwordx4 v132, s[24:25]
	s_add_i32 m0, s51, 0x2000
	s_nop 0
	global_load_lds_dwordx4 v128, s[24:25]
	s_waitcnt vmcnt(10)
	s_barrier
	s_waitcnt lgkmcnt(0)
	s_setprio 1
	s_waitcnt lgkmcnt(0)
	v_mfma_f32_16x16x32_bf16 v[116:119], v[222:225], v[186:189], v[116:119]
	v_mfma_f32_16x16x32_bf16 v[108:111], v[230:233], v[186:189], v[108:111]
	v_mfma_f32_16x16x32_bf16 v[100:103], v[222:225], v[194:197], v[100:103]
	v_mfma_f32_16x16x32_bf16 v[96:99], v[230:233], v[194:197], v[96:99]
	v_mfma_f32_16x16x32_bf16 v[84:87], v[222:225], v[202:205], v[84:87]
	v_mfma_f32_16x16x32_bf16 v[76:79], v[230:233], v[202:205], v[76:79]
	v_mfma_f32_16x16x32_bf16 v[68:71], v[222:225], v[210:213], v[68:71]
	v_mfma_f32_16x16x32_bf16 v[64:67], v[230:233], v[210:213], v[64:67]
	v_mfma_f32_16x16x32_bf16 v[116:119], v[226:229], v[190:193], v[116:119]
	v_mfma_f32_16x16x32_bf16 v[108:111], v[234:237], v[190:193], v[108:111]
	v_mfma_f32_16x16x32_bf16 v[100:103], v[226:229], v[198:201], v[100:103]
	v_mfma_f32_16x16x32_bf16 v[96:99], v[234:237], v[198:201], v[96:99]
	v_mfma_f32_16x16x32_bf16 v[84:87], v[226:229], v[206:209], v[84:87]
	v_mfma_f32_16x16x32_bf16 v[76:79], v[234:237], v[206:209], v[76:79]
	v_mfma_f32_16x16x32_bf16 v[68:71], v[226:229], v[214:217], v[68:71]
	s_barrier
	v_mfma_f32_16x16x32_bf16 v[64:67], v[234:237], v[214:217], v[64:67]
	s_setprio 0
	s_mov_b32 m0, s29
	s_add_u32 s100, s26, 0x80
	s_addc_u32 s101, s27, 0
	ds_read_b128 v[186:189], v177 offset:16384
	ds_read_b128 v[190:193], v177 offset:17408
	ds_read_b128 v[194:197], v177 offset:18432
	ds_read_b128 v[198:201], v177 offset:19456
	ds_read_b128 v[202:205], v177 offset:20480
	ds_read_b128 v[206:209], v177 offset:21504
	ds_read_b128 v[210:213], v177 offset:22528
	ds_read_b128 v[214:217], v177 offset:23552
	global_load_lds_dwordx4 v134, s[26:27]
	s_mov_b32 m0, s30
	s_nop 0
	global_load_lds_dwordx4 v130, s[26:27]
	s_waitcnt vmcnt(10)
	s_barrier
	s_waitcnt lgkmcnt(0)
	s_setprio 1
	s_waitcnt lgkmcnt(0)
	v_mfma_f32_16x16x32_bf16 v[60:63], v[164:167], v[186:189], v[60:63]
	v_mfma_f32_16x16x32_bf16 v[56:59], v[178:181], v[186:189], v[56:59]
	v_mfma_f32_16x16x32_bf16 v[48:51], v[164:167], v[194:197], v[48:51]
	v_mfma_f32_16x16x32_bf16 v[40:43], v[178:181], v[194:197], v[40:43]
	v_mfma_f32_16x16x32_bf16 v[28:31], v[164:167], v[202:205], v[28:31]
	v_mfma_f32_16x16x32_bf16 v[24:27], v[178:181], v[202:205], v[24:27]
	v_mfma_f32_16x16x32_bf16 v[16:19], v[164:167], v[210:213], v[16:19]
	v_mfma_f32_16x16x32_bf16 v[8:11], v[178:181], v[210:213], v[8:11]
	v_mfma_f32_16x16x32_bf16 v[60:63], v[168:171], v[190:193], v[60:63]
	v_mfma_f32_16x16x32_bf16 v[56:59], v[182:185], v[190:193], v[56:59]
	v_mfma_f32_16x16x32_bf16 v[48:51], v[168:171], v[198:201], v[48:51]
	v_mfma_f32_16x16x32_bf16 v[40:43], v[182:185], v[198:201], v[40:43]
	v_mfma_f32_16x16x32_bf16 v[28:31], v[168:171], v[206:209], v[28:31]
	v_mfma_f32_16x16x32_bf16 v[24:27], v[182:185], v[206:209], v[24:27]
	v_mfma_f32_16x16x32_bf16 v[16:19], v[168:171], v[214:217], v[16:19]
	s_barrier
	v_mfma_f32_16x16x32_bf16 v[8:11], v[182:185], v[214:217], v[8:11]
	s_setprio 0
	s_add_u32 s52, s24, 0x80000
	s_addc_u32 s53, s25, 0
	s_add_i32 s51, s40, s11
	s_mov_b32 m0, s51
	s_nop 0
	global_load_lds_dwordx4 v132, s[52:53]
	s_add_i32 m0, s51, 0x2000
	s_nop 0
	global_load_lds_dwordx4 v128, s[52:53]
	s_waitcnt vmcnt(10)
	s_barrier
; #define PG8_STAGE(bufoff, gbase, voff) do { _Pragma("unroll") for (int _i = 0; _i < 2; ++_i) \
;         __builtin_amdgcn_global_load_lds((const unsigned*)((const char*)(gbase) + (voff)[_i]), (LAS unsigned*)(lds + (bufoff) + ldsw + _i * 8192), 16, 0, 0); } while (0)
; #define PG8_LDA(dst, b, h) do { _Pragma("unroll") for (int m = 0; m < 4; ++m) _Pragma("unroll") for (int k = 0; k < 2; ++k) dst[m][k] = *(const LAS bf16x8*)(lds + PG8_SA(b, h) + aoff + m * 2048 + k * 1024); } while (0)
; #define PG8_LDB(dst, b, h) do { _Pragma("unroll") for (int n = 0; n < 2; ++n) _Pragma("unroll") for (int k = 0; k < 2; ++k) dst[n][k] = *(const LAS bf16x8*)(lds + PG8_SB(b, h) + boff + n * 2048 + k * 1024); } while (0)
; #define PG8_MMA(ai, bj, At, Bt) do { __builtin_amdgcn_s_setprio(1); _Pragma("unroll") for (int m = 0; m < 4; ++m) _Pragma("unroll") for (int n = 0; n < 2; ++n) _Pragma("unroll") for (int k = 0; k < 2; ++k) \
;         acc[ai][bj][m][n] = __builtin_amdgcn_mfma_f32_16x16x32_bf16(Bt[n][k], At[m][k], acc[ai][bj][m][n], 0, 0, 0); __builtin_amdgcn_s_setprio(0); } while (0)
; #define PG8_WAIT_V(n) asm volatile("s_waitcnt vmcnt(" #n ")" ::: "memory")
; #define PG8_WAIT_L(n) asm volatile("s_waitcnt lgkmcnt(" #n ")" ::: "memory")
; #define PG8_BAR __builtin_amdgcn_s_barrier()
; #define PG8_SCHED __builtin_amdgcn_sched_barrier(0)
; template <class Epi>
; __device__ __forceinline__ void gemm_phase(ldsp lds, const Gemm g, const StaticOrder& S, const Epi& E) {
;     ...
;             PG8_WAIT_V(10); PG8_BAR; PG8_MMA(1, 1, At, B1); PG8_BAR;
;             PG8_LDB(B0, 1, 0); PG8_SCHED; PG8_LDA(At, 1, 0); PG8_STAGE(PG8_SA(0, 1), a2 + hstep, voffA);
;             PG8_WAIT_L(8); PG8_WAIT_V(10); PG8_BAR; PG8_WAIT_L(0); PG8_MMA(0, 0, At, B0); PG8_BAR; PG8_SCHED;
;             PG8_LDB(B1, 1, 1); PG8_STAGE(PG8_SB(1, 0), b3, voffB);
;             PG8_WAIT_V(10); PG8_BAR; PG8_WAIT_L(0); PG8_MMA(0, 1, At, B1); PG8_BAR;
;             PG8_LDA(At, 1, 1); PG8_STAGE(PG8_SA(1, 0), a3, voffA);
	s_setprio 1
	v_mfma_f32_16x16x32_bf16 v[52:55], v[222:225], v[186:189], v[52:55]
	v_mfma_f32_16x16x32_bf16 v[44:47], v[230:233], v[186:189], v[44:47]
	v_mfma_f32_16x16x32_bf16 v[36:39], v[222:225], v[194:197], v[36:39]
	v_mfma_f32_16x16x32_bf16 v[32:35], v[230:233], v[194:197], v[32:35]
	v_mfma_f32_16x16x32_bf16 v[20:23], v[222:225], v[202:205], v[20:23]
	v_mfma_f32_16x16x32_bf16 v[12:15], v[230:233], v[202:205], v[12:15]
	v_mfma_f32_16x16x32_bf16 v[4:7], v[222:225], v[210:213], v[4:7]
	v_mfma_f32_16x16x32_bf16 v[0:3], v[230:233], v[210:213], v[0:3]
	v_mfma_f32_16x16x32_bf16 v[52:55], v[226:229], v[190:193], v[52:55]
	v_mfma_f32_16x16x32_bf16 v[44:47], v[234:237], v[190:193], v[44:47]
	v_mfma_f32_16x16x32_bf16 v[36:39], v[226:229], v[198:201], v[36:39]
	v_mfma_f32_16x16x32_bf16 v[32:35], v[234:237], v[198:201], v[32:35]
	v_mfma_f32_16x16x32_bf16 v[20:23], v[226:229], v[206:209], v[20:23]
	v_mfma_f32_16x16x32_bf16 v[12:15], v[234:237], v[206:209], v[12:15]
	v_mfma_f32_16x16x32_bf16 v[4:7], v[226:229], v[214:217], v[4:7]
	s_barrier
	v_mfma_f32_16x16x32_bf16 v[0:3], v[234:237], v[214:217], v[0:3]
	s_setprio 0
	s_add_i32 s51, 0, 0x18000
	v_add_u32_e32 v161, s51, v175
	ds_read_b128 v[164:167], v161
	ds_read_b128 v[168:171], v161 offset:1024
	ds_read_b128 v[178:181], v161 offset:2048
	ds_read_b128 v[182:185], v161 offset:3072
	s_add_u32 s26, s26, 0x80000
	s_addc_u32 s27, s27, 0
	s_mov_b32 m0, s31
	ds_read_b128 v[186:189], v177 offset:32768
	ds_read_b128 v[190:193], v177 offset:33792
	ds_read_b128 v[194:197], v177 offset:34816
	ds_read_b128 v[198:201], v177 offset:35840
	ds_read_b128 v[202:205], v177 offset:36864
	ds_read_b128 v[206:209], v177 offset:37888
	ds_read_b128 v[210:213], v177 offset:38912
	ds_read_b128 v[214:217], v177 offset:39936
	global_load_lds_dwordx4 v134, s[26:27]
	s_mov_b32 m0, s33
	s_nop 0
	global_load_lds_dwordx4 v130, s[26:27]
	s_waitcnt lgkmcnt(8)
	s_waitcnt vmcnt(10)
	s_barrier
	s_waitcnt lgkmcnt(0)
	s_setprio 1
	s_waitcnt lgkmcnt(0)
	v_mfma_f32_16x16x32_bf16 v[124:127], v[164:167], v[186:189], v[124:127]
	v_mfma_f32_16x16x32_bf16 v[120:123], v[178:181], v[186:189], v[120:123]
	v_mfma_f32_16x16x32_bf16 v[112:115], v[164:167], v[194:197], v[112:115]
	v_mfma_f32_16x16x32_bf16 v[104:107], v[178:181], v[194:197], v[104:107]
	v_mfma_f32_16x16x32_bf16 v[92:95], v[164:167], v[202:205], v[92:95]
	v_mfma_f32_16x16x32_bf16 v[88:91], v[178:181], v[202:205], v[88:91]
	v_mfma_f32_16x16x32_bf16 v[80:83], v[164:167], v[210:213], v[80:83]
	v_mfma_f32_16x16x32_bf16 v[72:75], v[178:181], v[210:213], v[72:75]
	v_mfma_f32_16x16x32_bf16 v[124:127], v[168:171], v[190:193], v[124:127]
	v_mfma_f32_16x16x32_bf16 v[120:123], v[182:185], v[190:193], v[120:123]
	v_mfma_f32_16x16x32_bf16 v[112:115], v[168:171], v[198:201], v[112:115]
	v_mfma_f32_16x16x32_bf16 v[104:107], v[182:185], v[198:201], v[104:107]
	v_mfma_f32_16x16x32_bf16 v[92:95], v[168:171], v[206:209], v[92:95]
	v_mfma_f32_16x16x32_bf16 v[88:91], v[182:185], v[206:209], v[88:91]
	v_mfma_f32_16x16x32_bf16 v[80:83], v[168:171], v[214:217], v[80:83]
	s_barrier
	v_mfma_f32_16x16x32_bf16 v[72:75], v[182:185], v[214:217], v[72:75]
	s_setprio 0
	s_add_i32 s26, 0, 0x1c000
	s_add_i32 s27, s51, s11
	v_add_u32_e32 v161, s26, v175
	s_mov_b32 m0, s27
	ds_read_b128 v[222:225], v161
	ds_read_b128 v[226:229], v161 offset:1024
	ds_read_b128 v[230:233], v161 offset:2048
	ds_read_b128 v[234:237], v161 offset:3072
	global_load_lds_dwordx4 v132, s[98:99]
	s_add_i32 m0, s27, 0x2000
	s_nop 0
	global_load_lds_dwordx4 v128, s[98:99]
	s_waitcnt vmcnt(10)
	s_barrier
; #define PG8_STAGE(bufoff, gbase, voff) do { _Pragma("unroll") for (int _i = 0; _i < 2; ++_i) \
;         __builtin_amdgcn_global_load_lds((const unsigned*)((const char*)(gbase) + (voff)[_i]), (LAS unsigned*)(lds + (bufoff) + ldsw + _i * 8192), 16, 0, 0); } while (0)
; #define PG8_LDA(dst, b, h) do { _Pragma("unroll") for (int m = 0; m < 4; ++m) _Pragma("unroll") for (int k = 0; k < 2; ++k) dst[m][k] = *(const LAS bf16x8*)(lds + PG8_SA(b, h) + aoff + m * 2048 + k * 1024); } while (0)
; #define PG8_MMA(ai, bj, At, Bt) do { __builtin_amdgcn_s_setprio(1); _Pragma("unroll") for (int m = 0; m < 4; ++m) _Pragma("unroll") for (int n = 0; n < 2; ++n) _Pragma("unroll") for (int k = 0; k < 2; ++k) \
;         acc[ai][bj][m][n] = __builtin_amdgcn_mfma_f32_16x16x32_bf16(Bt[n][k], At[m][k], acc[ai][bj][m][n], 0, 0, 0); __builtin_amdgcn_s_setprio(0); } while (0)
; #define PG8_WAIT_V(n) asm volatile("s_waitcnt vmcnt(" #n ")" ::: "memory")
; #define PG8_WAIT_L(n) asm volatile("s_waitcnt lgkmcnt(" #n ")" ::: "memory")
; #define PG8_BAR __builtin_amdgcn_s_barrier()
; #define PG8_SCHED __builtin_amdgcn_sched_barrier(0)
; template <class Epi>
; __device__ __forceinline__ void gemm_phase(ldsp lds, const Gemm g, const StaticOrder& S, const Epi& E) {
;     ...
;             PG8_WAIT_V(10); PG8_BAR; PG8_WAIT_L(0); PG8_MMA(0, 1, At, B1); PG8_BAR;
;             PG8_LDA(At, 1, 1); PG8_STAGE(PG8_SA(1, 0), a3, voffA);
;             PG8_WAIT_V(10); PG8_BAR; PG8_WAIT_L(0); PG8_MMA(1, 0, At, B0); PG8_BAR; PG8_SCHED;
;             PG8_STAGE(PG8_SB(1, 1), b3 + hstep, voffB);
;             PG8_WAIT_V(10); PG8_BAR; PG8_MMA(1, 1, At, B1); PG8_BAR;
;         }
	s_waitcnt lgkmcnt(0)
	s_setprio 1
	s_waitcnt lgkmcnt(0)
	v_mfma_f32_16x16x32_bf16 v[116:119], v[222:225], v[186:189], v[116:119]
	v_mfma_f32_16x16x32_bf16 v[108:111], v[230:233], v[186:189], v[108:111]
	v_mfma_f32_16x16x32_bf16 v[100:103], v[222:225], v[194:197], v[100:103]
	v_mfma_f32_16x16x32_bf16 v[96:99], v[230:233], v[194:197], v[96:99]
	v_mfma_f32_16x16x32_bf16 v[84:87], v[222:225], v[202:205], v[84:87]
	v_mfma_f32_16x16x32_bf16 v[76:79], v[230:233], v[202:205], v[76:79]
	v_mfma_f32_16x16x32_bf16 v[68:71], v[222:225], v[210:213], v[68:71]
	v_mfma_f32_16x16x32_bf16 v[64:67], v[230:233], v[210:213], v[64:67]
	v_mfma_f32_16x16x32_bf16 v[116:119], v[226:229], v[190:193], v[116:119]
	v_mfma_f32_16x16x32_bf16 v[108:111], v[234:237], v[190:193], v[108:111]
	v_mfma_f32_16x16x32_bf16 v[100:103], v[226:229], v[198:201], v[100:103]
	v_mfma_f32_16x16x32_bf16 v[96:99], v[234:237], v[198:201], v[96:99]
	v_mfma_f32_16x16x32_bf16 v[84:87], v[226:229], v[206:209], v[84:87]
	v_mfma_f32_16x16x32_bf16 v[76:79], v[234:237], v[206:209], v[76:79]
	v_mfma_f32_16x16x32_bf16 v[68:71], v[226:229], v[214:217], v[68:71]
	s_barrier
	v_mfma_f32_16x16x32_bf16 v[64:67], v[234:237], v[214:217], v[64:67]
	s_setprio 0
	s_mov_b32 m0, s35
	ds_read_b128 v[186:189], v177 offset:49152
	ds_read_b128 v[190:193], v177 offset:50176
	ds_read_b128 v[194:197], v177 offset:51200
	ds_read_b128 v[198:201], v177 offset:52224
	ds_read_b128 v[202:205], v177 offset:53248
	ds_read_b128 v[206:209], v177 offset:54272
	ds_read_b128 v[210:213], v177 offset:55296
	ds_read_b128 v[214:217], v177 offset:56320
	global_load_lds_dwordx4 v134, s[100:101]
	s_mov_b32 m0, s36
	s_nop 0
	global_load_lds_dwordx4 v130, s[100:101]
	s_waitcnt vmcnt(10)
	s_barrier
	s_waitcnt lgkmcnt(0)
	s_setprio 1
	s_waitcnt lgkmcnt(0)
	v_mfma_f32_16x16x32_bf16 v[60:63], v[164:167], v[186:189], v[60:63]
	v_mfma_f32_16x16x32_bf16 v[56:59], v[178:181], v[186:189], v[56:59]
	v_mfma_f32_16x16x32_bf16 v[48:51], v[164:167], v[194:197], v[48:51]
	v_mfma_f32_16x16x32_bf16 v[40:43], v[178:181], v[194:197], v[40:43]
	v_mfma_f32_16x16x32_bf16 v[28:31], v[164:167], v[202:205], v[28:31]
	v_mfma_f32_16x16x32_bf16 v[24:27], v[178:181], v[202:205], v[24:27]
	v_mfma_f32_16x16x32_bf16 v[16:19], v[164:167], v[210:213], v[16:19]
	v_mfma_f32_16x16x32_bf16 v[8:11], v[178:181], v[210:213], v[8:11]
	v_mfma_f32_16x16x32_bf16 v[60:63], v[168:171], v[190:193], v[60:63]
	v_mfma_f32_16x16x32_bf16 v[56:59], v[182:185], v[190:193], v[56:59]
	v_mfma_f32_16x16x32_bf16 v[48:51], v[168:171], v[198:201], v[48:51]
	v_mfma_f32_16x16x32_bf16 v[40:43], v[182:185], v[198:201], v[40:43]
	v_mfma_f32_16x16x32_bf16 v[28:31], v[168:171], v[206:209], v[28:31]
	v_mfma_f32_16x16x32_bf16 v[24:27], v[182:185], v[206:209], v[24:27]
	v_mfma_f32_16x16x32_bf16 v[16:19], v[168:171], v[214:217], v[16:19]
	s_barrier
	v_mfma_f32_16x16x32_bf16 v[8:11], v[182:185], v[214:217], v[8:11]
	s_setprio 0
	s_add_u32 s24, s24, 0x80080
	s_addc_u32 s25, s25, 0
	s_add_i32 s26, s26, s11
	s_mov_b32 m0, s26
	s_nop 0
	global_load_lds_dwordx4 v132, s[24:25]
	s_add_i32 m0, s26, 0x2000
	s_nop 0
	global_load_lds_dwordx4 v128, s[24:25]
	s_waitcnt vmcnt(10)
	s_barrier
	s_setprio 1
	v_mfma_f32_16x16x32_bf16 v[52:55], v[222:225], v[186:189], v[52:55]
	v_mfma_f32_16x16x32_bf16 v[44:47], v[230:233], v[186:189], v[44:47]
	v_mfma_f32_16x16x32_bf16 v[36:39], v[222:225], v[194:197], v[36:39]
	v_mfma_f32_16x16x32_bf16 v[32:35], v[230:233], v[194:197], v[32:35]
	v_mfma_f32_16x16x32_bf16 v[20:23], v[222:225], v[202:205], v[20:23]
	v_mfma_f32_16x16x32_bf16 v[12:15], v[230:233], v[202:205], v[12:15]
	v_mfma_f32_16x16x32_bf16 v[4:7], v[222:225], v[210:213], v[4:7]
	v_mfma_f32_16x16x32_bf16 v[0:3], v[230:233], v[210:213], v[0:3]
	v_mfma_f32_16x16x32_bf16 v[52:55], v[226:229], v[190:193], v[52:55]
	v_mfma_f32_16x16x32_bf16 v[44:47], v[234:237], v[190:193], v[44:47]
	v_mfma_f32_16x16x32_bf16 v[36:39], v[226:229], v[198:201], v[36:39]
	v_mfma_f32_16x16x32_bf16 v[32:35], v[234:237], v[198:201], v[32:35]
	v_mfma_f32_16x16x32_bf16 v[20:23], v[226:229], v[206:209], v[20:23]
	v_mfma_f32_16x16x32_bf16 v[12:15], v[234:237], v[206:209], v[12:15]
	v_mfma_f32_16x16x32_bf16 v[4:7], v[226:229], v[214:217], v[4:7]
	s_barrier
	v_mfma_f32_16x16x32_bf16 v[0:3], v[234:237], v[214:217], v[0:3]
	s_setprio 0
	s_add_i32 s50, s50, 2
	s_add_u32 s22, s22, 0x100
	s_addc_u32 s23, s23, 0
	s_add_u32 s46, s46, 0x100
	s_addc_u32 s47, s47, 0
	s_cmp_gt_u32 s50, 29
	s_cbranch_scc1 .LBB0_812

; #define PG8_STAGE(bufoff, gbase, voff) do { _Pragma("unroll") for (int _i = 0; _i < 2; ++_i) \
;         __builtin_amdgcn_global_load_lds((const unsigned*)((const char*)(gbase) + (voff)[_i]), (LAS unsigned*)(lds + (bufoff) + ldsw + _i * 8192), 16, 0, 0); } while (0)
; #define PG8_LDA(dst, b, h) do { _Pragma("unroll") for (int m = 0; m < 4; ++m) _Pragma("unroll") for (int k = 0; k < 2; ++k) dst[m][k] = *(const LAS bf16x8*)(lds + PG8_SA(b, h) + aoff + m * 2048 + k * 1024); } while (0)
; #define PG8_LDB(dst, b, h) do { _Pragma("unroll") for (int n = 0; n < 2; ++n) _Pragma("unroll") for (int k = 0; k < 2; ++k) dst[n][k] = *(const LAS bf16x8*)(lds + PG8_SB(b, h) + boff + n * 2048 + k * 1024); } while (0)
; #define PG8_MMA(ai, bj, At, Bt) do { __builtin_amdgcn_s_setprio(1); _Pragma("unroll") for (int m = 0; m < 4; ++m) _Pragma("unroll") for (int n = 0; n < 2; ++n) _Pragma("unroll") for (int k = 0; k < 2; ++k) \
;         acc[ai][bj][m][n] = __builtin_amdgcn_mfma_f32_16x16x32_bf16(Bt[n][k], At[m][k], acc[ai][bj][m][n], 0, 0, 0); __builtin_amdgcn_s_setprio(0); } while (0)
; #define PG8_BAR __builtin_amdgcn_s_barrier()
; template <class Epi>
; __device__ __forceinline__ void gemm_phase(ldsp lds, const Gemm g, const StaticOrder& S, const Epi& E) {
;     ...
;         for (int t = 0; t < nt; t += 2) {
;             const bool last = (t == nt - 2);
;             const char* a1 = cA + (size_t)(t + 1) * kstep;
;             const char* a2 = last ? nA : cA + (size_t)(t + 2) * kstep; const char* b2 = last ? nB : cB + (size_t)(t + 2) * kstep;
;             const char* a3 = a2 + kstep; const char* b3 = b2 + kstep;
;             if constexpr (Epi::NPRE > 0) { if (last) E.pre(pre, cur, wr, fr); }
;             if constexpr (Epi::MID_T > 0) { if (t == Epi::MID_T) E.mid(acc, cur, wr, wc, fr, fq); }
;             PG8_LDB(B0, 0, 0); PG8_SCHED; PG8_LDA(At, 0, 0); PG8_STAGE(PG8_SA(1, 1), a1 + hstep, voffA);
;             PG8_WAIT_L(8); PG8_WAIT_V(10); PG8_BAR; PG8_WAIT_L(0); PG8_MMA(0, 0, At, B0); PG8_BAR; PG8_SCHED;
;             PG8_LDB(B1, 0, 1); PG8_STAGE(PG8_SB(0, 0), b2, voffB);
;             PG8_WAIT_V(10); PG8_BAR; PG8_WAIT_L(0); PG8_MMA(0, 1, At, B1); PG8_BAR;
;             PG8_LDA(At, 0, 1); PG8_STAGE(PG8_SA(0, 0), a2, voffA);
;             PG8_WAIT_V(10); PG8_BAR; PG8_WAIT_L(0); PG8_MMA(1, 0, At, B0); PG8_BAR; PG8_SCHED;
;             PG8_STAGE(PG8_SB(0, 1), b2 + hstep, voffB);
.LBB0_899:
	ds_read_b128 v[128:131], v211
	ds_read_b128 v[132:135], v211 offset:1024
	ds_read_b128 v[136:139], v211 offset:2048
	ds_read_b128 v[140:143], v211 offset:3072
	s_add_u32 s16, s14, 0xffea0080
	s_addc_u32 s17, s15, -1
	s_cmpk_eq_i32 s42, 0x54
	s_cselect_b32 s19, s1, s17
	s_cselect_b32 s18, s0, s16
	s_cselect_b32 s17, s7, s41
	s_cselect_b32 s16, s6, s40
	s_add_i32 m0, s22, 0xc000
	ds_read_b128 v[144:147], v212
	ds_read_b128 v[148:151], v212 offset:1024
	ds_read_b128 v[152:155], v212 offset:2048
	ds_read_b128 v[156:159], v212 offset:3072
	ds_read_b128 v[160:163], v212 offset:4096
	ds_read_b128 v[164:167], v212 offset:5120
	ds_read_b128 v[168:171], v212 offset:6144
	ds_read_b128 v[172:175], v212 offset:7168
	global_load_lds_dwordx4 v184, s[14:15]
	s_add_i32 m0, s22, 0xe000
	s_nop 0
	global_load_lds_dwordx4 v186, s[14:15]
	s_waitcnt lgkmcnt(8)
	s_waitcnt vmcnt(10)
	s_barrier
	s_waitcnt lgkmcnt(0)
	s_setprio 1
	s_waitcnt lgkmcnt(0)
	v_mfma_f32_16x16x32_bf16 v[124:127], v[128:131], v[144:147], v[124:127]
	v_mfma_f32_16x16x32_bf16 v[120:123], v[136:139], v[144:147], v[120:123]
	v_mfma_f32_16x16x32_bf16 v[108:111], v[128:131], v[152:155], v[108:111]
	v_mfma_f32_16x16x32_bf16 v[104:107], v[136:139], v[152:155], v[104:107]
	v_mfma_f32_16x16x32_bf16 v[92:95], v[128:131], v[160:163], v[92:95]
	v_mfma_f32_16x16x32_bf16 v[88:91], v[136:139], v[160:163], v[88:91]
	v_mfma_f32_16x16x32_bf16 v[76:79], v[128:131], v[168:171], v[76:79]
	v_mfma_f32_16x16x32_bf16 v[72:75], v[136:139], v[168:171], v[72:75]
	v_mfma_f32_16x16x32_bf16 v[124:127], v[132:135], v[148:151], v[124:127]
	v_mfma_f32_16x16x32_bf16 v[120:123], v[140:143], v[148:151], v[120:123]
	v_mfma_f32_16x16x32_bf16 v[108:111], v[132:135], v[156:159], v[108:111]
	v_mfma_f32_16x16x32_bf16 v[104:107], v[140:143], v[156:159], v[104:107]
	v_mfma_f32_16x16x32_bf16 v[92:95], v[132:135], v[164:167], v[92:95]
	v_mfma_f32_16x16x32_bf16 v[88:91], v[140:143], v[164:167], v[88:91]
	v_mfma_f32_16x16x32_bf16 v[76:79], v[132:135], v[172:175], v[76:79]
	s_barrier
	v_mfma_f32_16x16x32_bf16 v[72:75], v[140:143], v[172:175], v[72:75]
	s_setprio 0
	s_add_i32 s43, s33, s21
	s_add_u32 s98, s16, 0x80
	s_addc_u32 s99, s17, 0
	s_mov_b32 m0, s43
	ds_read_b128 v[192:195], v213
	ds_read_b128 v[196:199], v213 offset:1024
	ds_read_b128 v[200:203], v213 offset:2048
	ds_read_b128 v[204:207], v213 offset:3072
	global_load_lds_dwordx4 v178, s[16:17]
	s_add_i32 m0, s43, 0x2000
	s_nop 0
	global_load_lds_dwordx4 v182, s[16:17]
	s_waitcnt vmcnt(10)
	s_barrier
	s_waitcnt lgkmcnt(0)
	s_setprio 1
	s_waitcnt lgkmcnt(0)
	v_mfma_f32_16x16x32_bf16 v[116:119], v[192:195], v[144:147], v[116:119]
	v_mfma_f32_16x16x32_bf16 v[112:115], v[200:203], v[144:147], v[112:115]
	v_mfma_f32_16x16x32_bf16 v[100:103], v[192:195], v[152:155], v[100:103]
	v_mfma_f32_16x16x32_bf16 v[96:99], v[200:203], v[152:155], v[96:99]
	v_mfma_f32_16x16x32_bf16 v[84:87], v[192:195], v[160:163], v[84:87]
	v_mfma_f32_16x16x32_bf16 v[80:83], v[200:203], v[160:163], v[80:83]
	v_mfma_f32_16x16x32_bf16 v[68:71], v[192:195], v[168:171], v[68:71]
	v_mfma_f32_16x16x32_bf16 v[64:67], v[200:203], v[168:171], v[64:67]
	v_mfma_f32_16x16x32_bf16 v[116:119], v[196:199], v[148:151], v[116:119]
	v_mfma_f32_16x16x32_bf16 v[112:115], v[204:207], v[148:151], v[112:115]
	v_mfma_f32_16x16x32_bf16 v[100:103], v[196:199], v[156:159], v[100:103]
	v_mfma_f32_16x16x32_bf16 v[96:99], v[204:207], v[156:159], v[96:99]
	v_mfma_f32_16x16x32_bf16 v[84:87], v[196:199], v[164:167], v[84:87]
	v_mfma_f32_16x16x32_bf16 v[80:83], v[204:207], v[164:167], v[80:83]
	v_mfma_f32_16x16x32_bf16 v[68:71], v[196:199], v[172:175], v[68:71]
	s_barrier
	v_mfma_f32_16x16x32_bf16 v[64:67], v[204:207], v[172:175], v[64:67]
	s_setprio 0
	s_mov_b32 m0, s22
	s_add_u32 s100, s18, 0x80
	s_addc_u32 s101, s19, 0
	ds_read_b128 v[144:147], v212 offset:16384
	ds_read_b128 v[148:151], v212 offset:17408
	ds_read_b128 v[152:155], v212 offset:18432
	ds_read_b128 v[156:159], v212 offset:19456
	ds_read_b128 v[160:163], v212 offset:20480
	ds_read_b128 v[164:167], v212 offset:21504
	ds_read_b128 v[168:171], v212 offset:22528
	ds_read_b128 v[172:175], v212 offset:23552
	global_load_lds_dwordx4 v176, s[18:19]
	s_mov_b32 m0, s23
	s_nop 0
	global_load_lds_dwordx4 v180, s[18:19]
	s_waitcnt vmcnt(10)
	s_barrier
	s_waitcnt lgkmcnt(0)
	s_setprio 1
	s_waitcnt lgkmcnt(0)
	v_mfma_f32_16x16x32_bf16 v[60:63], v[128:131], v[144:147], v[60:63]
	v_mfma_f32_16x16x32_bf16 v[56:59], v[136:139], v[144:147], v[56:59]
	v_mfma_f32_16x16x32_bf16 v[44:47], v[128:131], v[152:155], v[44:47]
	v_mfma_f32_16x16x32_bf16 v[40:43], v[136:139], v[152:155], v[40:43]
	v_mfma_f32_16x16x32_bf16 v[28:31], v[128:131], v[160:163], v[28:31]
	v_mfma_f32_16x16x32_bf16 v[24:27], v[136:139], v[160:163], v[24:27]
	v_mfma_f32_16x16x32_bf16 v[12:15], v[128:131], v[168:171], v[12:15]
	v_mfma_f32_16x16x32_bf16 v[8:11], v[136:139], v[168:171], v[8:11]
	v_mfma_f32_16x16x32_bf16 v[60:63], v[132:135], v[148:151], v[60:63]
	v_mfma_f32_16x16x32_bf16 v[56:59], v[140:143], v[148:151], v[56:59]
	v_mfma_f32_16x16x32_bf16 v[44:47], v[132:135], v[156:159], v[44:47]
	v_mfma_f32_16x16x32_bf16 v[40:43], v[140:143], v[156:159], v[40:43]
	v_mfma_f32_16x16x32_bf16 v[28:31], v[132:135], v[164:167], v[28:31]
	v_mfma_f32_16x16x32_bf16 v[24:27], v[140:143], v[164:167], v[24:27]
	v_mfma_f32_16x16x32_bf16 v[12:15], v[132:135], v[172:175], v[12:15]
	s_barrier
	v_mfma_f32_16x16x32_bf16 v[8:11], v[140:143], v[172:175], v[8:11]
	s_setprio 0
	s_add_u32 s44, s16, 0x160000
	s_addc_u32 s45, s17, 0
	s_add_i32 s43, s34, s21
	s_mov_b32 m0, s43
	s_nop 0
	global_load_lds_dwordx4 v178, s[44:45]
	s_add_i32 m0, s43, 0x2000
	s_nop 0
	global_load_lds_dwordx4 v182, s[44:45]
	s_waitcnt vmcnt(10)
	s_barrier
; #define PG8_STAGE(bufoff, gbase, voff) do { _Pragma("unroll") for (int _i = 0; _i < 2; ++_i) \
;         __builtin_amdgcn_global_load_lds((const unsigned*)((const char*)(gbase) + (voff)[_i]), (LAS unsigned*)(lds + (bufoff) + ldsw + _i * 8192), 16, 0, 0); } while (0)
; #define PG8_LDA(dst, b, h) do { _Pragma("unroll") for (int m = 0; m < 4; ++m) _Pragma("unroll") for (int k = 0; k < 2; ++k) dst[m][k] = *(const LAS bf16x8*)(lds + PG8_SA(b, h) + aoff + m * 2048 + k * 1024); } while (0)
; #define PG8_LDB(dst, b, h) do { _Pragma("unroll") for (int n = 0; n < 2; ++n) _Pragma("unroll") for (int k = 0; k < 2; ++k) dst[n][k] = *(const LAS bf16x8*)(lds + PG8_SB(b, h) + boff + n * 2048 + k * 1024); } while (0)
; #define PG8_MMA(ai, bj, At, Bt) do { __builtin_amdgcn_s_setprio(1); _Pragma("unroll") for (int m = 0; m < 4; ++m) _Pragma("unroll") for (int n = 0; n < 2; ++n) _Pragma("unroll") for (int k = 0; k < 2; ++k) \
;         acc[ai][bj][m][n] = __builtin_amdgcn_mfma_f32_16x16x32_bf16(Bt[n][k], At[m][k], acc[ai][bj][m][n], 0, 0, 0); __builtin_amdgcn_s_setprio(0); } while (0)
; #define PG8_WAIT_V(n) asm volatile("s_waitcnt vmcnt(" #n ")" ::: "memory")
; #define PG8_WAIT_L(n) asm volatile("s_waitcnt lgkmcnt(" #n ")" ::: "memory")
; #define PG8_BAR __builtin_amdgcn_s_barrier()
; #define PG8_SCHED __builtin_amdgcn_sched_barrier(0)
; template <class Epi>
; __device__ __forceinline__ void gemm_phase(ldsp lds, const Gemm g, const StaticOrder& S, const Epi& E) {
;     ...
;             PG8_WAIT_V(10); PG8_BAR; PG8_MMA(1, 1, At, B1); PG8_BAR;
;             PG8_LDB(B0, 1, 0); PG8_SCHED; PG8_LDA(At, 1, 0); PG8_STAGE(PG8_SA(0, 1), a2 + hstep, voffA);
;             PG8_WAIT_L(8); PG8_WAIT_V(10); PG8_BAR; PG8_WAIT_L(0); PG8_MMA(0, 0, At, B0); PG8_BAR; PG8_SCHED;
;             PG8_LDB(B1, 1, 1); PG8_STAGE(PG8_SB(1, 0), b3, voffB);
;             PG8_WAIT_V(10); PG8_BAR; PG8_WAIT_L(0); PG8_MMA(0, 1, At, B1); PG8_BAR;
;             PG8_LDA(At, 1, 1); PG8_STAGE(PG8_SA(1, 0), a3, voffA);
	s_setprio 1
	v_mfma_f32_16x16x32_bf16 v[52:55], v[192:195], v[144:147], v[52:55]
	v_mfma_f32_16x16x32_bf16 v[48:51], v[200:203], v[144:147], v[48:51]
	v_mfma_f32_16x16x32_bf16 v[36:39], v[192:195], v[152:155], v[36:39]
	v_mfma_f32_16x16x32_bf16 v[32:35], v[200:203], v[152:155], v[32:35]
	v_mfma_f32_16x16x32_bf16 v[20:23], v[192:195], v[160:163], v[20:23]
	v_mfma_f32_16x16x32_bf16 v[16:19], v[200:203], v[160:163], v[16:19]
	v_mfma_f32_16x16x32_bf16 v[4:7], v[192:195], v[168:171], v[4:7]
	v_mfma_f32_16x16x32_bf16 v[0:3], v[200:203], v[168:171], v[0:3]
	v_mfma_f32_16x16x32_bf16 v[52:55], v[196:199], v[148:151], v[52:55]
	v_mfma_f32_16x16x32_bf16 v[48:51], v[204:207], v[148:151], v[48:51]
	v_mfma_f32_16x16x32_bf16 v[36:39], v[196:199], v[156:159], v[36:39]
	v_mfma_f32_16x16x32_bf16 v[32:35], v[204:207], v[156:159], v[32:35]
	v_mfma_f32_16x16x32_bf16 v[20:23], v[196:199], v[164:167], v[20:23]
	v_mfma_f32_16x16x32_bf16 v[16:19], v[204:207], v[164:167], v[16:19]
	v_mfma_f32_16x16x32_bf16 v[4:7], v[196:199], v[172:175], v[4:7]
	s_barrier
	v_mfma_f32_16x16x32_bf16 v[0:3], v[204:207], v[172:175], v[0:3]
	s_setprio 0
	s_add_i32 s43, 0, 0x18000
	v_add_u32_e32 v140, s43, v209
	ds_read_b128 v[128:131], v140
	ds_read_b128 v[132:135], v140 offset:1024
	ds_read_b128 v[136:139], v140 offset:2048
	ds_read_b128 v[140:143], v140 offset:3072
	s_add_u32 s18, s18, 0x160000
	s_addc_u32 s19, s19, 0
	s_mov_b32 m0, s24
	ds_read_b128 v[144:147], v212 offset:32768
	ds_read_b128 v[148:151], v212 offset:33792
	ds_read_b128 v[152:155], v212 offset:34816
	ds_read_b128 v[156:159], v212 offset:35840
	ds_read_b128 v[160:163], v212 offset:36864
	ds_read_b128 v[164:167], v212 offset:37888
	ds_read_b128 v[168:171], v212 offset:38912
	ds_read_b128 v[172:175], v212 offset:39936
	global_load_lds_dwordx4 v176, s[18:19]
	s_mov_b32 m0, s25
	s_nop 0
	global_load_lds_dwordx4 v180, s[18:19]
	s_waitcnt lgkmcnt(8)
	s_waitcnt vmcnt(10)
	s_barrier
	s_waitcnt lgkmcnt(0)
	s_setprio 1
	s_waitcnt lgkmcnt(0)
	v_mfma_f32_16x16x32_bf16 v[124:127], v[128:131], v[144:147], v[124:127]
	v_mfma_f32_16x16x32_bf16 v[120:123], v[136:139], v[144:147], v[120:123]
	v_mfma_f32_16x16x32_bf16 v[108:111], v[128:131], v[152:155], v[108:111]
	v_mfma_f32_16x16x32_bf16 v[104:107], v[136:139], v[152:155], v[104:107]
	v_mfma_f32_16x16x32_bf16 v[92:95], v[128:131], v[160:163], v[92:95]
	v_mfma_f32_16x16x32_bf16 v[88:91], v[136:139], v[160:163], v[88:91]
	v_mfma_f32_16x16x32_bf16 v[76:79], v[128:131], v[168:171], v[76:79]
	v_mfma_f32_16x16x32_bf16 v[72:75], v[136:139], v[168:171], v[72:75]
	v_mfma_f32_16x16x32_bf16 v[124:127], v[132:135], v[148:151], v[124:127]
	v_mfma_f32_16x16x32_bf16 v[120:123], v[140:143], v[148:151], v[120:123]
	v_mfma_f32_16x16x32_bf16 v[108:111], v[132:135], v[156:159], v[108:111]
	v_mfma_f32_16x16x32_bf16 v[104:107], v[140:143], v[156:159], v[104:107]
	v_mfma_f32_16x16x32_bf16 v[92:95], v[132:135], v[164:167], v[92:95]
	v_mfma_f32_16x16x32_bf16 v[88:91], v[140:143], v[164:167], v[88:91]
	v_mfma_f32_16x16x32_bf16 v[76:79], v[132:135], v[172:175], v[76:79]
	s_barrier
	v_mfma_f32_16x16x32_bf16 v[72:75], v[140:143], v[172:175], v[72:75]
	s_setprio 0
	s_add_i32 s18, 0, 0x1c000
	s_add_i32 s19, s43, s21
	v_add_u32_e32 v204, s18, v209
	s_mov_b32 m0, s19
	ds_read_b128 v[192:195], v204
	ds_read_b128 v[196:199], v204 offset:1024
	ds_read_b128 v[200:203], v204 offset:2048
	ds_read_b128 v[204:207], v204 offset:3072
	global_load_lds_dwordx4 v178, s[98:99]
	s_add_i32 m0, s19, 0x2000
	s_nop 0
	global_load_lds_dwordx4 v182, s[98:99]
	s_waitcnt vmcnt(10)
	s_barrier
	s_waitcnt lgkmcnt(0)
	s_setprio 1
	s_waitcnt lgkmcnt(0)
	v_mfma_f32_16x16x32_bf16 v[116:119], v[192:195], v[144:147], v[116:119]
	v_mfma_f32_16x16x32_bf16 v[112:115], v[200:203], v[144:147], v[112:115]
	v_mfma_f32_16x16x32_bf16 v[100:103], v[192:195], v[152:155], v[100:103]
	v_mfma_f32_16x16x32_bf16 v[96:99], v[200:203], v[152:155], v[96:99]
	v_mfma_f32_16x16x32_bf16 v[84:87], v[192:195], v[160:163], v[84:87]
	v_mfma_f32_16x16x32_bf16 v[80:83], v[200:203], v[160:163], v[80:83]
	v_mfma_f32_16x16x32_bf16 v[68:71], v[192:195], v[168:171], v[68:71]
	v_mfma_f32_16x16x32_bf16 v[64:67], v[200:203], v[168:171], v[64:67]
	v_mfma_f32_16x16x32_bf16 v[116:119], v[196:199], v[148:151], v[116:119]
	v_mfma_f32_16x16x32_bf16 v[112:115], v[204:207], v[148:151], v[112:115]
	v_mfma_f32_16x16x32_bf16 v[100:103], v[196:199], v[156:159], v[100:103]
	v_mfma_f32_16x16x32_bf16 v[96:99], v[204:207], v[156:159], v[96:99]
	v_mfma_f32_16x16x32_bf16 v[84:87], v[196:199], v[164:167], v[84:87]
	v_mfma_f32_16x16x32_bf16 v[80:83], v[204:207], v[164:167], v[80:83]
	v_mfma_f32_16x16x32_bf16 v[68:71], v[196:199], v[172:175], v[68:71]
	s_barrier
	v_mfma_f32_16x16x32_bf16 v[64:67], v[204:207], v[172:175], v[64:67]
	s_setprio 0
	s_mov_b32 m0, s27
	ds_read_b128 v[144:147], v212 offset:49152
	ds_read_b128 v[148:151], v212 offset:50176
	ds_read_b128 v[152:155], v212 offset:51200
	ds_read_b128 v[156:159], v212 offset:52224
	ds_read_b128 v[160:163], v212 offset:53248
	ds_read_b128 v[164:167], v212 offset:54272
	ds_read_b128 v[168:171], v212 offset:55296
	ds_read_b128 v[172:175], v212 offset:56320
	global_load_lds_dwordx4 v176, s[100:101]
	s_mov_b32 m0, s28
	s_nop 0
	global_load_lds_dwordx4 v180, s[100:101]
	s_waitcnt vmcnt(10)
	s_barrier
; #define PG8_STAGE(bufoff, gbase, voff) do { _Pragma("unroll") for (int _i = 0; _i < 2; ++_i) \
;         __builtin_amdgcn_global_load_lds((const unsigned*)((const char*)(gbase) + (voff)[_i]), (LAS unsigned*)(lds + (bufoff) + ldsw + _i * 8192), 16, 0, 0); } while (0)
; #define PG8_WAIT_V(n) asm volatile("s_waitcnt vmcnt(" #n ")" ::: "memory")
; #define PG8_WAIT_L(n) asm volatile("s_waitcnt lgkmcnt(" #n ")" ::: "memory")
; #define PG8_BAR __builtin_amdgcn_s_barrier()
; #define PG8_SCHED __builtin_amdgcn_sched_barrier(0)
; template <class Epi>
; __device__ __forceinline__ void gemm_phase(ldsp lds, const Gemm g, const StaticOrder& S, const Epi& E) {
;     ...
;             PG8_WAIT_V(10); PG8_BAR; PG8_WAIT_L(0); PG8_MMA(1, 0, At, B0); PG8_BAR; PG8_SCHED;
;             PG8_STAGE(PG8_SB(1, 1), b3 + hstep, voffB);
;             PG8_WAIT_V(10); PG8_BAR; PG8_MMA(1, 1, At, B1); PG8_BAR;
;         }
;     __device__ __forceinline__ void ld(f32x4 (&xv)[2][2][2], int row0, int col0, int ai, int mh) const {
; #pragma unroll
;         for (int mm = 0; mm < 2; ++mm)
; #pragma unroll
;             for (int bj = 0; bj < 2; ++bj) { const size_t off = (size_t)(row0 + ai * 128 + (2 * mh + mm) * 16) * 2048 + col0 + bj * 128;
;                 xv[mm][bj][0] = *(const f32x4*)(base + off); xv[mm][bj][1] = *(const f32x4*)(base + off + 4); }
;     }
;     __device__ __forceinline__ void fin(const f32x4 (&acc)[2][2][4][2], const f32x4 (&xv)[2][2][2], int row0, int col0, int fq, int ai, int mh) const {
; #pragma unroll
;         for (int mm = 0; mm < 2; ++mm) { const int m = 2 * mh + mm; const int row = row0 + ai * 128 + m * 16; float sq = 0.f;
; #pragma unroll
;             for (int bj = 0; bj < 2; ++bj) { const size_t off = (size_t)row * 2048 + col0 + bj * 128;
;                 const f32x4 y0 = xv[mm][bj][0] + acc[ai][bj][m][0], y1 = xv[mm][bj][1] + acc[ai][bj][m][1];
;                 *(f32x4*)(out + off) = y0; *(f32x4*)(out + off + 4) = y1;
;                 if (ob) *(u32x4*)(ob + off) = pack8(y0, y1);
;                 sq += (y0[0] * y0[0] + y0[1] * y0[1]) + (y0[2] * y0[2] + y0[3] * y0[3]) + (y1[0] * y1[0] + y1[1] * y1[1]) + (y1[2] * y1[2] + y1[3] * y1[3]); }
;             sq += __shfl_xor(sq, 16); sq += __shfl_xor(sq, 32);
;             if (fq == 0) atomicAdd(ssq + row, (unsigned long long)(sq * 16777216.0f + 0.5f)); }
	s_waitcnt lgkmcnt(0)
	s_setprio 1
	s_waitcnt lgkmcnt(0)
	v_mfma_f32_16x16x32_bf16 v[60:63], v[128:131], v[144:147], v[60:63]
	v_mfma_f32_16x16x32_bf16 v[56:59], v[136:139], v[144:147], v[56:59]
	v_mfma_f32_16x16x32_bf16 v[44:47], v[128:131], v[152:155], v[44:47]
	v_mfma_f32_16x16x32_bf16 v[40:43], v[136:139], v[152:155], v[40:43]
	v_mfma_f32_16x16x32_bf16 v[28:31], v[128:131], v[160:163], v[28:31]
	v_mfma_f32_16x16x32_bf16 v[24:27], v[136:139], v[160:163], v[24:27]
	v_mfma_f32_16x16x32_bf16 v[12:15], v[128:131], v[168:171], v[12:15]
	v_mfma_f32_16x16x32_bf16 v[8:11], v[136:139], v[168:171], v[8:11]
	v_mfma_f32_16x16x32_bf16 v[60:63], v[132:135], v[148:151], v[60:63]
	v_mfma_f32_16x16x32_bf16 v[56:59], v[140:143], v[148:151], v[56:59]
	v_mfma_f32_16x16x32_bf16 v[44:47], v[132:135], v[156:159], v[44:47]
	v_mfma_f32_16x16x32_bf16 v[40:43], v[140:143], v[156:159], v[40:43]
	v_mfma_f32_16x16x32_bf16 v[28:31], v[132:135], v[164:167], v[28:31]
	v_mfma_f32_16x16x32_bf16 v[24:27], v[140:143], v[164:167], v[24:27]
	v_mfma_f32_16x16x32_bf16 v[12:15], v[132:135], v[172:175], v[12:15]
	s_barrier
	v_mfma_f32_16x16x32_bf16 v[8:11], v[140:143], v[172:175], v[8:11]
	s_setprio 0
	s_add_u32 s16, s16, 0x160080
	s_addc_u32 s17, s17, 0
	s_add_i32 s18, s18, s21
	s_mov_b32 m0, s18
	s_nop 0
	global_load_lds_dwordx4 v178, s[16:17]
	s_add_i32 m0, s18, 0x2000
	s_nop 0
	global_load_lds_dwordx4 v182, s[16:17]
	s_waitcnt vmcnt(10)
	s_barrier
	s_setprio 1
	v_mfma_f32_16x16x32_bf16 v[52:55], v[192:195], v[144:147], v[52:55]
	v_mfma_f32_16x16x32_bf16 v[48:51], v[200:203], v[144:147], v[48:51]
	v_mfma_f32_16x16x32_bf16 v[36:39], v[192:195], v[152:155], v[36:39]
	v_mfma_f32_16x16x32_bf16 v[32:35], v[200:203], v[152:155], v[32:35]
	v_mfma_f32_16x16x32_bf16 v[20:23], v[192:195], v[160:163], v[20:23]
	v_mfma_f32_16x16x32_bf16 v[16:19], v[200:203], v[160:163], v[16:19]
	v_mfma_f32_16x16x32_bf16 v[4:7], v[192:195], v[168:171], v[4:7]
	v_mfma_f32_16x16x32_bf16 v[0:3], v[200:203], v[168:171], v[0:3]
	v_mfma_f32_16x16x32_bf16 v[52:55], v[196:199], v[148:151], v[52:55]
	v_mfma_f32_16x16x32_bf16 v[48:51], v[204:207], v[148:151], v[48:51]
	v_mfma_f32_16x16x32_bf16 v[36:39], v[196:199], v[156:159], v[36:39]
	v_mfma_f32_16x16x32_bf16 v[32:35], v[204:207], v[156:159], v[32:35]
	v_mfma_f32_16x16x32_bf16 v[20:23], v[196:199], v[164:167], v[20:23]
	v_mfma_f32_16x16x32_bf16 v[16:19], v[204:207], v[164:167], v[16:19]
	v_mfma_f32_16x16x32_bf16 v[4:7], v[196:199], v[172:175], v[4:7]
	s_barrier
	v_mfma_f32_16x16x32_bf16 v[0:3], v[204:207], v[172:175], v[0:3]
	s_setprio 0
	s_add_i32 s42, s42, 2
	s_add_u32 s14, s14, 0x100
	s_addc_u32 s15, s15, 0
	s_add_u32 s40, s40, 0x100
	s_addc_u32 s41, s41, 0
	s_cmpk_gt_u32 s42, 0x55
	s_cbranch_scc0 .LBB0_899
	v_lshl_add_u32 v192, s38, 8, v208
	v_lshl_or_b32 v128, s39, 8, v210
	v_ashrrev_i32_e32 v193, 31, v192
	v_ashrrev_i32_e32 v129, 31, v128
	v_lshlrev_b64 v[130:131], 13, v[192:193]
	v_lshl_add_u64 v[130:131], s[70:71], 0, v[130:131]
	v_lshlrev_b64 v[194:195], 2, v[128:129]
	v_lshl_add_u64 v[234:235], v[130:131], 0, v[194:195]
	global_load_dwordx4 v[216:219], v[234:235], off
	global_load_dwordx4 v[222:225], v[234:235], off offset:16
	global_load_dwordx4 v[226:229], v[234:235], off offset:512
	global_load_dwordx4 v[230:233], v[234:235], off offset:528
	v_or_b32_e32 v204, 16, v192
	v_or_b32_e32 v200, 32, v192
	v_or_b32_e32 v196, 48, v192
	v_ashrrev_i32_e32 v205, 31, v204
	v_ashrrev_i32_e32 v201, 31, v200
	v_ashrrev_i32_e32 v197, 31, v196
	v_lshlrev_b64 v[128:129], 13, v[204:205]
	v_lshlrev_b64 v[130:131], 13, v[200:201]
	v_lshlrev_b64 v[132:133], 13, v[196:197]
	v_lshl_add_u64 v[128:129], s[70:71], 0, v[128:129]
	v_lshl_add_u64 v[130:131], s[70:71], 0, v[130:131]
	v_lshl_add_u64 v[132:133], s[70:71], 0, v[132:133]
	v_lshl_add_u64 v[206:207], v[128:129], 0, v[194:195]
	v_lshl_add_u64 v[202:203], v[130:131], 0, v[194:195]
	v_lshl_add_u64 v[198:199], v[132:133], 0, v[194:195]
	global_load_dwordx4 v[168:171], v[206:207], off offset:16
	global_load_dwordx4 v[172:175], v[206:207], off
	global_load_dwordx4 v[160:163], v[206:207], off offset:528
	global_load_dwordx4 v[164:167], v[206:207], off offset:512
	global_load_dwordx4 v[152:155], v[202:203], off offset:16
	global_load_dwordx4 v[156:159], v[202:203], off
	global_load_dwordx4 v[144:147], v[202:203], off offset:528
	global_load_dwordx4 v[148:151], v[202:203], off offset:512
	global_load_dwordx4 v[136:139], v[198:199], off offset:16
	global_load_dwordx4 v[140:143], v[198:199], off
	global_load_dwordx4 v[128:131], v[198:199], off offset:528
	global_load_dwordx4 v[132:135], v[198:199], off offset:512
	v_and_b32_e32 v221, 64, v214
	v_xor_b32_e32 v215, 16, v214
	v_add_u32_e32 v221, 64, v221
	v_cmp_lt_i32_e32 vcc, v215, v221
	s_waitcnt vmcnt(0)
	v_pk_add_f32 v[126:127], v[126:127], v[218:219]
	v_pk_add_f32 v[124:125], v[124:125], v[216:217]
	v_pk_add_f32 v[118:119], v[118:119], v[228:229]
	v_pk_add_f32 v[116:117], v[116:117], v[226:227]
	v_pk_add_f32 v[120:121], v[120:121], v[222:223]
	v_pk_add_f32 v[222:223], v[112:113], v[230:231]
	v_mul_f32_e32 v112, v125, v125
	v_mul_f32_e32 v113, v127, v127
	v_mul_f32_e32 v216, v117, v117
	v_mul_f32_e32 v217, v119, v119
	v_pk_add_f32 v[122:123], v[122:123], v[224:225]
	v_pk_add_f32 v[224:225], v[114:115], v[232:233]
	v_mul_f32_e32 v114, v121, v121
	v_mul_f32_e32 v218, v223, v223
	v_fmac_f32_e32 v112, v124, v124
	v_fmac_f32_e32 v113, v126, v126
	v_fmac_f32_e32 v216, v116, v116
	v_fmac_f32_e32 v217, v118, v118
	v_mul_f32_e32 v115, v123, v123
	v_mul_f32_e32 v219, v225, v225
	v_fmac_f32_e32 v114, v120, v120
	v_fmac_f32_e32 v218, v222, v222
	v_add_f32_e32 v112, v112, v113
	v_add_f32_e32 v113, v216, v217
	v_fmac_f32_e32 v115, v122, v122
	v_fmac_f32_e32 v219, v224, v224
	v_add_f32_e32 v112, v112, v114
	v_add_f32_e32 v113, v113, v218
	v_cndmask_b32_e32 v215, v214, v215, vcc
	v_add_f32_e32 v112, v115, v112
	v_add_f32_e32 v113, v219, v113
	v_lshlrev_b32_e32 v215, 2, v215
	v_add_f32_e32 v112, v112, v113
	ds_bpermute_b32 v113, v215, v112
	v_xor_b32_e32 v114, 32, v214
	v_cmp_lt_i32_e32 vcc, v114, v221
	global_store_dwordx4 v[234:235], v[124:127], off
	global_store_dwordx4 v[234:235], v[120:123], off offset:16
	global_store_dwordx4 v[234:235], v[116:119], off offset:512
	global_store_dwordx4 v[234:235], v[222:225], off offset:528
	v_cndmask_b32_e32 v114, v214, v114, vcc
	v_lshlrev_b32_e32 v216, 2, v114
	s_waitcnt lgkmcnt(0)
	v_add_f32_e32 v112, v112, v113
	ds_bpermute_b32 v113, v216, v112
	s_and_saveexec_b64 s[14:15], s[2:3]
	s_cbranch_execz .LBB0_902
	s_waitcnt lgkmcnt(0)
	v_add_f32_e32 v112, v112, v113
	v_fma_f32 v112, v112, s35, 0.5
	v_trunc_f32_e32 v112, v112
	v_mul_f32_e32 v113, 0x2f800000, v112
	v_floor_f32_e32 v113, v113
	v_fmac_f32_e32 v112, 0xcf800000, v113
	v_cvt_u32_f32_e32 v112, v112
	v_cvt_u32_f32_e32 v113, v113
	v_lshl_add_u64 v[114:115], v[192:193], 3, s[8:9]
	global_atomic_add_x2 v[114:115], v[112:113], off

; __global__ void __launch_bounds__(512, 2) fwd_megakernel(Params p) {
	.amdhsa_kernel _Z14fwd_megakernel6Params
		.amdhsa_group_segment_fixed_size 0
		.amdhsa_private_segment_fixed_size 0
		.amdhsa_kernarg_size 464
		.amdhsa_user_sgpr_count 2
		.amdhsa_user_sgpr_dispatch_ptr 0
		.amdhsa_user_sgpr_queue_ptr 0
		.amdhsa_user_sgpr_kernarg_segment_ptr 1
		.amdhsa_user_sgpr_dispatch_id 0
		.amdhsa_user_sgpr_kernarg_preload_length 0
		.amdhsa_user_sgpr_kernarg_preload_offset 0
		.amdhsa_user_sgpr_private_segment_size 0
		.amdhsa_uses_dynamic_stack 0
		.amdhsa_enable_private_segment 0
		.amdhsa_system_sgpr_workgroup_id_x 1
		.amdhsa_system_sgpr_workgroup_id_y 0
		.amdhsa_system_sgpr_workgroup_id_z 0
		.amdhsa_system_sgpr_workgroup_info 0
		.amdhsa_system_vgpr_workitem_id 2
		.amdhsa_next_free_vgpr 248
		.amdhsa_next_free_sgpr 102
		.amdhsa_accum_offset 248
		.amdhsa_reserve_vcc 1
		.amdhsa_float_round_mode_32 0
		.amdhsa_float_round_mode_16_64 0
		.amdhsa_float_denorm_mode_32 3
		.amdhsa_float_denorm_mode_16_64 3
		.amdhsa_dx10_clamp 1
		.amdhsa_ieee_mode 1
		.amdhsa_fp16_overflow 0
		.amdhsa_tg_split 0
		.amdhsa_exception_fp_ieee_invalid_op 0
		.amdhsa_exception_fp_denorm_src 0
		.amdhsa_exception_fp_ieee_div_zero 0
		.amdhsa_exception_fp_ieee_overflow 0
		.amdhsa_exception_fp_ieee_underflow 0
		.amdhsa_exception_fp_ieee_inexact 0
		.amdhsa_exception_int_div_zero 0
	.end_amdhsa_kernel

; __global__ void __launch_bounds__(512, 2) fwd_megakernel(Params p) {
amdhsa.kernels:
  - .agpr_count:     0
    .args:
      - .offset:         0
        .size:           208
        .value_kind:     by_value
      - .offset:         208
        .size:           4
        .value_kind:     hidden_block_count_x
      - .offset:         212
        .size:           4
        .value_kind:     hidden_block_count_y
      - .offset:         216
        .size:           4
        .value_kind:     hidden_block_count_z
      - .offset:         220
        .size:           2
        .value_kind:     hidden_group_size_x
      - .offset:         222
        .size:           2
        .value_kind:     hidden_group_size_y
      - .offset:         224
        .size:           2
        .value_kind:     hidden_group_size_z
      - .offset:         226
        .size:           2
        .value_kind:     hidden_remainder_x
      - .offset:         228
        .size:           2
        .value_kind:     hidden_remainder_y
      - .offset:         230
        .size:           2
        .value_kind:     hidden_remainder_z
      - .offset:         248
        .size:           8
        .value_kind:     hidden_global_offset_x
      - .offset:         256
        .size:           8
        .value_kind:     hidden_global_offset_y
      - .offset:         264
        .size:           8
        .value_kind:     hidden_global_offset_z
      - .offset:         272
        .size:           2
        .value_kind:     hidden_grid_dims
      - .offset:         296
        .size:           8
        .value_kind:     hidden_multigrid_sync_arg
      - .offset:         328
        .size:           4
        .value_kind:     hidden_dynamic_lds_size
    .group_segment_fixed_size: 0
    .kernarg_segment_align: 8
    .kernarg_segment_size: 464
    .language:       OpenCL C
    .language_version:
      - 2
      - 0
    .max_flat_workgroup_size: 512
    .name:           _Z14fwd_megakernel6Params
    .private_segment_fixed_size: 0
    .sgpr_count:     108
    .sgpr_spill_count: 63
    .symbol:         _Z14fwd_megakernel6Params.kd
    .uniform_work_group_size: 1
    .uses_dynamic_stack: false
    .vgpr_count:     248
    .vgpr_spill_count: 0
    .wavefront_size: 64
